# GEMM K loops: per-phase s_setprio flips and duplicate consecutive lgkmcnt(0) waits removed
# speedup vs baseline: 1.0027x; 1.0027x over previous
.LBB0_195:
	v_mov_b32_e32 v127, 0
	s_andn2_b64 vcc, exec, s[80:81]
	v_mov_b32_e32 v126, v127
	v_mov_b32_e32 v125, v127
	v_mov_b32_e32 v124, v127
	v_mov_b32_e32 v123, v127
	v_mov_b32_e32 v122, v127
	v_mov_b32_e32 v121, v127
	v_mov_b32_e32 v120, v127
	v_mov_b32_e32 v111, v127
	v_mov_b32_e32 v110, v127
	v_mov_b32_e32 v109, v127
	v_mov_b32_e32 v108, v127
	v_mov_b32_e32 v107, v127
	v_mov_b32_e32 v106, v127
	v_mov_b32_e32 v105, v127
	v_mov_b32_e32 v104, v127
	v_mov_b32_e32 v95, v127
	v_mov_b32_e32 v94, v127
	v_mov_b32_e32 v93, v127
	v_mov_b32_e32 v92, v127
	v_mov_b32_e32 v91, v127
	v_mov_b32_e32 v90, v127
	v_mov_b32_e32 v89, v127
	v_mov_b32_e32 v88, v127
	v_mov_b32_e32 v79, v127
	v_mov_b32_e32 v78, v127
	v_mov_b32_e32 v77, v127
	v_mov_b32_e32 v76, v127
	v_mov_b32_e32 v75, v127
	v_mov_b32_e32 v74, v127
	v_mov_b32_e32 v73, v127
	v_mov_b32_e32 v72, v127
	v_mov_b32_e32 v119, v127
	v_mov_b32_e32 v118, v127
	v_mov_b32_e32 v117, v127
	v_mov_b32_e32 v116, v127
	v_mov_b32_e32 v115, v127
	v_mov_b32_e32 v114, v127
	v_mov_b32_e32 v113, v127
	v_mov_b32_e32 v112, v127
	v_mov_b32_e32 v103, v127
	v_mov_b32_e32 v102, v127
	v_mov_b32_e32 v101, v127
	v_mov_b32_e32 v100, v127
	v_mov_b32_e32 v99, v127
	v_mov_b32_e32 v98, v127
	v_mov_b32_e32 v97, v127
	v_mov_b32_e32 v96, v127
	v_mov_b32_e32 v87, v127
	v_mov_b32_e32 v86, v127
	v_mov_b32_e32 v85, v127
	v_mov_b32_e32 v84, v127
	v_mov_b32_e32 v83, v127
	v_mov_b32_e32 v82, v127
	v_mov_b32_e32 v81, v127
	v_mov_b32_e32 v80, v127
	v_mov_b32_e32 v71, v127
	v_mov_b32_e32 v70, v127
	v_mov_b32_e32 v69, v127
	v_mov_b32_e32 v68, v127
	v_mov_b32_e32 v67, v127
	v_mov_b32_e32 v66, v127
	v_mov_b32_e32 v65, v127
	v_mov_b32_e32 v64, v127
	v_mov_b32_e32 v63, v127
	v_mov_b32_e32 v62, v127
	v_mov_b32_e32 v61, v127
	v_mov_b32_e32 v60, v127
	v_mov_b32_e32 v59, v127
	v_mov_b32_e32 v58, v127
	v_mov_b32_e32 v57, v127
	v_mov_b32_e32 v56, v127
	v_mov_b32_e32 v47, v127
	v_mov_b32_e32 v46, v127
	v_mov_b32_e32 v45, v127
	v_mov_b32_e32 v44, v127
	v_mov_b32_e32 v43, v127
	v_mov_b32_e32 v42, v127
	v_mov_b32_e32 v41, v127
	v_mov_b32_e32 v40, v127
	v_mov_b32_e32 v31, v127
	v_mov_b32_e32 v30, v127
	v_mov_b32_e32 v29, v127
	v_mov_b32_e32 v28, v127
	v_mov_b32_e32 v27, v127
	v_mov_b32_e32 v26, v127
	v_mov_b32_e32 v25, v127
	v_mov_b32_e32 v24, v127
	v_mov_b32_e32 v15, v127
	v_mov_b32_e32 v14, v127
	v_mov_b32_e32 v13, v127
	v_mov_b32_e32 v12, v127
	v_mov_b32_e32 v11, v127
	v_mov_b32_e32 v10, v127
	v_mov_b32_e32 v9, v127
	v_mov_b32_e32 v8, v127
	v_mov_b32_e32 v55, v127
	v_mov_b32_e32 v54, v127
	v_mov_b32_e32 v53, v127
	v_mov_b32_e32 v52, v127
	v_mov_b32_e32 v51, v127
	v_mov_b32_e32 v50, v127
	v_mov_b32_e32 v49, v127
	v_mov_b32_e32 v48, v127
	v_mov_b32_e32 v39, v127
	v_mov_b32_e32 v38, v127
	v_mov_b32_e32 v37, v127
	v_mov_b32_e32 v36, v127
	v_mov_b32_e32 v35, v127
	v_mov_b32_e32 v34, v127
	v_mov_b32_e32 v33, v127
	v_mov_b32_e32 v32, v127
	v_mov_b32_e32 v23, v127
	v_mov_b32_e32 v22, v127
	v_mov_b32_e32 v21, v127
	v_mov_b32_e32 v20, v127
	v_mov_b32_e32 v19, v127
	v_mov_b32_e32 v18, v127
	v_mov_b32_e32 v17, v127
	v_mov_b32_e32 v16, v127
	v_mov_b32_e32 v7, v127
	v_mov_b32_e32 v6, v127
	v_mov_b32_e32 v5, v127
	v_mov_b32_e32 v4, v127
	v_mov_b32_e32 v3, v127
	v_mov_b32_e32 v2, v127
	v_mov_b32_e32 v1, v127
	v_mov_b32_e32 v0, v127
	s_cbranch_vccnz .LBB0_198
	s_add_u32 s10, s6, 0x100
	s_addc_u32 s40, s7, 0
	s_add_u32 s6, s38, 0x80
	s_addc_u32 s7, s39, 0
	s_mov_b32 s2, 0
	s_add_i32 s41, s2, 2
	s_add_u32 s21, s6, 0x80
	s_addc_u32 s3, s7, 0
	s_add_i32 s42, 0, 0x10000
	v_add_u32_e32 v140, s42, v154
	ds_read_b128 v[142:145], v140
	ds_read_b128 v[162:165], v140 offset:1024
	ds_read_b128 v[166:169], v140 offset:2048
	ds_read_b128 v[170:173], v140 offset:3072
	s_cmp_eq_u32 s9, s2
	s_cselect_b32 s2, s68, s21
	s_cselect_b32 s3, s69, s3
	s_cselect_b32 s39, s95, s40
	s_cselect_b32 s38, s94, s10
	v_lshl_add_u64 v[226:227], s[6:7], 0, v[138:139]
	s_add_i32 m0, s79, 0xc000
	ds_read_b128 v[174:177], v155
	ds_read_b128 v[178:181], v155 offset:1024
	ds_read_b128 v[182:185], v155 offset:2048
	ds_read_b128 v[186:189], v155 offset:3072
	ds_read_b128 v[206:209], v155 offset:4096
	ds_read_b128 v[214:217], v155 offset:5120
	ds_read_b128 v[218:221], v155 offset:6144
	ds_read_b128 v[222:225], v155 offset:7168
	global_load_lds_dwordx4 v[226:227], off
	v_lshl_add_u64 v[226:227], s[6:7], 0, v[136:137]
	s_add_i32 m0, s79, 0xe000
	s_nop 0
	global_load_lds_dwordx4 v[226:227], off
	s_waitcnt lgkmcnt(8)
	s_barrier
	s_waitcnt lgkmcnt(0)
	v_mfma_f32_16x16x32_bf16 v[124:127], v[142:145], v[174:177], 0
	v_mfma_f32_16x16x32_bf16 v[120:123], v[166:169], v[174:177], 0
	v_mfma_f32_16x16x32_bf16 v[108:111], v[142:145], v[182:185], 0
	v_mfma_f32_16x16x32_bf16 v[104:107], v[166:169], v[182:185], 0
	v_mfma_f32_16x16x32_bf16 v[92:95], v[142:145], v[206:209], 0
	v_mfma_f32_16x16x32_bf16 v[88:91], v[166:169], v[206:209], 0
	v_mfma_f32_16x16x32_bf16 v[76:79], v[142:145], v[218:221], 0
	v_mfma_f32_16x16x32_bf16 v[72:75], v[166:169], v[218:221], 0
	v_mfma_f32_16x16x32_bf16 v[124:127], v[162:165], v[178:181], v[124:127]
	v_mfma_f32_16x16x32_bf16 v[120:123], v[170:173], v[178:181], v[120:123]
	v_mfma_f32_16x16x32_bf16 v[108:111], v[162:165], v[186:189], v[108:111]
	v_mfma_f32_16x16x32_bf16 v[104:107], v[170:173], v[186:189], v[104:107]
	v_mfma_f32_16x16x32_bf16 v[92:95], v[162:165], v[214:217], v[92:95]
	v_mfma_f32_16x16x32_bf16 v[88:91], v[170:173], v[214:217], v[88:91]
	v_mfma_f32_16x16x32_bf16 v[76:79], v[162:165], v[222:225], v[76:79]
	v_mfma_f32_16x16x32_bf16 v[72:75], v[170:173], v[222:225], v[72:75]
	s_barrier
	s_add_i32 s21, 0, 0x14000
	s_add_i32 s42, s42, s54
	v_add_u32_e32 v140, s21, v154
	v_lshl_add_u64 v[242:243], s[38:39], 0, v[130:131]
	s_mov_b32 m0, s42
	ds_read_b128 v[226:229], v140
	ds_read_b128 v[230:233], v140 offset:1024
	ds_read_b128 v[234:237], v140 offset:2048
	ds_read_b128 v[238:241], v140 offset:3072
	global_load_lds_dwordx4 v[242:243], off
	v_lshl_add_u64 v[244:245], s[38:39], 0, v[128:129]
	s_add_i32 m0, s42, 0x2000
	s_nop 0
	global_load_lds_dwordx4 v[244:245], off
	s_barrier
	s_waitcnt lgkmcnt(0)
	v_mfma_f32_16x16x32_bf16 v[116:119], v[226:229], v[174:177], 0
	v_mfma_f32_16x16x32_bf16 v[112:115], v[234:237], v[174:177], 0
	v_mfma_f32_16x16x32_bf16 v[100:103], v[226:229], v[182:185], 0
	v_mfma_f32_16x16x32_bf16 v[96:99], v[234:237], v[182:185], 0
	v_mfma_f32_16x16x32_bf16 v[84:87], v[226:229], v[206:209], 0
	v_mfma_f32_16x16x32_bf16 v[80:83], v[234:237], v[206:209], 0
	v_mfma_f32_16x16x32_bf16 v[68:71], v[226:229], v[218:221], 0
	v_mfma_f32_16x16x32_bf16 v[64:67], v[234:237], v[218:221], 0
	v_mfma_f32_16x16x32_bf16 v[116:119], v[230:233], v[178:181], v[116:119]
	v_mfma_f32_16x16x32_bf16 v[112:115], v[238:241], v[178:181], v[112:115]
	v_mfma_f32_16x16x32_bf16 v[100:103], v[230:233], v[186:189], v[100:103]
	v_mfma_f32_16x16x32_bf16 v[96:99], v[238:241], v[186:189], v[96:99]
	v_mfma_f32_16x16x32_bf16 v[84:87], v[230:233], v[214:217], v[84:87]
	v_mfma_f32_16x16x32_bf16 v[80:83], v[238:241], v[214:217], v[80:83]
	v_mfma_f32_16x16x32_bf16 v[68:71], v[230:233], v[222:225], v[68:71]
	v_mfma_f32_16x16x32_bf16 v[64:67], v[238:241], v[222:225], v[64:67]
	s_mov_b32 m0, s79
	v_lshl_add_u64 v[246:247], s[2:3], 0, v[130:131]
	s_barrier
	ds_read_b128 v[174:177], v155 offset:16384
	ds_read_b128 v[178:181], v155 offset:17408
	ds_read_b128 v[182:185], v155 offset:18432
	ds_read_b128 v[186:189], v155 offset:19456
	ds_read_b128 v[206:209], v155 offset:20480
	ds_read_b128 v[214:217], v155 offset:21504
	ds_read_b128 v[218:221], v155 offset:22528
	ds_read_b128 v[222:225], v155 offset:23552
	global_load_lds_dwordx4 v[246:247], off
	v_lshl_add_u64 v[248:249], s[2:3], 0, v[128:129]
	s_mov_b32 m0, s34
	s_nop 0
	global_load_lds_dwordx4 v[248:249], off
	s_barrier
	s_waitcnt lgkmcnt(0)
	v_mfma_f32_16x16x32_bf16 v[60:63], v[142:145], v[174:177], 0
	v_mfma_f32_16x16x32_bf16 v[56:59], v[166:169], v[174:177], 0
	v_mfma_f32_16x16x32_bf16 v[44:47], v[142:145], v[182:185], 0
	v_mfma_f32_16x16x32_bf16 v[40:43], v[166:169], v[182:185], 0
	v_mfma_f32_16x16x32_bf16 v[28:31], v[142:145], v[206:209], 0
	v_mfma_f32_16x16x32_bf16 v[24:27], v[166:169], v[206:209], 0
	v_mfma_f32_16x16x32_bf16 v[12:15], v[142:145], v[218:221], 0
	v_mfma_f32_16x16x32_bf16 v[8:11], v[166:169], v[218:221], 0
	v_mfma_f32_16x16x32_bf16 v[60:63], v[162:165], v[178:181], v[60:63]
	v_mfma_f32_16x16x32_bf16 v[56:59], v[170:173], v[178:181], v[56:59]
	v_mfma_f32_16x16x32_bf16 v[44:47], v[162:165], v[186:189], v[44:47]
	v_mfma_f32_16x16x32_bf16 v[40:43], v[170:173], v[186:189], v[40:43]
	v_mfma_f32_16x16x32_bf16 v[28:31], v[162:165], v[214:217], v[28:31]
	v_mfma_f32_16x16x32_bf16 v[24:27], v[170:173], v[214:217], v[24:27]
	v_mfma_f32_16x16x32_bf16 v[12:15], v[162:165], v[222:225], v[12:15]
	v_mfma_f32_16x16x32_bf16 v[8:11], v[170:173], v[222:225], v[8:11]
	s_barrier
	s_add_u32 s38, s38, s88
	s_addc_u32 s39, s39, s89
	s_add_i32 s21, s21, s54
	v_lshl_add_u64 v[250:251], s[38:39], 0, v[130:131]
	s_mov_b32 m0, s21
	v_lshl_add_u64 v[252:253], s[38:39], 0, v[128:129]
	global_load_lds_dwordx4 v[250:251], off
	s_add_i32 m0, s21, 0x2000
	s_nop 0
	global_load_lds_dwordx4 v[252:253], off
	s_waitcnt vmcnt(6)
	s_barrier
	v_mfma_f32_16x16x32_bf16 v[52:55], v[226:229], v[174:177], 0
	v_mfma_f32_16x16x32_bf16 v[48:51], v[234:237], v[174:177], 0
	v_mfma_f32_16x16x32_bf16 v[36:39], v[226:229], v[182:185], 0
	v_mfma_f32_16x16x32_bf16 v[32:35], v[234:237], v[182:185], 0
	v_mfma_f32_16x16x32_bf16 v[20:23], v[226:229], v[206:209], 0
	v_mfma_f32_16x16x32_bf16 v[16:19], v[234:237], v[206:209], 0
	v_mfma_f32_16x16x32_bf16 v[4:7], v[226:229], v[218:221], 0
	v_mfma_f32_16x16x32_bf16 v[0:3], v[234:237], v[218:221], 0
	v_mfma_f32_16x16x32_bf16 v[52:55], v[230:233], v[178:181], v[52:55]
	v_mfma_f32_16x16x32_bf16 v[48:51], v[238:241], v[178:181], v[48:51]
	v_mfma_f32_16x16x32_bf16 v[36:39], v[230:233], v[186:189], v[36:39]
	v_mfma_f32_16x16x32_bf16 v[32:35], v[238:241], v[186:189], v[32:35]
	v_mfma_f32_16x16x32_bf16 v[20:23], v[230:233], v[214:217], v[20:23]
	v_mfma_f32_16x16x32_bf16 v[16:19], v[238:241], v[214:217], v[16:19]
	v_mfma_f32_16x16x32_bf16 v[4:7], v[230:233], v[222:225], v[4:7]
	v_mfma_f32_16x16x32_bf16 v[0:3], v[238:241], v[222:225], v[0:3]
	s_add_i32 s21, 0, 0x18000
	v_add_u32_e32 v140, s21, v154
	s_barrier
	ds_read_b128 v[142:145], v140
	ds_read_b128 v[162:165], v140 offset:1024
	ds_read_b128 v[166:169], v140 offset:2048
	ds_read_b128 v[170:173], v140 offset:3072
	s_add_u32 s2, s2, s88
	s_addc_u32 s3, s3, s89
	s_mov_b32 m0, s35
	v_lshl_add_u64 v[226:227], s[2:3], 0, v[130:131]
	ds_read_b128 v[174:177], v155 offset:32768
	ds_read_b128 v[178:181], v155 offset:33792
	ds_read_b128 v[182:185], v155 offset:34816
	ds_read_b128 v[186:189], v155 offset:35840
	ds_read_b128 v[206:209], v155 offset:36864
	ds_read_b128 v[214:217], v155 offset:37888
	ds_read_b128 v[218:221], v155 offset:38912
	ds_read_b128 v[222:225], v155 offset:39936
	global_load_lds_dwordx4 v[226:227], off
	v_lshl_add_u64 v[226:227], s[2:3], 0, v[128:129]
	s_mov_b32 m0, s44
	s_nop 0
	global_load_lds_dwordx4 v[226:227], off
	s_waitcnt lgkmcnt(8)
	s_barrier
	s_waitcnt lgkmcnt(0)
	v_mfma_f32_16x16x32_bf16 v[124:127], v[142:145], v[174:177], v[124:127]
	v_mfma_f32_16x16x32_bf16 v[120:123], v[166:169], v[174:177], v[120:123]
	v_mfma_f32_16x16x32_bf16 v[108:111], v[142:145], v[182:185], v[108:111]
	v_mfma_f32_16x16x32_bf16 v[104:107], v[166:169], v[182:185], v[104:107]
	v_mfma_f32_16x16x32_bf16 v[92:95], v[142:145], v[206:209], v[92:95]
	v_mfma_f32_16x16x32_bf16 v[88:91], v[166:169], v[206:209], v[88:91]
	v_mfma_f32_16x16x32_bf16 v[76:79], v[142:145], v[218:221], v[76:79]
	v_mfma_f32_16x16x32_bf16 v[72:75], v[166:169], v[218:221], v[72:75]
	v_mfma_f32_16x16x32_bf16 v[124:127], v[162:165], v[178:181], v[124:127]
	v_mfma_f32_16x16x32_bf16 v[120:123], v[170:173], v[178:181], v[120:123]
	v_mfma_f32_16x16x32_bf16 v[108:111], v[162:165], v[186:189], v[108:111]
	v_mfma_f32_16x16x32_bf16 v[104:107], v[170:173], v[186:189], v[104:107]
	v_mfma_f32_16x16x32_bf16 v[92:95], v[162:165], v[214:217], v[92:95]
	v_mfma_f32_16x16x32_bf16 v[88:91], v[170:173], v[214:217], v[88:91]
	v_mfma_f32_16x16x32_bf16 v[76:79], v[162:165], v[222:225], v[76:79]
	v_mfma_f32_16x16x32_bf16 v[72:75], v[170:173], v[222:225], v[72:75]
	s_barrier
	s_add_i32 s2, 0, 0x1c000
	s_add_i32 s3, s21, s54
	v_add_u32_e32 v140, s2, v154
	v_lshl_add_u64 v[242:243], v[242:243], 0, s[50:51]
	s_mov_b32 m0, s3
	ds_read_b128 v[226:229], v140
	ds_read_b128 v[230:233], v140 offset:1024
	ds_read_b128 v[234:237], v140 offset:2048
	ds_read_b128 v[238:241], v140 offset:3072
	global_load_lds_dwordx4 v[242:243], off
	v_lshl_add_u64 v[242:243], v[244:245], 0, s[50:51]
	s_add_i32 m0, s3, 0x2000
	s_nop 0
	global_load_lds_dwordx4 v[242:243], off
	s_barrier
	s_waitcnt lgkmcnt(0)
	v_mfma_f32_16x16x32_bf16 v[116:119], v[226:229], v[174:177], v[116:119]
	v_mfma_f32_16x16x32_bf16 v[112:115], v[234:237], v[174:177], v[112:115]
	v_mfma_f32_16x16x32_bf16 v[100:103], v[226:229], v[182:185], v[100:103]
	v_mfma_f32_16x16x32_bf16 v[96:99], v[234:237], v[182:185], v[96:99]
	v_mfma_f32_16x16x32_bf16 v[84:87], v[226:229], v[206:209], v[84:87]
	v_mfma_f32_16x16x32_bf16 v[80:83], v[234:237], v[206:209], v[80:83]
	v_mfma_f32_16x16x32_bf16 v[68:71], v[226:229], v[218:221], v[68:71]
	v_mfma_f32_16x16x32_bf16 v[64:67], v[234:237], v[218:221], v[64:67]
	v_mfma_f32_16x16x32_bf16 v[116:119], v[230:233], v[178:181], v[116:119]
	v_mfma_f32_16x16x32_bf16 v[112:115], v[238:241], v[178:181], v[112:115]
	v_mfma_f32_16x16x32_bf16 v[100:103], v[230:233], v[186:189], v[100:103]
	v_mfma_f32_16x16x32_bf16 v[96:99], v[238:241], v[186:189], v[96:99]
	v_mfma_f32_16x16x32_bf16 v[84:87], v[230:233], v[214:217], v[84:87]
	v_mfma_f32_16x16x32_bf16 v[80:83], v[238:241], v[214:217], v[80:83]
	v_mfma_f32_16x16x32_bf16 v[68:71], v[230:233], v[222:225], v[68:71]
	v_mfma_f32_16x16x32_bf16 v[64:67], v[238:241], v[222:225], v[64:67]
	s_mov_b32 m0, s82
	v_lshl_add_u64 v[242:243], v[246:247], 0, s[50:51]
	s_barrier
	ds_read_b128 v[174:177], v155 offset:49152
	ds_read_b128 v[178:181], v155 offset:50176
	ds_read_b128 v[182:185], v155 offset:51200
	ds_read_b128 v[186:189], v155 offset:52224
	ds_read_b128 v[206:209], v155 offset:53248
	ds_read_b128 v[214:217], v155 offset:54272
	ds_read_b128 v[218:221], v155 offset:55296
	ds_read_b128 v[222:225], v155 offset:56320
	global_load_lds_dwordx4 v[242:243], off
	v_lshl_add_u64 v[242:243], v[248:249], 0, s[50:51]
	s_mov_b32 m0, s83
	s_nop 0
	global_load_lds_dwordx4 v[242:243], off
	s_barrier
	s_waitcnt lgkmcnt(0)
	v_mfma_f32_16x16x32_bf16 v[60:63], v[142:145], v[174:177], v[60:63]
	v_mfma_f32_16x16x32_bf16 v[56:59], v[166:169], v[174:177], v[56:59]
	v_mfma_f32_16x16x32_bf16 v[44:47], v[142:145], v[182:185], v[44:47]
	v_mfma_f32_16x16x32_bf16 v[40:43], v[166:169], v[182:185], v[40:43]
	v_mfma_f32_16x16x32_bf16 v[28:31], v[142:145], v[206:209], v[28:31]
	v_mfma_f32_16x16x32_bf16 v[24:27], v[166:169], v[206:209], v[24:27]
	v_mfma_f32_16x16x32_bf16 v[12:15], v[142:145], v[218:221], v[12:15]
	v_mfma_f32_16x16x32_bf16 v[8:11], v[166:169], v[218:221], v[8:11]
	v_mfma_f32_16x16x32_bf16 v[60:63], v[162:165], v[178:181], v[60:63]
	v_mfma_f32_16x16x32_bf16 v[56:59], v[170:173], v[178:181], v[56:59]
	v_mfma_f32_16x16x32_bf16 v[44:47], v[162:165], v[186:189], v[44:47]
	v_mfma_f32_16x16x32_bf16 v[40:43], v[170:173], v[186:189], v[40:43]
	v_mfma_f32_16x16x32_bf16 v[28:31], v[162:165], v[214:217], v[28:31]
	v_mfma_f32_16x16x32_bf16 v[24:27], v[170:173], v[214:217], v[24:27]
	v_mfma_f32_16x16x32_bf16 v[12:15], v[162:165], v[222:225], v[12:15]
	v_mfma_f32_16x16x32_bf16 v[8:11], v[170:173], v[222:225], v[8:11]
	s_barrier
	s_add_i32 s2, s2, s54
	v_lshl_add_u64 v[142:143], v[250:251], 0, s[50:51]
	s_mov_b32 m0, s2
	s_nop 0
	global_load_lds_dwordx4 v[142:143], off
	v_lshl_add_u64 v[142:143], v[252:253], 0, s[50:51]
	s_add_i32 m0, s2, 0x2000
	s_nop 0
	global_load_lds_dwordx4 v[142:143], off
	s_waitcnt vmcnt(6)
	s_barrier
	v_mfma_f32_16x16x32_bf16 v[52:55], v[226:229], v[174:177], v[52:55]
	v_mfma_f32_16x16x32_bf16 v[48:51], v[234:237], v[174:177], v[48:51]
	v_mfma_f32_16x16x32_bf16 v[36:39], v[226:229], v[182:185], v[36:39]
	v_mfma_f32_16x16x32_bf16 v[32:35], v[234:237], v[182:185], v[32:35]
	v_mfma_f32_16x16x32_bf16 v[20:23], v[226:229], v[206:209], v[20:23]
	v_mfma_f32_16x16x32_bf16 v[16:19], v[234:237], v[206:209], v[16:19]
	v_mfma_f32_16x16x32_bf16 v[4:7], v[226:229], v[218:221], v[4:7]
	v_mfma_f32_16x16x32_bf16 v[0:3], v[234:237], v[218:221], v[0:3]
	v_mfma_f32_16x16x32_bf16 v[52:55], v[230:233], v[178:181], v[52:55]
	v_mfma_f32_16x16x32_bf16 v[48:51], v[238:241], v[178:181], v[48:51]
	v_mfma_f32_16x16x32_bf16 v[36:39], v[230:233], v[186:189], v[36:39]
	v_mfma_f32_16x16x32_bf16 v[32:35], v[238:241], v[186:189], v[32:35]
	v_mfma_f32_16x16x32_bf16 v[20:23], v[230:233], v[214:217], v[20:23]
	v_mfma_f32_16x16x32_bf16 v[16:19], v[238:241], v[214:217], v[16:19]
	v_mfma_f32_16x16x32_bf16 v[4:7], v[230:233], v[222:225], v[4:7]
	v_mfma_f32_16x16x32_bf16 v[0:3], v[238:241], v[222:225], v[0:3]
	s_add_u32 s10, s10, 0x100
	s_addc_u32 s40, s40, 0
	s_add_u32 s6, s6, 0x100
	s_addc_u32 s7, s7, 0
	s_cmp_ge_i32 s41, s66
	s_mov_b32 s2, s41
	s_barrier
	s_cbranch_scc1 .Lpost_197
.LBB0_197:
	s_add_i32 s41, s2, 2
	s_add_u32 s21, s6, 0x80
	s_addc_u32 s3, s7, 0
	s_add_i32 s42, 0, 0x10000
	v_add_u32_e32 v140, s42, v154
	ds_read_b128 v[142:145], v140
	ds_read_b128 v[162:165], v140 offset:1024
	ds_read_b128 v[166:169], v140 offset:2048
	ds_read_b128 v[170:173], v140 offset:3072
	s_cmp_eq_u32 s9, s2
	s_cselect_b32 s2, s68, s21
	s_cselect_b32 s3, s69, s3
	s_cselect_b32 s39, s95, s40
	s_cselect_b32 s38, s94, s10
	v_lshl_add_u64 v[226:227], s[6:7], 0, v[138:139]
	s_add_i32 m0, s79, 0xc000
	ds_read_b128 v[174:177], v155
	ds_read_b128 v[178:181], v155 offset:1024
	ds_read_b128 v[182:185], v155 offset:2048
	ds_read_b128 v[186:189], v155 offset:3072
	ds_read_b128 v[206:209], v155 offset:4096
	ds_read_b128 v[214:217], v155 offset:5120
	ds_read_b128 v[218:221], v155 offset:6144
	ds_read_b128 v[222:225], v155 offset:7168
	global_load_lds_dwordx4 v[226:227], off
	v_lshl_add_u64 v[226:227], s[6:7], 0, v[136:137]
	s_add_i32 m0, s79, 0xe000
	s_nop 0
	global_load_lds_dwordx4 v[226:227], off
	s_waitcnt lgkmcnt(8)
	s_barrier
	s_waitcnt lgkmcnt(0)
	v_mfma_f32_16x16x32_bf16 v[124:127], v[142:145], v[174:177], v[124:127]
	v_mfma_f32_16x16x32_bf16 v[120:123], v[166:169], v[174:177], v[120:123]
	v_mfma_f32_16x16x32_bf16 v[108:111], v[142:145], v[182:185], v[108:111]
	v_mfma_f32_16x16x32_bf16 v[104:107], v[166:169], v[182:185], v[104:107]
	v_mfma_f32_16x16x32_bf16 v[92:95], v[142:145], v[206:209], v[92:95]
	v_mfma_f32_16x16x32_bf16 v[88:91], v[166:169], v[206:209], v[88:91]
	v_mfma_f32_16x16x32_bf16 v[76:79], v[142:145], v[218:221], v[76:79]
	v_mfma_f32_16x16x32_bf16 v[72:75], v[166:169], v[218:221], v[72:75]
	v_mfma_f32_16x16x32_bf16 v[124:127], v[162:165], v[178:181], v[124:127]
	v_mfma_f32_16x16x32_bf16 v[120:123], v[170:173], v[178:181], v[120:123]
	v_mfma_f32_16x16x32_bf16 v[108:111], v[162:165], v[186:189], v[108:111]
	v_mfma_f32_16x16x32_bf16 v[104:107], v[170:173], v[186:189], v[104:107]
	v_mfma_f32_16x16x32_bf16 v[92:95], v[162:165], v[214:217], v[92:95]
	v_mfma_f32_16x16x32_bf16 v[88:91], v[170:173], v[214:217], v[88:91]
	v_mfma_f32_16x16x32_bf16 v[76:79], v[162:165], v[222:225], v[76:79]
	v_mfma_f32_16x16x32_bf16 v[72:75], v[170:173], v[222:225], v[72:75]
	s_barrier
	s_add_i32 s21, 0, 0x14000
	s_add_i32 s42, s42, s54
	v_add_u32_e32 v140, s21, v154
	v_lshl_add_u64 v[242:243], s[38:39], 0, v[130:131]
	s_mov_b32 m0, s42
	ds_read_b128 v[226:229], v140
	ds_read_b128 v[230:233], v140 offset:1024
	ds_read_b128 v[234:237], v140 offset:2048
	ds_read_b128 v[238:241], v140 offset:3072
	global_load_lds_dwordx4 v[242:243], off
	v_lshl_add_u64 v[244:245], s[38:39], 0, v[128:129]
	s_add_i32 m0, s42, 0x2000
	s_nop 0
	global_load_lds_dwordx4 v[244:245], off
	s_barrier
	s_waitcnt lgkmcnt(0)
	v_mfma_f32_16x16x32_bf16 v[116:119], v[226:229], v[174:177], v[116:119]
	v_mfma_f32_16x16x32_bf16 v[112:115], v[234:237], v[174:177], v[112:115]
	v_mfma_f32_16x16x32_bf16 v[100:103], v[226:229], v[182:185], v[100:103]
	v_mfma_f32_16x16x32_bf16 v[96:99], v[234:237], v[182:185], v[96:99]
	v_mfma_f32_16x16x32_bf16 v[84:87], v[226:229], v[206:209], v[84:87]
	v_mfma_f32_16x16x32_bf16 v[80:83], v[234:237], v[206:209], v[80:83]
	v_mfma_f32_16x16x32_bf16 v[68:71], v[226:229], v[218:221], v[68:71]
	v_mfma_f32_16x16x32_bf16 v[64:67], v[234:237], v[218:221], v[64:67]
	v_mfma_f32_16x16x32_bf16 v[116:119], v[230:233], v[178:181], v[116:119]
	v_mfma_f32_16x16x32_bf16 v[112:115], v[238:241], v[178:181], v[112:115]
	v_mfma_f32_16x16x32_bf16 v[100:103], v[230:233], v[186:189], v[100:103]
	v_mfma_f32_16x16x32_bf16 v[96:99], v[238:241], v[186:189], v[96:99]
	v_mfma_f32_16x16x32_bf16 v[84:87], v[230:233], v[214:217], v[84:87]
	v_mfma_f32_16x16x32_bf16 v[80:83], v[238:241], v[214:217], v[80:83]
	v_mfma_f32_16x16x32_bf16 v[68:71], v[230:233], v[222:225], v[68:71]
	v_mfma_f32_16x16x32_bf16 v[64:67], v[238:241], v[222:225], v[64:67]
	s_mov_b32 m0, s79
	v_lshl_add_u64 v[246:247], s[2:3], 0, v[130:131]
	s_barrier
	ds_read_b128 v[174:177], v155 offset:16384
	ds_read_b128 v[178:181], v155 offset:17408
	ds_read_b128 v[182:185], v155 offset:18432
	ds_read_b128 v[186:189], v155 offset:19456
	ds_read_b128 v[206:209], v155 offset:20480
	ds_read_b128 v[214:217], v155 offset:21504
	ds_read_b128 v[218:221], v155 offset:22528
	ds_read_b128 v[222:225], v155 offset:23552
	global_load_lds_dwordx4 v[246:247], off
	v_lshl_add_u64 v[248:249], s[2:3], 0, v[128:129]
	s_mov_b32 m0, s34
	s_nop 0
	global_load_lds_dwordx4 v[248:249], off
	s_barrier
	s_waitcnt lgkmcnt(0)
	v_mfma_f32_16x16x32_bf16 v[60:63], v[142:145], v[174:177], v[60:63]
	v_mfma_f32_16x16x32_bf16 v[56:59], v[166:169], v[174:177], v[56:59]
	v_mfma_f32_16x16x32_bf16 v[44:47], v[142:145], v[182:185], v[44:47]
	v_mfma_f32_16x16x32_bf16 v[40:43], v[166:169], v[182:185], v[40:43]
	v_mfma_f32_16x16x32_bf16 v[28:31], v[142:145], v[206:209], v[28:31]
	v_mfma_f32_16x16x32_bf16 v[24:27], v[166:169], v[206:209], v[24:27]
	v_mfma_f32_16x16x32_bf16 v[12:15], v[142:145], v[218:221], v[12:15]
	v_mfma_f32_16x16x32_bf16 v[8:11], v[166:169], v[218:221], v[8:11]
	v_mfma_f32_16x16x32_bf16 v[60:63], v[162:165], v[178:181], v[60:63]
	v_mfma_f32_16x16x32_bf16 v[56:59], v[170:173], v[178:181], v[56:59]
	v_mfma_f32_16x16x32_bf16 v[44:47], v[162:165], v[186:189], v[44:47]
	v_mfma_f32_16x16x32_bf16 v[40:43], v[170:173], v[186:189], v[40:43]
	v_mfma_f32_16x16x32_bf16 v[28:31], v[162:165], v[214:217], v[28:31]
	v_mfma_f32_16x16x32_bf16 v[24:27], v[170:173], v[214:217], v[24:27]
	v_mfma_f32_16x16x32_bf16 v[12:15], v[162:165], v[222:225], v[12:15]
	v_mfma_f32_16x16x32_bf16 v[8:11], v[170:173], v[222:225], v[8:11]
	s_barrier
	s_add_u32 s38, s38, s88
	s_addc_u32 s39, s39, s89
	s_add_i32 s21, s21, s54
	v_lshl_add_u64 v[250:251], s[38:39], 0, v[130:131]
	s_mov_b32 m0, s21
	v_lshl_add_u64 v[252:253], s[38:39], 0, v[128:129]
	global_load_lds_dwordx4 v[250:251], off
	s_add_i32 m0, s21, 0x2000
	s_nop 0
	global_load_lds_dwordx4 v[252:253], off
	s_waitcnt vmcnt(6)
	s_barrier
	v_mfma_f32_16x16x32_bf16 v[52:55], v[226:229], v[174:177], v[52:55]
	v_mfma_f32_16x16x32_bf16 v[48:51], v[234:237], v[174:177], v[48:51]
	v_mfma_f32_16x16x32_bf16 v[36:39], v[226:229], v[182:185], v[36:39]
	v_mfma_f32_16x16x32_bf16 v[32:35], v[234:237], v[182:185], v[32:35]
	v_mfma_f32_16x16x32_bf16 v[20:23], v[226:229], v[206:209], v[20:23]
	v_mfma_f32_16x16x32_bf16 v[16:19], v[234:237], v[206:209], v[16:19]
	v_mfma_f32_16x16x32_bf16 v[4:7], v[226:229], v[218:221], v[4:7]
	v_mfma_f32_16x16x32_bf16 v[0:3], v[234:237], v[218:221], v[0:3]
	v_mfma_f32_16x16x32_bf16 v[52:55], v[230:233], v[178:181], v[52:55]
	v_mfma_f32_16x16x32_bf16 v[48:51], v[238:241], v[178:181], v[48:51]
	v_mfma_f32_16x16x32_bf16 v[36:39], v[230:233], v[186:189], v[36:39]
	v_mfma_f32_16x16x32_bf16 v[32:35], v[238:241], v[186:189], v[32:35]
	v_mfma_f32_16x16x32_bf16 v[20:23], v[230:233], v[214:217], v[20:23]
	v_mfma_f32_16x16x32_bf16 v[16:19], v[238:241], v[214:217], v[16:19]
	v_mfma_f32_16x16x32_bf16 v[4:7], v[230:233], v[222:225], v[4:7]
	v_mfma_f32_16x16x32_bf16 v[0:3], v[238:241], v[222:225], v[0:3]
	s_add_i32 s21, 0, 0x18000
	v_add_u32_e32 v140, s21, v154
	s_barrier
	ds_read_b128 v[142:145], v140
	ds_read_b128 v[162:165], v140 offset:1024
	ds_read_b128 v[166:169], v140 offset:2048
	ds_read_b128 v[170:173], v140 offset:3072
	s_add_u32 s2, s2, s88
	s_addc_u32 s3, s3, s89
	s_mov_b32 m0, s35
	v_lshl_add_u64 v[226:227], s[2:3], 0, v[130:131]
	ds_read_b128 v[174:177], v155 offset:32768
	ds_read_b128 v[178:181], v155 offset:33792
	ds_read_b128 v[182:185], v155 offset:34816
	ds_read_b128 v[186:189], v155 offset:35840
	ds_read_b128 v[206:209], v155 offset:36864
	ds_read_b128 v[214:217], v155 offset:37888
	ds_read_b128 v[218:221], v155 offset:38912
	ds_read_b128 v[222:225], v155 offset:39936
	global_load_lds_dwordx4 v[226:227], off
	v_lshl_add_u64 v[226:227], s[2:3], 0, v[128:129]
	s_mov_b32 m0, s44
	s_nop 0
	global_load_lds_dwordx4 v[226:227], off
	s_waitcnt lgkmcnt(8)
	s_barrier
	s_waitcnt lgkmcnt(0)
	v_mfma_f32_16x16x32_bf16 v[124:127], v[142:145], v[174:177], v[124:127]
	v_mfma_f32_16x16x32_bf16 v[120:123], v[166:169], v[174:177], v[120:123]
	v_mfma_f32_16x16x32_bf16 v[108:111], v[142:145], v[182:185], v[108:111]
	v_mfma_f32_16x16x32_bf16 v[104:107], v[166:169], v[182:185], v[104:107]
	v_mfma_f32_16x16x32_bf16 v[92:95], v[142:145], v[206:209], v[92:95]
	v_mfma_f32_16x16x32_bf16 v[88:91], v[166:169], v[206:209], v[88:91]
	v_mfma_f32_16x16x32_bf16 v[76:79], v[142:145], v[218:221], v[76:79]
	v_mfma_f32_16x16x32_bf16 v[72:75], v[166:169], v[218:221], v[72:75]
	v_mfma_f32_16x16x32_bf16 v[124:127], v[162:165], v[178:181], v[124:127]
	v_mfma_f32_16x16x32_bf16 v[120:123], v[170:173], v[178:181], v[120:123]
	v_mfma_f32_16x16x32_bf16 v[108:111], v[162:165], v[186:189], v[108:111]
	v_mfma_f32_16x16x32_bf16 v[104:107], v[170:173], v[186:189], v[104:107]
	v_mfma_f32_16x16x32_bf16 v[92:95], v[162:165], v[214:217], v[92:95]
	v_mfma_f32_16x16x32_bf16 v[88:91], v[170:173], v[214:217], v[88:91]
	v_mfma_f32_16x16x32_bf16 v[76:79], v[162:165], v[222:225], v[76:79]
	v_mfma_f32_16x16x32_bf16 v[72:75], v[170:173], v[222:225], v[72:75]
	s_barrier
	s_add_i32 s2, 0, 0x1c000
	s_add_i32 s3, s21, s54
	v_add_u32_e32 v140, s2, v154
	v_lshl_add_u64 v[242:243], v[242:243], 0, s[50:51]
	s_mov_b32 m0, s3
	ds_read_b128 v[226:229], v140
	ds_read_b128 v[230:233], v140 offset:1024
	ds_read_b128 v[234:237], v140 offset:2048
	ds_read_b128 v[238:241], v140 offset:3072
	global_load_lds_dwordx4 v[242:243], off
	v_lshl_add_u64 v[242:243], v[244:245], 0, s[50:51]
	s_add_i32 m0, s3, 0x2000
	s_nop 0
	global_load_lds_dwordx4 v[242:243], off
	s_barrier
	s_waitcnt lgkmcnt(0)
	v_mfma_f32_16x16x32_bf16 v[116:119], v[226:229], v[174:177], v[116:119]
	v_mfma_f32_16x16x32_bf16 v[112:115], v[234:237], v[174:177], v[112:115]
	v_mfma_f32_16x16x32_bf16 v[100:103], v[226:229], v[182:185], v[100:103]
	v_mfma_f32_16x16x32_bf16 v[96:99], v[234:237], v[182:185], v[96:99]
	v_mfma_f32_16x16x32_bf16 v[84:87], v[226:229], v[206:209], v[84:87]
	v_mfma_f32_16x16x32_bf16 v[80:83], v[234:237], v[206:209], v[80:83]
	v_mfma_f32_16x16x32_bf16 v[68:71], v[226:229], v[218:221], v[68:71]
	v_mfma_f32_16x16x32_bf16 v[64:67], v[234:237], v[218:221], v[64:67]
	v_mfma_f32_16x16x32_bf16 v[116:119], v[230:233], v[178:181], v[116:119]
	v_mfma_f32_16x16x32_bf16 v[112:115], v[238:241], v[178:181], v[112:115]
	v_mfma_f32_16x16x32_bf16 v[100:103], v[230:233], v[186:189], v[100:103]
	v_mfma_f32_16x16x32_bf16 v[96:99], v[238:241], v[186:189], v[96:99]
	v_mfma_f32_16x16x32_bf16 v[84:87], v[230:233], v[214:217], v[84:87]
	v_mfma_f32_16x16x32_bf16 v[80:83], v[238:241], v[214:217], v[80:83]
	v_mfma_f32_16x16x32_bf16 v[68:71], v[230:233], v[222:225], v[68:71]
	v_mfma_f32_16x16x32_bf16 v[64:67], v[238:241], v[222:225], v[64:67]
	s_mov_b32 m0, s82
	v_lshl_add_u64 v[242:243], v[246:247], 0, s[50:51]
	s_barrier
	ds_read_b128 v[174:177], v155 offset:49152
	ds_read_b128 v[178:181], v155 offset:50176
	ds_read_b128 v[182:185], v155 offset:51200
	ds_read_b128 v[186:189], v155 offset:52224
	ds_read_b128 v[206:209], v155 offset:53248
	ds_read_b128 v[214:217], v155 offset:54272
	ds_read_b128 v[218:221], v155 offset:55296
	ds_read_b128 v[222:225], v155 offset:56320
	global_load_lds_dwordx4 v[242:243], off
	v_lshl_add_u64 v[242:243], v[248:249], 0, s[50:51]
	s_mov_b32 m0, s83
	s_nop 0
	global_load_lds_dwordx4 v[242:243], off
	s_barrier
	s_waitcnt lgkmcnt(0)
	v_mfma_f32_16x16x32_bf16 v[60:63], v[142:145], v[174:177], v[60:63]
	v_mfma_f32_16x16x32_bf16 v[56:59], v[166:169], v[174:177], v[56:59]
	v_mfma_f32_16x16x32_bf16 v[44:47], v[142:145], v[182:185], v[44:47]
	v_mfma_f32_16x16x32_bf16 v[40:43], v[166:169], v[182:185], v[40:43]
	v_mfma_f32_16x16x32_bf16 v[28:31], v[142:145], v[206:209], v[28:31]
	v_mfma_f32_16x16x32_bf16 v[24:27], v[166:169], v[206:209], v[24:27]
	v_mfma_f32_16x16x32_bf16 v[12:15], v[142:145], v[218:221], v[12:15]
	v_mfma_f32_16x16x32_bf16 v[8:11], v[166:169], v[218:221], v[8:11]
	v_mfma_f32_16x16x32_bf16 v[60:63], v[162:165], v[178:181], v[60:63]
	v_mfma_f32_16x16x32_bf16 v[56:59], v[170:173], v[178:181], v[56:59]
	v_mfma_f32_16x16x32_bf16 v[44:47], v[162:165], v[186:189], v[44:47]
	v_mfma_f32_16x16x32_bf16 v[40:43], v[170:173], v[186:189], v[40:43]
	v_mfma_f32_16x16x32_bf16 v[28:31], v[162:165], v[214:217], v[28:31]
	v_mfma_f32_16x16x32_bf16 v[24:27], v[170:173], v[214:217], v[24:27]
	v_mfma_f32_16x16x32_bf16 v[12:15], v[162:165], v[222:225], v[12:15]
	v_mfma_f32_16x16x32_bf16 v[8:11], v[170:173], v[222:225], v[8:11]
	s_barrier
	s_add_i32 s2, s2, s54
	v_lshl_add_u64 v[142:143], v[250:251], 0, s[50:51]
	s_mov_b32 m0, s2
	s_nop 0
	global_load_lds_dwordx4 v[142:143], off
	v_lshl_add_u64 v[142:143], v[252:253], 0, s[50:51]
	s_add_i32 m0, s2, 0x2000
	s_nop 0
	global_load_lds_dwordx4 v[142:143], off
	s_waitcnt vmcnt(6)
	s_barrier
	v_mfma_f32_16x16x32_bf16 v[52:55], v[226:229], v[174:177], v[52:55]
	v_mfma_f32_16x16x32_bf16 v[48:51], v[234:237], v[174:177], v[48:51]
	v_mfma_f32_16x16x32_bf16 v[36:39], v[226:229], v[182:185], v[36:39]
	v_mfma_f32_16x16x32_bf16 v[32:35], v[234:237], v[182:185], v[32:35]
	v_mfma_f32_16x16x32_bf16 v[20:23], v[226:229], v[206:209], v[20:23]
	v_mfma_f32_16x16x32_bf16 v[16:19], v[234:237], v[206:209], v[16:19]
	v_mfma_f32_16x16x32_bf16 v[4:7], v[226:229], v[218:221], v[4:7]
	v_mfma_f32_16x16x32_bf16 v[0:3], v[234:237], v[218:221], v[0:3]
	v_mfma_f32_16x16x32_bf16 v[52:55], v[230:233], v[178:181], v[52:55]
	v_mfma_f32_16x16x32_bf16 v[48:51], v[238:241], v[178:181], v[48:51]
	v_mfma_f32_16x16x32_bf16 v[36:39], v[230:233], v[186:189], v[36:39]
	v_mfma_f32_16x16x32_bf16 v[32:35], v[238:241], v[186:189], v[32:35]
	v_mfma_f32_16x16x32_bf16 v[20:23], v[230:233], v[214:217], v[20:23]
	v_mfma_f32_16x16x32_bf16 v[16:19], v[238:241], v[214:217], v[16:19]
	v_mfma_f32_16x16x32_bf16 v[4:7], v[230:233], v[222:225], v[4:7]
	v_mfma_f32_16x16x32_bf16 v[0:3], v[238:241], v[222:225], v[0:3]
	s_add_u32 s10, s10, 0x100
	s_addc_u32 s40, s40, 0
	s_add_u32 s6, s6, 0x100
	s_addc_u32 s7, s7, 0
	s_cmp_ge_i32 s41, s66
	s_mov_b32 s2, s41
	s_barrier
	s_cbranch_scc0 .LBB0_197

.LBB0_270:
	v_lshl_add_u64 v[0:1], s[40:41], 0, v[156:157]
	v_mov_b32_e32 v129, v157
	v_lshl_add_u64 v[4:5], s[2:3], 0, v[156:157]
	v_lshl_add_u64 v[6:7], s[2:3], 0, v[128:129]
	s_lshl_b32 s2, s19, 5
	s_add_i32 m0, s25, 0x18000
	v_lshl_add_u64 v[0:1], v[0:1], 0, s[50:51]
	s_and_b32 s19, s2, 0x60
	s_waitcnt vmcnt(4)
	s_barrier
	global_load_lds_dwordx4 v[0:1], off
	s_add_i32 m0, s25, 0x1a000
	v_lshl_add_u64 v[2:3], s[40:41], 0, v[128:129]
	s_add_u32 s2, s26, 0x1a4a4080
	v_lshl_add_u64 v[0:1], v[2:3], 0, s[50:51]
	s_addc_u32 s3, s27, 0
	s_add_i32 s45, s25, 0x8000
	global_load_lds_dwordx4 v[0:1], off
	v_lshl_add_u64 v[0:1], s[2:3], 0, v[156:157]
	s_mov_b32 m0, s45
	s_add_i32 s48, s25, 0xa000
	global_load_lds_dwordx4 v[0:1], off
	v_lshl_add_u64 v[0:1], s[2:3], 0, v[128:129]
	s_mov_b32 m0, s48
	v_mov_b32_e32 v127, 0
	global_load_lds_dwordx4 v[0:1], off
	s_add_i32 m0, s25, 0x1c000
	v_lshl_add_u64 v[0:1], v[4:5], 0, s[50:51]
	global_load_lds_dwordx4 v[0:1], off
	v_lshl_add_u64 v[0:1], v[6:7], 0, s[50:51]
	s_add_i32 m0, s25, 0x1e000
	v_lshl_or_b32 v134, s42, 6, v149
	global_load_lds_dwordx4 v[0:1], off
	s_waitcnt vmcnt(6)
	s_cmp_lt_i32 s6, 64
	v_mov_b32_e32 v126, v127
	v_mov_b32_e32 v125, v127
	v_mov_b32_e32 v124, v127
	v_mov_b32_e32 v123, v127
	v_mov_b32_e32 v122, v127
	v_mov_b32_e32 v121, v127
	v_mov_b32_e32 v120, v127
	v_mov_b32_e32 v111, v127
	v_mov_b32_e32 v110, v127
	v_mov_b32_e32 v109, v127
	v_mov_b32_e32 v108, v127
	v_mov_b32_e32 v107, v127
	v_mov_b32_e32 v106, v127
	v_mov_b32_e32 v105, v127
	v_mov_b32_e32 v104, v127
	v_mov_b32_e32 v95, v127
	v_mov_b32_e32 v94, v127
	v_mov_b32_e32 v93, v127
	v_mov_b32_e32 v92, v127
	v_mov_b32_e32 v91, v127
	v_mov_b32_e32 v90, v127
	v_mov_b32_e32 v89, v127
	v_mov_b32_e32 v88, v127
	v_mov_b32_e32 v79, v127
	v_mov_b32_e32 v78, v127
	v_mov_b32_e32 v77, v127
	v_mov_b32_e32 v76, v127
	v_mov_b32_e32 v75, v127
	v_mov_b32_e32 v74, v127
	v_mov_b32_e32 v73, v127
	v_mov_b32_e32 v72, v127
	v_mov_b32_e32 v119, v127
	v_mov_b32_e32 v118, v127
	v_mov_b32_e32 v117, v127
	v_mov_b32_e32 v116, v127
	v_mov_b32_e32 v115, v127
	v_mov_b32_e32 v114, v127
	v_mov_b32_e32 v113, v127
	v_mov_b32_e32 v112, v127
	v_mov_b32_e32 v103, v127
	v_mov_b32_e32 v102, v127
	v_mov_b32_e32 v101, v127
	v_mov_b32_e32 v100, v127
	v_mov_b32_e32 v99, v127
	v_mov_b32_e32 v98, v127
	v_mov_b32_e32 v97, v127
	v_mov_b32_e32 v96, v127
	v_mov_b32_e32 v87, v127
	v_mov_b32_e32 v86, v127
	v_mov_b32_e32 v85, v127
	v_mov_b32_e32 v84, v127
	v_mov_b32_e32 v83, v127
	v_mov_b32_e32 v82, v127
	v_mov_b32_e32 v81, v127
	v_mov_b32_e32 v80, v127
	v_mov_b32_e32 v71, v127
	v_mov_b32_e32 v70, v127
	v_mov_b32_e32 v69, v127
	v_mov_b32_e32 v68, v127
	v_mov_b32_e32 v67, v127
	v_mov_b32_e32 v66, v127
	v_mov_b32_e32 v65, v127
	v_mov_b32_e32 v64, v127
	v_mov_b32_e32 v63, v127
	v_mov_b32_e32 v62, v127
	v_mov_b32_e32 v61, v127
	v_mov_b32_e32 v60, v127
	v_mov_b32_e32 v59, v127
	v_mov_b32_e32 v58, v127
	v_mov_b32_e32 v57, v127
	v_mov_b32_e32 v56, v127
	v_mov_b32_e32 v47, v127
	v_mov_b32_e32 v46, v127
	v_mov_b32_e32 v45, v127
	v_mov_b32_e32 v44, v127
	v_mov_b32_e32 v43, v127
	v_mov_b32_e32 v42, v127
	v_mov_b32_e32 v41, v127
	v_mov_b32_e32 v40, v127
	v_mov_b32_e32 v31, v127
	v_mov_b32_e32 v30, v127
	v_mov_b32_e32 v29, v127
	v_mov_b32_e32 v28, v127
	v_mov_b32_e32 v27, v127
	v_mov_b32_e32 v26, v127
	v_mov_b32_e32 v25, v127
	v_mov_b32_e32 v24, v127
	v_mov_b32_e32 v15, v127
	v_mov_b32_e32 v14, v127
	v_mov_b32_e32 v13, v127
	v_mov_b32_e32 v12, v127
	v_mov_b32_e32 v11, v127
	v_mov_b32_e32 v10, v127
	v_mov_b32_e32 v9, v127
	v_mov_b32_e32 v8, v127
	v_mov_b32_e32 v55, v127
	v_mov_b32_e32 v54, v127
	v_mov_b32_e32 v53, v127
	v_mov_b32_e32 v52, v127
	v_mov_b32_e32 v51, v127
	v_mov_b32_e32 v50, v127
	v_mov_b32_e32 v49, v127
	v_mov_b32_e32 v48, v127
	v_mov_b32_e32 v39, v127
	v_mov_b32_e32 v38, v127
	v_mov_b32_e32 v37, v127
	v_mov_b32_e32 v36, v127
	v_mov_b32_e32 v35, v127
	v_mov_b32_e32 v34, v127
	v_mov_b32_e32 v33, v127
	v_mov_b32_e32 v32, v127
	v_mov_b32_e32 v23, v127
	v_mov_b32_e32 v22, v127
	v_mov_b32_e32 v21, v127
	v_mov_b32_e32 v20, v127
	v_mov_b32_e32 v19, v127
	v_mov_b32_e32 v18, v127
	v_mov_b32_e32 v17, v127
	v_mov_b32_e32 v16, v127
	v_mov_b32_e32 v7, v127
	v_mov_b32_e32 v6, v127
	v_mov_b32_e32 v5, v127
	v_mov_b32_e32 v4, v127
	v_mov_b32_e32 v3, v127
	v_mov_b32_e32 v2, v127
	v_mov_b32_e32 v1, v127
	v_mov_b32_e32 v0, v127
	s_barrier
	s_cbranch_scc1 .LBB0_273
	s_lshr_b32 s2, s7, 26
	s_add_i32 s2, s6, s2
	s_ashr_i32 s49, s2, 6
	v_lshlrev_b32_e32 v0, 6, v134
	s_movk_i32 s2, 0x3c0
	v_lshlrev_b32_e32 v1, 2, v134
	s_add_i32 s53, s49, -2
	v_and_or_b32 v0, v0, s2, v147
	s_lshl_b32 s2, s42, 13
	v_and_b32_e32 v1, 32, v1
	v_bitop3_b32 v2, v0, s2, v1 bitop3:0xde
	s_add_u32 s2, s26, s36
	v_add_u32_e32 v0, v132, v133
	s_addc_u32 s3, s27, s37
	v_add_lshl_u32 v0, v0, v146, 1
	v_mov_b32_e32 v1, v157
	v_lshl_add_u64 v[132:133], s[2:3], 0, v[0:1]
	v_lshl_or_b32 v135, s19, 7, v148
	v_lshl_add_u64 v[130:131], s[2:3], 0, v[128:129]
	s_mov_b32 s2, 0
	s_mov_b64 s[6:7], 0x1a4a4080
	v_add_u32_e32 v136, 0, v2
	s_add_i32 s54, s2, 2
	s_add_u32 s3, s6, 0xe5b5c080
	s_addc_u32 s21, s7, -1
	s_cmp_lg_u32 s53, s2
	s_cselect_b32 s42, s3, 0
	s_cselect_b32 s21, s21, 0
	s_add_u32 s2, s38, s42
	s_addc_u32 s3, s39, s21
	s_add_i32 s55, 0, 0x10000
	v_add_u32_e32 v137, s55, v135
	ds_read_b128 v[142:145], v137
	ds_read_b128 v[146:149], v137 offset:1024
	ds_read_b128 v[150:153], v137 offset:2048
	ds_read_b128 v[162:165], v137 offset:3072
	s_add_u32 s42, s40, s42
	s_addc_u32 s43, s41, s21
	v_lshl_add_u64 v[138:139], v[132:133], 0, s[6:7]
	s_add_i32 m0, s25, 0xc000
	ds_read_b128 v[166:169], v136
	ds_read_b128 v[170:173], v136 offset:1024
	ds_read_b128 v[174:177], v136 offset:2048
	ds_read_b128 v[178:181], v136 offset:3072
	ds_read_b128 v[182:185], v136 offset:4096
	ds_read_b128 v[186:189], v136 offset:5120
	ds_read_b128 v[206:209], v136 offset:6144
	ds_read_b128 v[214:217], v136 offset:7168
	global_load_lds_dwordx4 v[138:139], off
	v_lshl_add_u64 v[138:139], v[130:131], 0, s[6:7]
	s_add_i32 m0, s25, 0xe000
	s_nop 0
	global_load_lds_dwordx4 v[138:139], off
	s_waitcnt lgkmcnt(8)
	s_barrier
	s_waitcnt lgkmcnt(0)
	v_mfma_f32_16x16x32_bf16 v[124:127], v[142:145], v[166:169], 0
	v_mfma_f32_16x16x32_bf16 v[120:123], v[150:153], v[166:169], 0
	v_mfma_f32_16x16x32_bf16 v[108:111], v[142:145], v[174:177], 0
	v_mfma_f32_16x16x32_bf16 v[104:107], v[150:153], v[174:177], 0
	v_mfma_f32_16x16x32_bf16 v[92:95], v[142:145], v[182:185], 0
	v_mfma_f32_16x16x32_bf16 v[88:91], v[150:153], v[182:185], 0
	v_mfma_f32_16x16x32_bf16 v[76:79], v[142:145], v[206:209], 0
	v_mfma_f32_16x16x32_bf16 v[72:75], v[150:153], v[206:209], 0
	v_mfma_f32_16x16x32_bf16 v[124:127], v[146:149], v[170:173], v[124:127]
	v_mfma_f32_16x16x32_bf16 v[120:123], v[162:165], v[170:173], v[120:123]
	v_mfma_f32_16x16x32_bf16 v[108:111], v[146:149], v[178:181], v[108:111]
	v_mfma_f32_16x16x32_bf16 v[104:107], v[162:165], v[178:181], v[104:107]
	v_mfma_f32_16x16x32_bf16 v[92:95], v[146:149], v[186:189], v[92:95]
	v_mfma_f32_16x16x32_bf16 v[88:91], v[162:165], v[186:189], v[88:91]
	v_mfma_f32_16x16x32_bf16 v[76:79], v[146:149], v[214:217], v[76:79]
	v_mfma_f32_16x16x32_bf16 v[72:75], v[162:165], v[214:217], v[72:75]
	s_barrier
	s_add_i32 s21, 0, 0x14000
	s_add_i32 s55, s55, s24
	v_add_u32_e32 v137, s21, v135
	v_lshl_add_u64 v[138:139], s[42:43], 0, v[156:157]
	s_mov_b32 m0, s55
	ds_read_b128 v[218:221], v137
	ds_read_b128 v[222:225], v137 offset:1024
	ds_read_b128 v[226:229], v137 offset:2048
	ds_read_b128 v[230:233], v137 offset:3072
	global_load_lds_dwordx4 v[138:139], off
	v_lshl_add_u64 v[154:155], s[42:43], 0, v[128:129]
	s_add_i32 m0, s55, 0x2000
	s_nop 0
	global_load_lds_dwordx4 v[154:155], off
	s_barrier
	s_waitcnt lgkmcnt(0)
	v_mfma_f32_16x16x32_bf16 v[116:119], v[218:221], v[166:169], 0
	v_mfma_f32_16x16x32_bf16 v[112:115], v[226:229], v[166:169], 0
	v_mfma_f32_16x16x32_bf16 v[100:103], v[218:221], v[174:177], 0
	v_mfma_f32_16x16x32_bf16 v[96:99], v[226:229], v[174:177], 0
	v_mfma_f32_16x16x32_bf16 v[84:87], v[218:221], v[182:185], 0
	v_mfma_f32_16x16x32_bf16 v[80:83], v[226:229], v[182:185], 0
	v_mfma_f32_16x16x32_bf16 v[68:71], v[218:221], v[206:209], 0
	v_mfma_f32_16x16x32_bf16 v[64:67], v[226:229], v[206:209], 0
	v_mfma_f32_16x16x32_bf16 v[116:119], v[222:225], v[170:173], v[116:119]
	v_mfma_f32_16x16x32_bf16 v[112:115], v[230:233], v[170:173], v[112:115]
	v_mfma_f32_16x16x32_bf16 v[100:103], v[222:225], v[178:181], v[100:103]
	v_mfma_f32_16x16x32_bf16 v[96:99], v[230:233], v[178:181], v[96:99]
	v_mfma_f32_16x16x32_bf16 v[84:87], v[222:225], v[186:189], v[84:87]
	v_mfma_f32_16x16x32_bf16 v[80:83], v[230:233], v[186:189], v[80:83]
	v_mfma_f32_16x16x32_bf16 v[68:71], v[222:225], v[214:217], v[68:71]
	v_mfma_f32_16x16x32_bf16 v[64:67], v[230:233], v[214:217], v[64:67]
	s_mov_b32 m0, s25
	v_lshl_add_u64 v[234:235], s[2:3], 0, v[156:157]
	s_barrier
	ds_read_b128 v[166:169], v136 offset:16384
	ds_read_b128 v[170:173], v136 offset:17408
	ds_read_b128 v[174:177], v136 offset:18432
	ds_read_b128 v[178:181], v136 offset:19456
	ds_read_b128 v[182:185], v136 offset:20480
	ds_read_b128 v[186:189], v136 offset:21504
	ds_read_b128 v[206:209], v136 offset:22528
	ds_read_b128 v[214:217], v136 offset:23552
	global_load_lds_dwordx4 v[234:235], off
	v_lshl_add_u64 v[236:237], s[2:3], 0, v[128:129]
	s_mov_b32 m0, s34
	s_nop 0
	global_load_lds_dwordx4 v[236:237], off
	s_barrier
	s_waitcnt lgkmcnt(0)
	v_mfma_f32_16x16x32_bf16 v[60:63], v[142:145], v[166:169], 0
	v_mfma_f32_16x16x32_bf16 v[56:59], v[150:153], v[166:169], 0
	v_mfma_f32_16x16x32_bf16 v[44:47], v[142:145], v[174:177], 0
	v_mfma_f32_16x16x32_bf16 v[40:43], v[150:153], v[174:177], 0
	v_mfma_f32_16x16x32_bf16 v[28:31], v[142:145], v[182:185], 0
	v_mfma_f32_16x16x32_bf16 v[24:27], v[150:153], v[182:185], 0
	v_mfma_f32_16x16x32_bf16 v[12:15], v[142:145], v[206:209], 0
	v_mfma_f32_16x16x32_bf16 v[8:11], v[150:153], v[206:209], 0
	v_mfma_f32_16x16x32_bf16 v[60:63], v[146:149], v[170:173], v[60:63]
	v_mfma_f32_16x16x32_bf16 v[56:59], v[162:165], v[170:173], v[56:59]
	v_mfma_f32_16x16x32_bf16 v[44:47], v[146:149], v[178:181], v[44:47]
	v_mfma_f32_16x16x32_bf16 v[40:43], v[162:165], v[178:181], v[40:43]
	v_mfma_f32_16x16x32_bf16 v[28:31], v[146:149], v[186:189], v[28:31]
	v_mfma_f32_16x16x32_bf16 v[24:27], v[162:165], v[186:189], v[24:27]
	v_mfma_f32_16x16x32_bf16 v[12:15], v[146:149], v[214:217], v[12:15]
	v_mfma_f32_16x16x32_bf16 v[8:11], v[162:165], v[214:217], v[8:11]
	s_barrier
	s_add_u32 s42, s42, s36
	s_addc_u32 s43, s43, s37
	s_add_i32 s21, s21, s24
	v_lshl_add_u64 v[238:239], s[42:43], 0, v[156:157]
	s_mov_b32 m0, s21
	v_lshl_add_u64 v[240:241], s[42:43], 0, v[128:129]
	global_load_lds_dwordx4 v[238:239], off
	s_add_i32 m0, s21, 0x2000
	s_nop 0
	global_load_lds_dwordx4 v[240:241], off
	s_waitcnt vmcnt(6)
	s_barrier
	v_mfma_f32_16x16x32_bf16 v[52:55], v[218:221], v[166:169], 0
	v_mfma_f32_16x16x32_bf16 v[48:51], v[226:229], v[166:169], 0
	v_mfma_f32_16x16x32_bf16 v[36:39], v[218:221], v[174:177], 0
	v_mfma_f32_16x16x32_bf16 v[32:35], v[226:229], v[174:177], 0
	v_mfma_f32_16x16x32_bf16 v[20:23], v[218:221], v[182:185], 0
	v_mfma_f32_16x16x32_bf16 v[16:19], v[226:229], v[182:185], 0
	v_mfma_f32_16x16x32_bf16 v[4:7], v[218:221], v[206:209], 0
	v_mfma_f32_16x16x32_bf16 v[0:3], v[226:229], v[206:209], 0
	v_mfma_f32_16x16x32_bf16 v[52:55], v[222:225], v[170:173], v[52:55]
	v_mfma_f32_16x16x32_bf16 v[48:51], v[230:233], v[170:173], v[48:51]
	v_mfma_f32_16x16x32_bf16 v[36:39], v[222:225], v[178:181], v[36:39]
	v_mfma_f32_16x16x32_bf16 v[32:35], v[230:233], v[178:181], v[32:35]
	v_mfma_f32_16x16x32_bf16 v[20:23], v[222:225], v[186:189], v[20:23]
	v_mfma_f32_16x16x32_bf16 v[16:19], v[230:233], v[186:189], v[16:19]
	v_mfma_f32_16x16x32_bf16 v[4:7], v[222:225], v[214:217], v[4:7]
	v_mfma_f32_16x16x32_bf16 v[0:3], v[230:233], v[214:217], v[0:3]
	s_add_i32 s21, 0, 0x18000
	v_add_u32_e32 v137, s21, v135
	s_barrier
	ds_read_b128 v[142:145], v137
	ds_read_b128 v[146:149], v137 offset:1024
	ds_read_b128 v[150:153], v137 offset:2048
	ds_read_b128 v[162:165], v137 offset:3072
	s_add_u32 s2, s2, s36
	s_addc_u32 s3, s3, s37
	s_mov_b32 m0, s35
	v_lshl_add_u64 v[218:219], s[2:3], 0, v[156:157]
	ds_read_b128 v[166:169], v136 offset:32768
	ds_read_b128 v[170:173], v136 offset:33792
	ds_read_b128 v[174:177], v136 offset:34816
	ds_read_b128 v[178:181], v136 offset:35840
	ds_read_b128 v[182:185], v136 offset:36864
	ds_read_b128 v[186:189], v136 offset:37888
	ds_read_b128 v[206:209], v136 offset:38912
	ds_read_b128 v[214:217], v136 offset:39936
	global_load_lds_dwordx4 v[218:219], off
	v_lshl_add_u64 v[218:219], s[2:3], 0, v[128:129]
	s_mov_b32 m0, s44
	s_nop 0
	global_load_lds_dwordx4 v[218:219], off
	s_waitcnt lgkmcnt(8)
	s_barrier
	s_waitcnt lgkmcnt(0)
	v_mfma_f32_16x16x32_bf16 v[124:127], v[142:145], v[166:169], v[124:127]
	v_mfma_f32_16x16x32_bf16 v[120:123], v[150:153], v[166:169], v[120:123]
	v_mfma_f32_16x16x32_bf16 v[108:111], v[142:145], v[174:177], v[108:111]
	v_mfma_f32_16x16x32_bf16 v[104:107], v[150:153], v[174:177], v[104:107]
	v_mfma_f32_16x16x32_bf16 v[92:95], v[142:145], v[182:185], v[92:95]
	v_mfma_f32_16x16x32_bf16 v[88:91], v[150:153], v[182:185], v[88:91]
	v_mfma_f32_16x16x32_bf16 v[76:79], v[142:145], v[206:209], v[76:79]
	v_mfma_f32_16x16x32_bf16 v[72:75], v[150:153], v[206:209], v[72:75]
	v_mfma_f32_16x16x32_bf16 v[124:127], v[146:149], v[170:173], v[124:127]
	v_mfma_f32_16x16x32_bf16 v[120:123], v[162:165], v[170:173], v[120:123]
	v_mfma_f32_16x16x32_bf16 v[108:111], v[146:149], v[178:181], v[108:111]
	v_mfma_f32_16x16x32_bf16 v[104:107], v[162:165], v[178:181], v[104:107]
	v_mfma_f32_16x16x32_bf16 v[92:95], v[146:149], v[186:189], v[92:95]
	v_mfma_f32_16x16x32_bf16 v[88:91], v[162:165], v[186:189], v[88:91]
	v_mfma_f32_16x16x32_bf16 v[76:79], v[146:149], v[214:217], v[76:79]
	v_mfma_f32_16x16x32_bf16 v[72:75], v[162:165], v[214:217], v[72:75]
	s_barrier
	s_add_i32 s2, 0, 0x1c000
	s_add_i32 s3, s21, s24
	v_add_u32_e32 v137, s2, v135
	v_lshl_add_u64 v[138:139], v[138:139], 0, s[50:51]
	s_mov_b32 m0, s3
	ds_read_b128 v[218:221], v137
	ds_read_b128 v[222:225], v137 offset:1024
	ds_read_b128 v[226:229], v137 offset:2048
	ds_read_b128 v[230:233], v137 offset:3072
	global_load_lds_dwordx4 v[138:139], off
	v_lshl_add_u64 v[138:139], v[154:155], 0, s[50:51]
	s_add_i32 m0, s3, 0x2000
	s_nop 0
	global_load_lds_dwordx4 v[138:139], off
	s_barrier
	s_waitcnt lgkmcnt(0)
	v_mfma_f32_16x16x32_bf16 v[116:119], v[218:221], v[166:169], v[116:119]
	v_mfma_f32_16x16x32_bf16 v[112:115], v[226:229], v[166:169], v[112:115]
	v_mfma_f32_16x16x32_bf16 v[100:103], v[218:221], v[174:177], v[100:103]
	v_mfma_f32_16x16x32_bf16 v[96:99], v[226:229], v[174:177], v[96:99]
	v_mfma_f32_16x16x32_bf16 v[84:87], v[218:221], v[182:185], v[84:87]
	v_mfma_f32_16x16x32_bf16 v[80:83], v[226:229], v[182:185], v[80:83]
	v_mfma_f32_16x16x32_bf16 v[68:71], v[218:221], v[206:209], v[68:71]
	v_mfma_f32_16x16x32_bf16 v[64:67], v[226:229], v[206:209], v[64:67]
	v_mfma_f32_16x16x32_bf16 v[116:119], v[222:225], v[170:173], v[116:119]
	v_mfma_f32_16x16x32_bf16 v[112:115], v[230:233], v[170:173], v[112:115]
	v_mfma_f32_16x16x32_bf16 v[100:103], v[222:225], v[178:181], v[100:103]
	v_mfma_f32_16x16x32_bf16 v[96:99], v[230:233], v[178:181], v[96:99]
	v_mfma_f32_16x16x32_bf16 v[84:87], v[222:225], v[186:189], v[84:87]
	v_mfma_f32_16x16x32_bf16 v[80:83], v[230:233], v[186:189], v[80:83]
	v_mfma_f32_16x16x32_bf16 v[68:71], v[222:225], v[214:217], v[68:71]
	v_mfma_f32_16x16x32_bf16 v[64:67], v[230:233], v[214:217], v[64:67]
	s_mov_b32 m0, s45
	v_lshl_add_u64 v[138:139], v[234:235], 0, s[50:51]
	s_barrier
	ds_read_b128 v[166:169], v136 offset:49152
	ds_read_b128 v[170:173], v136 offset:50176
	ds_read_b128 v[174:177], v136 offset:51200
	ds_read_b128 v[178:181], v136 offset:52224
	ds_read_b128 v[182:185], v136 offset:53248
	ds_read_b128 v[186:189], v136 offset:54272
	ds_read_b128 v[206:209], v136 offset:55296
	ds_read_b128 v[214:217], v136 offset:56320
	global_load_lds_dwordx4 v[138:139], off
	v_lshl_add_u64 v[138:139], v[236:237], 0, s[50:51]
	s_mov_b32 m0, s48
	s_nop 0
	global_load_lds_dwordx4 v[138:139], off
	s_barrier
	s_waitcnt lgkmcnt(0)
	v_mfma_f32_16x16x32_bf16 v[60:63], v[142:145], v[166:169], v[60:63]
	v_mfma_f32_16x16x32_bf16 v[56:59], v[150:153], v[166:169], v[56:59]
	v_mfma_f32_16x16x32_bf16 v[44:47], v[142:145], v[174:177], v[44:47]
	v_mfma_f32_16x16x32_bf16 v[40:43], v[150:153], v[174:177], v[40:43]
	v_mfma_f32_16x16x32_bf16 v[28:31], v[142:145], v[182:185], v[28:31]
	v_mfma_f32_16x16x32_bf16 v[24:27], v[150:153], v[182:185], v[24:27]
	v_mfma_f32_16x16x32_bf16 v[12:15], v[142:145], v[206:209], v[12:15]
	v_mfma_f32_16x16x32_bf16 v[8:11], v[150:153], v[206:209], v[8:11]
	v_mfma_f32_16x16x32_bf16 v[60:63], v[146:149], v[170:173], v[60:63]
	v_mfma_f32_16x16x32_bf16 v[56:59], v[162:165], v[170:173], v[56:59]
	v_mfma_f32_16x16x32_bf16 v[44:47], v[146:149], v[178:181], v[44:47]
	v_mfma_f32_16x16x32_bf16 v[40:43], v[162:165], v[178:181], v[40:43]
	v_mfma_f32_16x16x32_bf16 v[28:31], v[146:149], v[186:189], v[28:31]
	v_mfma_f32_16x16x32_bf16 v[24:27], v[162:165], v[186:189], v[24:27]
	v_mfma_f32_16x16x32_bf16 v[12:15], v[146:149], v[214:217], v[12:15]
	v_mfma_f32_16x16x32_bf16 v[8:11], v[162:165], v[214:217], v[8:11]
	s_barrier
	s_add_i32 s2, s2, s24
	v_lshl_add_u64 v[138:139], v[238:239], 0, s[50:51]
	s_mov_b32 m0, s2
	s_nop 0
	global_load_lds_dwordx4 v[138:139], off
	v_lshl_add_u64 v[138:139], v[240:241], 0, s[50:51]
	s_add_i32 m0, s2, 0x2000
	s_nop 0
	global_load_lds_dwordx4 v[138:139], off
	s_waitcnt vmcnt(6)
	s_barrier
	v_mfma_f32_16x16x32_bf16 v[52:55], v[218:221], v[166:169], v[52:55]
	v_mfma_f32_16x16x32_bf16 v[48:51], v[226:229], v[166:169], v[48:51]
	v_mfma_f32_16x16x32_bf16 v[36:39], v[218:221], v[174:177], v[36:39]
	v_mfma_f32_16x16x32_bf16 v[32:35], v[226:229], v[174:177], v[32:35]
	v_mfma_f32_16x16x32_bf16 v[20:23], v[218:221], v[182:185], v[20:23]
	v_mfma_f32_16x16x32_bf16 v[16:19], v[226:229], v[182:185], v[16:19]
	v_mfma_f32_16x16x32_bf16 v[4:7], v[218:221], v[206:209], v[4:7]
	v_mfma_f32_16x16x32_bf16 v[0:3], v[226:229], v[206:209], v[0:3]
	v_mfma_f32_16x16x32_bf16 v[52:55], v[222:225], v[170:173], v[52:55]
	v_mfma_f32_16x16x32_bf16 v[48:51], v[230:233], v[170:173], v[48:51]
	v_mfma_f32_16x16x32_bf16 v[36:39], v[222:225], v[178:181], v[36:39]
	v_mfma_f32_16x16x32_bf16 v[32:35], v[230:233], v[178:181], v[32:35]
	v_mfma_f32_16x16x32_bf16 v[20:23], v[222:225], v[186:189], v[20:23]
	v_mfma_f32_16x16x32_bf16 v[16:19], v[230:233], v[186:189], v[16:19]
	v_mfma_f32_16x16x32_bf16 v[4:7], v[222:225], v[214:217], v[4:7]
	v_mfma_f32_16x16x32_bf16 v[0:3], v[230:233], v[214:217], v[0:3]
	s_add_u32 s6, s6, 0x100
	s_addc_u32 s7, s7, 0
	s_cmp_ge_i32 s54, s49
	s_mov_b32 s2, s54
	s_barrier
	s_cbranch_scc1 .Lpost_272
.LBB0_272:
	s_add_i32 s54, s2, 2
	s_add_u32 s3, s6, 0xe5b5c080
	s_addc_u32 s21, s7, -1
	s_cmp_lg_u32 s53, s2
	s_cselect_b32 s42, s3, 0
	s_cselect_b32 s21, s21, 0
	s_add_u32 s2, s38, s42
	s_addc_u32 s3, s39, s21
	s_add_i32 s55, 0, 0x10000
	v_add_u32_e32 v137, s55, v135
	ds_read_b128 v[142:145], v137
	ds_read_b128 v[146:149], v137 offset:1024
	ds_read_b128 v[150:153], v137 offset:2048
	ds_read_b128 v[162:165], v137 offset:3072
	s_add_u32 s42, s40, s42
	s_addc_u32 s43, s41, s21
	v_lshl_add_u64 v[138:139], v[132:133], 0, s[6:7]
	s_add_i32 m0, s25, 0xc000
	ds_read_b128 v[166:169], v136
	ds_read_b128 v[170:173], v136 offset:1024
	ds_read_b128 v[174:177], v136 offset:2048
	ds_read_b128 v[178:181], v136 offset:3072
	ds_read_b128 v[182:185], v136 offset:4096
	ds_read_b128 v[186:189], v136 offset:5120
	ds_read_b128 v[206:209], v136 offset:6144
	ds_read_b128 v[214:217], v136 offset:7168
	global_load_lds_dwordx4 v[138:139], off
	v_lshl_add_u64 v[138:139], v[130:131], 0, s[6:7]
	s_add_i32 m0, s25, 0xe000
	s_nop 0
	global_load_lds_dwordx4 v[138:139], off
	s_waitcnt lgkmcnt(8)
	s_barrier
	s_waitcnt lgkmcnt(0)
	v_mfma_f32_16x16x32_bf16 v[124:127], v[142:145], v[166:169], v[124:127]
	v_mfma_f32_16x16x32_bf16 v[120:123], v[150:153], v[166:169], v[120:123]
	v_mfma_f32_16x16x32_bf16 v[108:111], v[142:145], v[174:177], v[108:111]
	v_mfma_f32_16x16x32_bf16 v[104:107], v[150:153], v[174:177], v[104:107]
	v_mfma_f32_16x16x32_bf16 v[92:95], v[142:145], v[182:185], v[92:95]
	v_mfma_f32_16x16x32_bf16 v[88:91], v[150:153], v[182:185], v[88:91]
	v_mfma_f32_16x16x32_bf16 v[76:79], v[142:145], v[206:209], v[76:79]
	v_mfma_f32_16x16x32_bf16 v[72:75], v[150:153], v[206:209], v[72:75]
	v_mfma_f32_16x16x32_bf16 v[124:127], v[146:149], v[170:173], v[124:127]
	v_mfma_f32_16x16x32_bf16 v[120:123], v[162:165], v[170:173], v[120:123]
	v_mfma_f32_16x16x32_bf16 v[108:111], v[146:149], v[178:181], v[108:111]
	v_mfma_f32_16x16x32_bf16 v[104:107], v[162:165], v[178:181], v[104:107]
	v_mfma_f32_16x16x32_bf16 v[92:95], v[146:149], v[186:189], v[92:95]
	v_mfma_f32_16x16x32_bf16 v[88:91], v[162:165], v[186:189], v[88:91]
	v_mfma_f32_16x16x32_bf16 v[76:79], v[146:149], v[214:217], v[76:79]
	v_mfma_f32_16x16x32_bf16 v[72:75], v[162:165], v[214:217], v[72:75]
	s_barrier
	s_add_i32 s21, 0, 0x14000
	s_add_i32 s55, s55, s24
	v_add_u32_e32 v137, s21, v135
	v_lshl_add_u64 v[138:139], s[42:43], 0, v[156:157]
	s_mov_b32 m0, s55
	ds_read_b128 v[218:221], v137
	ds_read_b128 v[222:225], v137 offset:1024
	ds_read_b128 v[226:229], v137 offset:2048
	ds_read_b128 v[230:233], v137 offset:3072
	global_load_lds_dwordx4 v[138:139], off
	v_lshl_add_u64 v[154:155], s[42:43], 0, v[128:129]
	s_add_i32 m0, s55, 0x2000
	s_nop 0
	global_load_lds_dwordx4 v[154:155], off
	s_barrier
	s_waitcnt lgkmcnt(0)
	v_mfma_f32_16x16x32_bf16 v[116:119], v[218:221], v[166:169], v[116:119]
	v_mfma_f32_16x16x32_bf16 v[112:115], v[226:229], v[166:169], v[112:115]
	v_mfma_f32_16x16x32_bf16 v[100:103], v[218:221], v[174:177], v[100:103]
	v_mfma_f32_16x16x32_bf16 v[96:99], v[226:229], v[174:177], v[96:99]
	v_mfma_f32_16x16x32_bf16 v[84:87], v[218:221], v[182:185], v[84:87]
	v_mfma_f32_16x16x32_bf16 v[80:83], v[226:229], v[182:185], v[80:83]
	v_mfma_f32_16x16x32_bf16 v[68:71], v[218:221], v[206:209], v[68:71]
	v_mfma_f32_16x16x32_bf16 v[64:67], v[226:229], v[206:209], v[64:67]
	v_mfma_f32_16x16x32_bf16 v[116:119], v[222:225], v[170:173], v[116:119]
	v_mfma_f32_16x16x32_bf16 v[112:115], v[230:233], v[170:173], v[112:115]
	v_mfma_f32_16x16x32_bf16 v[100:103], v[222:225], v[178:181], v[100:103]
	v_mfma_f32_16x16x32_bf16 v[96:99], v[230:233], v[178:181], v[96:99]
	v_mfma_f32_16x16x32_bf16 v[84:87], v[222:225], v[186:189], v[84:87]
	v_mfma_f32_16x16x32_bf16 v[80:83], v[230:233], v[186:189], v[80:83]
	v_mfma_f32_16x16x32_bf16 v[68:71], v[222:225], v[214:217], v[68:71]
	v_mfma_f32_16x16x32_bf16 v[64:67], v[230:233], v[214:217], v[64:67]
	s_mov_b32 m0, s25
	v_lshl_add_u64 v[234:235], s[2:3], 0, v[156:157]
	s_barrier
	ds_read_b128 v[166:169], v136 offset:16384
	ds_read_b128 v[170:173], v136 offset:17408
	ds_read_b128 v[174:177], v136 offset:18432
	ds_read_b128 v[178:181], v136 offset:19456
	ds_read_b128 v[182:185], v136 offset:20480
	ds_read_b128 v[186:189], v136 offset:21504
	ds_read_b128 v[206:209], v136 offset:22528
	ds_read_b128 v[214:217], v136 offset:23552
	global_load_lds_dwordx4 v[234:235], off
	v_lshl_add_u64 v[236:237], s[2:3], 0, v[128:129]
	s_mov_b32 m0, s34
	s_nop 0
	global_load_lds_dwordx4 v[236:237], off
	s_barrier
	s_waitcnt lgkmcnt(0)
	v_mfma_f32_16x16x32_bf16 v[60:63], v[142:145], v[166:169], v[60:63]
	v_mfma_f32_16x16x32_bf16 v[56:59], v[150:153], v[166:169], v[56:59]
	v_mfma_f32_16x16x32_bf16 v[44:47], v[142:145], v[174:177], v[44:47]
	v_mfma_f32_16x16x32_bf16 v[40:43], v[150:153], v[174:177], v[40:43]
	v_mfma_f32_16x16x32_bf16 v[28:31], v[142:145], v[182:185], v[28:31]
	v_mfma_f32_16x16x32_bf16 v[24:27], v[150:153], v[182:185], v[24:27]
	v_mfma_f32_16x16x32_bf16 v[12:15], v[142:145], v[206:209], v[12:15]
	v_mfma_f32_16x16x32_bf16 v[8:11], v[150:153], v[206:209], v[8:11]
	v_mfma_f32_16x16x32_bf16 v[60:63], v[146:149], v[170:173], v[60:63]
	v_mfma_f32_16x16x32_bf16 v[56:59], v[162:165], v[170:173], v[56:59]
	v_mfma_f32_16x16x32_bf16 v[44:47], v[146:149], v[178:181], v[44:47]
	v_mfma_f32_16x16x32_bf16 v[40:43], v[162:165], v[178:181], v[40:43]
	v_mfma_f32_16x16x32_bf16 v[28:31], v[146:149], v[186:189], v[28:31]
	v_mfma_f32_16x16x32_bf16 v[24:27], v[162:165], v[186:189], v[24:27]
	v_mfma_f32_16x16x32_bf16 v[12:15], v[146:149], v[214:217], v[12:15]
	v_mfma_f32_16x16x32_bf16 v[8:11], v[162:165], v[214:217], v[8:11]
	s_barrier
	s_add_u32 s42, s42, s36
	s_addc_u32 s43, s43, s37
	s_add_i32 s21, s21, s24
	v_lshl_add_u64 v[238:239], s[42:43], 0, v[156:157]
	s_mov_b32 m0, s21
	v_lshl_add_u64 v[240:241], s[42:43], 0, v[128:129]
	global_load_lds_dwordx4 v[238:239], off
	s_add_i32 m0, s21, 0x2000
	s_nop 0
	global_load_lds_dwordx4 v[240:241], off
	s_waitcnt vmcnt(6)
	s_barrier
	v_mfma_f32_16x16x32_bf16 v[52:55], v[218:221], v[166:169], v[52:55]
	v_mfma_f32_16x16x32_bf16 v[48:51], v[226:229], v[166:169], v[48:51]
	v_mfma_f32_16x16x32_bf16 v[36:39], v[218:221], v[174:177], v[36:39]
	v_mfma_f32_16x16x32_bf16 v[32:35], v[226:229], v[174:177], v[32:35]
	v_mfma_f32_16x16x32_bf16 v[20:23], v[218:221], v[182:185], v[20:23]
	v_mfma_f32_16x16x32_bf16 v[16:19], v[226:229], v[182:185], v[16:19]
	v_mfma_f32_16x16x32_bf16 v[4:7], v[218:221], v[206:209], v[4:7]
	v_mfma_f32_16x16x32_bf16 v[0:3], v[226:229], v[206:209], v[0:3]
	v_mfma_f32_16x16x32_bf16 v[52:55], v[222:225], v[170:173], v[52:55]
	v_mfma_f32_16x16x32_bf16 v[48:51], v[230:233], v[170:173], v[48:51]
	v_mfma_f32_16x16x32_bf16 v[36:39], v[222:225], v[178:181], v[36:39]
	v_mfma_f32_16x16x32_bf16 v[32:35], v[230:233], v[178:181], v[32:35]
	v_mfma_f32_16x16x32_bf16 v[20:23], v[222:225], v[186:189], v[20:23]
	v_mfma_f32_16x16x32_bf16 v[16:19], v[230:233], v[186:189], v[16:19]
	v_mfma_f32_16x16x32_bf16 v[4:7], v[222:225], v[214:217], v[4:7]
	v_mfma_f32_16x16x32_bf16 v[0:3], v[230:233], v[214:217], v[0:3]
	s_add_i32 s21, 0, 0x18000
	v_add_u32_e32 v137, s21, v135
	s_barrier
	ds_read_b128 v[142:145], v137
	ds_read_b128 v[146:149], v137 offset:1024
	ds_read_b128 v[150:153], v137 offset:2048
	ds_read_b128 v[162:165], v137 offset:3072
	s_add_u32 s2, s2, s36
	s_addc_u32 s3, s3, s37
	s_mov_b32 m0, s35
	v_lshl_add_u64 v[218:219], s[2:3], 0, v[156:157]
	ds_read_b128 v[166:169], v136 offset:32768
	ds_read_b128 v[170:173], v136 offset:33792
	ds_read_b128 v[174:177], v136 offset:34816
	ds_read_b128 v[178:181], v136 offset:35840
	ds_read_b128 v[182:185], v136 offset:36864
	ds_read_b128 v[186:189], v136 offset:37888
	ds_read_b128 v[206:209], v136 offset:38912
	ds_read_b128 v[214:217], v136 offset:39936
	global_load_lds_dwordx4 v[218:219], off
	v_lshl_add_u64 v[218:219], s[2:3], 0, v[128:129]
	s_mov_b32 m0, s44
	s_nop 0
	global_load_lds_dwordx4 v[218:219], off
	s_waitcnt lgkmcnt(8)
	s_barrier
	s_waitcnt lgkmcnt(0)
	v_mfma_f32_16x16x32_bf16 v[124:127], v[142:145], v[166:169], v[124:127]
	v_mfma_f32_16x16x32_bf16 v[120:123], v[150:153], v[166:169], v[120:123]
	v_mfma_f32_16x16x32_bf16 v[108:111], v[142:145], v[174:177], v[108:111]
	v_mfma_f32_16x16x32_bf16 v[104:107], v[150:153], v[174:177], v[104:107]
	v_mfma_f32_16x16x32_bf16 v[92:95], v[142:145], v[182:185], v[92:95]
	v_mfma_f32_16x16x32_bf16 v[88:91], v[150:153], v[182:185], v[88:91]
	v_mfma_f32_16x16x32_bf16 v[76:79], v[142:145], v[206:209], v[76:79]
	v_mfma_f32_16x16x32_bf16 v[72:75], v[150:153], v[206:209], v[72:75]
	v_mfma_f32_16x16x32_bf16 v[124:127], v[146:149], v[170:173], v[124:127]
	v_mfma_f32_16x16x32_bf16 v[120:123], v[162:165], v[170:173], v[120:123]
	v_mfma_f32_16x16x32_bf16 v[108:111], v[146:149], v[178:181], v[108:111]
	v_mfma_f32_16x16x32_bf16 v[104:107], v[162:165], v[178:181], v[104:107]
	v_mfma_f32_16x16x32_bf16 v[92:95], v[146:149], v[186:189], v[92:95]
	v_mfma_f32_16x16x32_bf16 v[88:91], v[162:165], v[186:189], v[88:91]
	v_mfma_f32_16x16x32_bf16 v[76:79], v[146:149], v[214:217], v[76:79]
	v_mfma_f32_16x16x32_bf16 v[72:75], v[162:165], v[214:217], v[72:75]
	s_barrier
	s_add_i32 s2, 0, 0x1c000
	s_add_i32 s3, s21, s24
	v_add_u32_e32 v137, s2, v135
	v_lshl_add_u64 v[138:139], v[138:139], 0, s[50:51]
	s_mov_b32 m0, s3
	ds_read_b128 v[218:221], v137
	ds_read_b128 v[222:225], v137 offset:1024
	ds_read_b128 v[226:229], v137 offset:2048
	ds_read_b128 v[230:233], v137 offset:3072
	global_load_lds_dwordx4 v[138:139], off
	v_lshl_add_u64 v[138:139], v[154:155], 0, s[50:51]
	s_add_i32 m0, s3, 0x2000
	s_nop 0
	global_load_lds_dwordx4 v[138:139], off
	s_barrier
	s_waitcnt lgkmcnt(0)
	v_mfma_f32_16x16x32_bf16 v[116:119], v[218:221], v[166:169], v[116:119]
	v_mfma_f32_16x16x32_bf16 v[112:115], v[226:229], v[166:169], v[112:115]
	v_mfma_f32_16x16x32_bf16 v[100:103], v[218:221], v[174:177], v[100:103]
	v_mfma_f32_16x16x32_bf16 v[96:99], v[226:229], v[174:177], v[96:99]
	v_mfma_f32_16x16x32_bf16 v[84:87], v[218:221], v[182:185], v[84:87]
	v_mfma_f32_16x16x32_bf16 v[80:83], v[226:229], v[182:185], v[80:83]
	v_mfma_f32_16x16x32_bf16 v[68:71], v[218:221], v[206:209], v[68:71]
	v_mfma_f32_16x16x32_bf16 v[64:67], v[226:229], v[206:209], v[64:67]
	v_mfma_f32_16x16x32_bf16 v[116:119], v[222:225], v[170:173], v[116:119]
	v_mfma_f32_16x16x32_bf16 v[112:115], v[230:233], v[170:173], v[112:115]
	v_mfma_f32_16x16x32_bf16 v[100:103], v[222:225], v[178:181], v[100:103]
	v_mfma_f32_16x16x32_bf16 v[96:99], v[230:233], v[178:181], v[96:99]
	v_mfma_f32_16x16x32_bf16 v[84:87], v[222:225], v[186:189], v[84:87]
	v_mfma_f32_16x16x32_bf16 v[80:83], v[230:233], v[186:189], v[80:83]
	v_mfma_f32_16x16x32_bf16 v[68:71], v[222:225], v[214:217], v[68:71]
	v_mfma_f32_16x16x32_bf16 v[64:67], v[230:233], v[214:217], v[64:67]
	s_mov_b32 m0, s45
	v_lshl_add_u64 v[138:139], v[234:235], 0, s[50:51]
	s_barrier
	ds_read_b128 v[166:169], v136 offset:49152
	ds_read_b128 v[170:173], v136 offset:50176
	ds_read_b128 v[174:177], v136 offset:51200
	ds_read_b128 v[178:181], v136 offset:52224
	ds_read_b128 v[182:185], v136 offset:53248
	ds_read_b128 v[186:189], v136 offset:54272
	ds_read_b128 v[206:209], v136 offset:55296
	ds_read_b128 v[214:217], v136 offset:56320
	global_load_lds_dwordx4 v[138:139], off
	v_lshl_add_u64 v[138:139], v[236:237], 0, s[50:51]
	s_mov_b32 m0, s48
	s_nop 0
	global_load_lds_dwordx4 v[138:139], off
	s_barrier
	s_waitcnt lgkmcnt(0)
	v_mfma_f32_16x16x32_bf16 v[60:63], v[142:145], v[166:169], v[60:63]
	v_mfma_f32_16x16x32_bf16 v[56:59], v[150:153], v[166:169], v[56:59]
	v_mfma_f32_16x16x32_bf16 v[44:47], v[142:145], v[174:177], v[44:47]
	v_mfma_f32_16x16x32_bf16 v[40:43], v[150:153], v[174:177], v[40:43]
	v_mfma_f32_16x16x32_bf16 v[28:31], v[142:145], v[182:185], v[28:31]
	v_mfma_f32_16x16x32_bf16 v[24:27], v[150:153], v[182:185], v[24:27]
	v_mfma_f32_16x16x32_bf16 v[12:15], v[142:145], v[206:209], v[12:15]
	v_mfma_f32_16x16x32_bf16 v[8:11], v[150:153], v[206:209], v[8:11]
	v_mfma_f32_16x16x32_bf16 v[60:63], v[146:149], v[170:173], v[60:63]
	v_mfma_f32_16x16x32_bf16 v[56:59], v[162:165], v[170:173], v[56:59]
	v_mfma_f32_16x16x32_bf16 v[44:47], v[146:149], v[178:181], v[44:47]
	v_mfma_f32_16x16x32_bf16 v[40:43], v[162:165], v[178:181], v[40:43]
	v_mfma_f32_16x16x32_bf16 v[28:31], v[146:149], v[186:189], v[28:31]
	v_mfma_f32_16x16x32_bf16 v[24:27], v[162:165], v[186:189], v[24:27]
	v_mfma_f32_16x16x32_bf16 v[12:15], v[146:149], v[214:217], v[12:15]
	v_mfma_f32_16x16x32_bf16 v[8:11], v[162:165], v[214:217], v[8:11]
	s_barrier
	s_add_i32 s2, s2, s24
	v_lshl_add_u64 v[138:139], v[238:239], 0, s[50:51]
	s_mov_b32 m0, s2
	s_nop 0
	global_load_lds_dwordx4 v[138:139], off
	v_lshl_add_u64 v[138:139], v[240:241], 0, s[50:51]
	s_add_i32 m0, s2, 0x2000
	s_nop 0
	global_load_lds_dwordx4 v[138:139], off
	s_waitcnt vmcnt(6)
	s_barrier
	v_mfma_f32_16x16x32_bf16 v[52:55], v[218:221], v[166:169], v[52:55]
	v_mfma_f32_16x16x32_bf16 v[48:51], v[226:229], v[166:169], v[48:51]
	v_mfma_f32_16x16x32_bf16 v[36:39], v[218:221], v[174:177], v[36:39]
	v_mfma_f32_16x16x32_bf16 v[32:35], v[226:229], v[174:177], v[32:35]
	v_mfma_f32_16x16x32_bf16 v[20:23], v[218:221], v[182:185], v[20:23]
	v_mfma_f32_16x16x32_bf16 v[16:19], v[226:229], v[182:185], v[16:19]
	v_mfma_f32_16x16x32_bf16 v[4:7], v[218:221], v[206:209], v[4:7]
	v_mfma_f32_16x16x32_bf16 v[0:3], v[226:229], v[206:209], v[0:3]
	v_mfma_f32_16x16x32_bf16 v[52:55], v[222:225], v[170:173], v[52:55]
	v_mfma_f32_16x16x32_bf16 v[48:51], v[230:233], v[170:173], v[48:51]
	v_mfma_f32_16x16x32_bf16 v[36:39], v[222:225], v[178:181], v[36:39]
	v_mfma_f32_16x16x32_bf16 v[32:35], v[230:233], v[178:181], v[32:35]
	v_mfma_f32_16x16x32_bf16 v[20:23], v[222:225], v[186:189], v[20:23]
	v_mfma_f32_16x16x32_bf16 v[16:19], v[230:233], v[186:189], v[16:19]
	v_mfma_f32_16x16x32_bf16 v[4:7], v[222:225], v[214:217], v[4:7]
	v_mfma_f32_16x16x32_bf16 v[0:3], v[230:233], v[214:217], v[0:3]
	s_add_u32 s6, s6, 0x100
	s_addc_u32 s7, s7, 0
	s_cmp_ge_i32 s54, s49
	s_mov_b32 s2, s54
	s_barrier
	s_cbranch_scc0 .LBB0_272

.LBB0_285:
	v_bfe_u32 v14, v160, 4, 2
	v_and_b32_e32 v131, 15, v160
	v_lshlrev_b32_e32 v130, 4, v14
	v_lshlrev_b32_e32 v15, 2, v160
	v_lshl_or_b32 v14, v131, 6, v130
	s_lshl_b32 s21, s44, 13
	v_and_b32_e32 v15, 32, v15
	v_bitop3_b32 v16, v14, s21, v15 bitop3:0xde
	s_lshl_b32 s21, s45, 5
	s_lshl_b32 s35, s44, 6
	s_and_b32 s44, s21, 0x60
	s_add_i32 m0, s19, 0x18000
	v_lshl_add_u64 v[6:7], v[6:7], 0, s[50:51]
	s_lshl_b32 s21, s44, 7
	s_waitcnt vmcnt(4)
	s_barrier
	global_load_lds_dwordx4 v[6:7], off
	v_lshl_add_u64 v[4:5], v[4:5], 0, s[50:51]
	s_add_i32 m0, s19, 0x1a000
	s_add_i32 s45, s19, 0x8000
	s_add_i32 s53, s19, 0xa000
	global_load_lds_dwordx4 v[4:5], off
	v_lshl_add_u64 v[2:3], v[2:3], 0, s[50:51]
	s_mov_b32 m0, s45
	s_add_u32 s54, s42, 0x80080
	global_load_lds_dwordx4 v[2:3], off
	v_lshl_add_u64 v[0:1], v[0:1], 0, s[50:51]
	s_mov_b32 m0, s53
	s_addc_u32 s55, s43, 0
	global_load_lds_dwordx4 v[0:1], off
	s_add_i32 m0, s19, 0x1c000
	v_lshl_add_u64 v[0:1], s[54:55], 0, v[156:157]
	global_load_lds_dwordx4 v[0:1], off
	v_lshl_add_u64 v[0:1], s[54:55], 0, v[128:129]
	s_add_i32 m0, s19, 0x1e000
	s_add_u32 s2, s6, s2
	global_load_lds_dwordx4 v[0:1], off
	s_addc_u32 s3, s7, s3
	v_lshlrev_b32_e32 v0, 15, v11
	v_and_b32_e32 v0, 0xffff0000, v0
	s_add_u32 s2, s26, s2
	v_lshl_add_u32 v0, v12, 12, v0
	v_and_b32_e32 v1, 1, v11
	s_addc_u32 s3, s27, s3
	v_lshl_or_b32 v0, v1, 6, v0
	s_add_u32 s2, s2, 0x19524080
	v_lshl_add_u32 v0, v13, 1, v0
	v_mov_b32_e32 v1, v157
	s_addc_u32 s3, s3, 0
	v_lshl_add_u64 v[132:133], s[2:3], 0, v[0:1]
	v_lshlrev_b32_e32 v0, 15, v8
	v_and_b32_e32 v0, 0xffff0000, v0
	v_lshl_add_u32 v0, v9, 12, v0
	v_and_b32_e32 v1, 1, v8
	v_lshl_or_b32 v0, v1, 6, v0
	s_waitcnt vmcnt(6)
	v_lshl_add_u32 v0, v10, 1, v0
	v_mov_b32_e32 v1, v157
	v_lshl_add_u64 v[134:135], s[2:3], 0, v[0:1]
	v_bitop3_b32 v136, s21, v14, v15 bitop3:0xf6
	s_mov_b32 s54, -2
	s_mov_b64 s[6:7], 0
	v_add_u32_e32 v137, 0, v16
	s_barrier
	s_add_u32 s60, s6, 0x100
	s_addc_u32 s61, s7, 0
	s_cmp_lg_u32 s54, 28
	s_cselect_b32 s55, s60, 0
	s_cselect_b32 s21, s61, 0
	s_add_u32 s2, s48, s55
	s_addc_u32 s3, s49, s21
	s_add_i32 s66, 0, 0x10000
	v_add_u32_e32 v150, s66, v136
	ds_read_b128 v[138:141], v150
	ds_read_b128 v[142:145], v150 offset:1024
	ds_read_b128 v[146:149], v150 offset:2048
	ds_read_b128 v[150:153], v150 offset:3072
	s_add_u32 s62, s42, s55
	s_addc_u32 s63, s43, s21
	v_lshl_add_u64 v[154:155], v[134:135], 0, s[6:7]
	s_add_i32 m0, s19, 0xc000
	ds_read_b128 v[162:165], v137
	ds_read_b128 v[166:169], v137 offset:1024
	ds_read_b128 v[170:173], v137 offset:2048
	ds_read_b128 v[174:177], v137 offset:3072
	ds_read_b128 v[178:181], v137 offset:4096
	ds_read_b128 v[182:185], v137 offset:5120
	ds_read_b128 v[186:189], v137 offset:6144
	ds_read_b128 v[206:209], v137 offset:7168
	global_load_lds_dwordx4 v[154:155], off
	v_lshl_add_u64 v[154:155], v[132:133], 0, s[6:7]
	s_add_i32 m0, s19, 0xe000
	s_nop 0
	global_load_lds_dwordx4 v[154:155], off
	s_waitcnt lgkmcnt(8)
	s_barrier
	s_waitcnt lgkmcnt(0)
	v_mfma_f32_16x16x32_bf16 v[124:127], v[138:141], v[162:165], 0
	v_mfma_f32_16x16x32_bf16 v[120:123], v[146:149], v[162:165], 0
	v_mfma_f32_16x16x32_bf16 v[116:119], v[138:141], v[170:173], 0
	v_mfma_f32_16x16x32_bf16 v[112:115], v[146:149], v[170:173], 0
	v_mfma_f32_16x16x32_bf16 v[108:111], v[138:141], v[178:181], 0
	v_mfma_f32_16x16x32_bf16 v[100:103], v[146:149], v[178:181], 0
	v_mfma_f32_16x16x32_bf16 v[92:95], v[138:141], v[186:189], 0
	v_mfma_f32_16x16x32_bf16 v[84:87], v[146:149], v[186:189], 0
	v_mfma_f32_16x16x32_bf16 v[124:127], v[142:145], v[166:169], v[124:127]
	v_mfma_f32_16x16x32_bf16 v[120:123], v[150:153], v[166:169], v[120:123]
	v_mfma_f32_16x16x32_bf16 v[116:119], v[142:145], v[174:177], v[116:119]
	v_mfma_f32_16x16x32_bf16 v[112:115], v[150:153], v[174:177], v[112:115]
	v_mfma_f32_16x16x32_bf16 v[108:111], v[142:145], v[182:185], v[108:111]
	v_mfma_f32_16x16x32_bf16 v[100:103], v[150:153], v[182:185], v[100:103]
	v_mfma_f32_16x16x32_bf16 v[92:95], v[142:145], v[206:209], v[92:95]
	v_mfma_f32_16x16x32_bf16 v[84:87], v[150:153], v[206:209], v[84:87]
	s_barrier
	s_add_i32 s21, 0, 0x14000
	v_add_u32_e32 v154, s21, v136
	s_add_i32 s6, s66, s10
	ds_read_b128 v[214:217], v154
	ds_read_b128 v[218:221], v154 offset:1024
	ds_read_b128 v[222:225], v154 offset:2048
	ds_read_b128 v[226:229], v154 offset:3072
	v_lshl_add_u64 v[154:155], s[62:63], 0, v[156:157]
	s_mov_b32 m0, s6
	v_lshl_add_u64 v[230:231], s[62:63], 0, v[128:129]
	global_load_lds_dwordx4 v[154:155], off
	s_add_i32 m0, s6, 0x2000
	s_nop 0
	global_load_lds_dwordx4 v[230:231], off
	s_barrier
	s_waitcnt lgkmcnt(0)
	v_mfma_f32_16x16x32_bf16 v[104:107], v[214:217], v[162:165], 0
	v_mfma_f32_16x16x32_bf16 v[96:99], v[222:225], v[162:165], 0
	v_mfma_f32_16x16x32_bf16 v[88:91], v[214:217], v[170:173], 0
	v_mfma_f32_16x16x32_bf16 v[80:83], v[222:225], v[170:173], 0
	v_mfma_f32_16x16x32_bf16 v[76:79], v[214:217], v[178:181], 0
	v_mfma_f32_16x16x32_bf16 v[72:75], v[222:225], v[178:181], 0
	v_mfma_f32_16x16x32_bf16 v[68:71], v[214:217], v[186:189], 0
	v_mfma_f32_16x16x32_bf16 v[64:67], v[222:225], v[186:189], 0
	v_mfma_f32_16x16x32_bf16 v[104:107], v[218:221], v[166:169], v[104:107]
	v_mfma_f32_16x16x32_bf16 v[96:99], v[226:229], v[166:169], v[96:99]
	v_mfma_f32_16x16x32_bf16 v[88:91], v[218:221], v[174:177], v[88:91]
	v_mfma_f32_16x16x32_bf16 v[80:83], v[226:229], v[174:177], v[80:83]
	v_mfma_f32_16x16x32_bf16 v[76:79], v[218:221], v[182:185], v[76:79]
	v_mfma_f32_16x16x32_bf16 v[72:75], v[226:229], v[182:185], v[72:75]
	v_mfma_f32_16x16x32_bf16 v[68:71], v[218:221], v[206:209], v[68:71]
	v_mfma_f32_16x16x32_bf16 v[64:67], v[226:229], v[206:209], v[64:67]
	s_mov_b32 m0, s19
	v_lshl_add_u64 v[232:233], s[2:3], 0, v[156:157]
	s_barrier
	ds_read_b128 v[162:165], v137 offset:16384
	ds_read_b128 v[166:169], v137 offset:17408
	ds_read_b128 v[170:173], v137 offset:18432
	ds_read_b128 v[174:177], v137 offset:19456
	ds_read_b128 v[178:181], v137 offset:20480
	ds_read_b128 v[182:185], v137 offset:21504
	ds_read_b128 v[186:189], v137 offset:22528
	ds_read_b128 v[206:209], v137 offset:23552
	global_load_lds_dwordx4 v[232:233], off
	v_lshl_add_u64 v[234:235], s[2:3], 0, v[128:129]
	s_mov_b32 m0, s24
	s_nop 0
	global_load_lds_dwordx4 v[234:235], off
	s_barrier
	s_waitcnt lgkmcnt(0)
	v_mfma_f32_16x16x32_bf16 v[60:63], v[138:141], v[162:165], 0
	v_mfma_f32_16x16x32_bf16 v[56:59], v[146:149], v[162:165], 0
	v_mfma_f32_16x16x32_bf16 v[52:55], v[138:141], v[170:173], 0
	v_mfma_f32_16x16x32_bf16 v[48:51], v[146:149], v[170:173], 0
	v_mfma_f32_16x16x32_bf16 v[40:43], v[138:141], v[178:181], 0
	v_mfma_f32_16x16x32_bf16 v[32:35], v[146:149], v[178:181], 0
	v_mfma_f32_16x16x32_bf16 v[24:27], v[138:141], v[186:189], 0
	v_mfma_f32_16x16x32_bf16 v[16:19], v[146:149], v[186:189], 0
	v_mfma_f32_16x16x32_bf16 v[60:63], v[142:145], v[166:169], v[60:63]
	v_mfma_f32_16x16x32_bf16 v[56:59], v[150:153], v[166:169], v[56:59]
	v_mfma_f32_16x16x32_bf16 v[52:55], v[142:145], v[174:177], v[52:55]
	v_mfma_f32_16x16x32_bf16 v[48:51], v[150:153], v[174:177], v[48:51]
	v_mfma_f32_16x16x32_bf16 v[40:43], v[142:145], v[182:185], v[40:43]
	v_mfma_f32_16x16x32_bf16 v[32:35], v[150:153], v[182:185], v[32:35]
	v_mfma_f32_16x16x32_bf16 v[24:27], v[142:145], v[206:209], v[24:27]
	v_mfma_f32_16x16x32_bf16 v[16:19], v[150:153], v[206:209], v[16:19]
	s_barrier
	s_add_u32 s6, s62, 0x80000
	s_addc_u32 s7, s63, 0
	s_add_i32 s21, s21, s10
	v_lshl_add_u64 v[138:139], s[6:7], 0, v[156:157]
	s_mov_b32 m0, s21
	s_nop 0
	global_load_lds_dwordx4 v[138:139], off
	v_lshl_add_u64 v[138:139], s[6:7], 0, v[128:129]
	s_add_i32 m0, s21, 0x2000
	s_nop 0
	global_load_lds_dwordx4 v[138:139], off
	s_waitcnt vmcnt(6)
	s_barrier
	v_mfma_f32_16x16x32_bf16 v[44:47], v[214:217], v[162:165], 0
	v_mfma_f32_16x16x32_bf16 v[36:39], v[222:225], v[162:165], 0
	v_mfma_f32_16x16x32_bf16 v[28:31], v[214:217], v[170:173], 0
	v_mfma_f32_16x16x32_bf16 v[20:23], v[222:225], v[170:173], 0
	v_mfma_f32_16x16x32_bf16 v[12:15], v[214:217], v[178:181], 0
	v_mfma_f32_16x16x32_bf16 v[8:11], v[222:225], v[178:181], 0
	v_mfma_f32_16x16x32_bf16 v[4:7], v[214:217], v[186:189], 0
	v_mfma_f32_16x16x32_bf16 v[0:3], v[222:225], v[186:189], 0
	v_mfma_f32_16x16x32_bf16 v[44:47], v[218:221], v[166:169], v[44:47]
	v_mfma_f32_16x16x32_bf16 v[36:39], v[226:229], v[166:169], v[36:39]
	v_mfma_f32_16x16x32_bf16 v[28:31], v[218:221], v[174:177], v[28:31]
	v_mfma_f32_16x16x32_bf16 v[20:23], v[226:229], v[174:177], v[20:23]
	v_mfma_f32_16x16x32_bf16 v[12:15], v[218:221], v[182:185], v[12:15]
	v_mfma_f32_16x16x32_bf16 v[8:11], v[226:229], v[182:185], v[8:11]
	v_mfma_f32_16x16x32_bf16 v[4:7], v[218:221], v[206:209], v[4:7]
	v_mfma_f32_16x16x32_bf16 v[0:3], v[226:229], v[206:209], v[0:3]
	s_add_i32 s6, 0, 0x18000
	v_add_u32_e32 v150, s6, v136
	s_barrier
	ds_read_b128 v[138:141], v150
	ds_read_b128 v[142:145], v150 offset:1024
	ds_read_b128 v[146:149], v150 offset:2048
	ds_read_b128 v[150:153], v150 offset:3072
	s_add_u32 s2, s2, 0x80000
	s_addc_u32 s3, s3, 0
	s_mov_b32 m0, s25
	v_lshl_add_u64 v[214:215], s[2:3], 0, v[156:157]
	ds_read_b128 v[162:165], v137 offset:32768
	ds_read_b128 v[166:169], v137 offset:33792
	ds_read_b128 v[170:173], v137 offset:34816
	ds_read_b128 v[174:177], v137 offset:35840
	ds_read_b128 v[178:181], v137 offset:36864
	ds_read_b128 v[182:185], v137 offset:37888
	ds_read_b128 v[186:189], v137 offset:38912
	ds_read_b128 v[206:209], v137 offset:39936
	global_load_lds_dwordx4 v[214:215], off
	v_lshl_add_u64 v[214:215], s[2:3], 0, v[128:129]
	s_mov_b32 m0, s34
	s_nop 0
	global_load_lds_dwordx4 v[214:215], off
	s_waitcnt lgkmcnt(8)
	s_barrier
	s_waitcnt lgkmcnt(0)
	v_mfma_f32_16x16x32_bf16 v[124:127], v[138:141], v[162:165], v[124:127]
	v_mfma_f32_16x16x32_bf16 v[120:123], v[146:149], v[162:165], v[120:123]
	v_mfma_f32_16x16x32_bf16 v[116:119], v[138:141], v[170:173], v[116:119]
	v_mfma_f32_16x16x32_bf16 v[112:115], v[146:149], v[170:173], v[112:115]
	v_mfma_f32_16x16x32_bf16 v[108:111], v[138:141], v[178:181], v[108:111]
	v_mfma_f32_16x16x32_bf16 v[100:103], v[146:149], v[178:181], v[100:103]
	v_mfma_f32_16x16x32_bf16 v[92:95], v[138:141], v[186:189], v[92:95]
	v_mfma_f32_16x16x32_bf16 v[84:87], v[146:149], v[186:189], v[84:87]
	v_mfma_f32_16x16x32_bf16 v[124:127], v[142:145], v[166:169], v[124:127]
	v_mfma_f32_16x16x32_bf16 v[120:123], v[150:153], v[166:169], v[120:123]
	v_mfma_f32_16x16x32_bf16 v[116:119], v[142:145], v[174:177], v[116:119]
	v_mfma_f32_16x16x32_bf16 v[112:115], v[150:153], v[174:177], v[112:115]
	v_mfma_f32_16x16x32_bf16 v[108:111], v[142:145], v[182:185], v[108:111]
	v_mfma_f32_16x16x32_bf16 v[100:103], v[150:153], v[182:185], v[100:103]
	v_mfma_f32_16x16x32_bf16 v[92:95], v[142:145], v[206:209], v[92:95]
	v_mfma_f32_16x16x32_bf16 v[84:87], v[150:153], v[206:209], v[84:87]
	s_barrier
	s_add_i32 s7, 0, 0x1c000
	s_add_i32 s2, s6, s10
	v_add_u32_e32 v161, s7, v136
	v_lshl_add_u64 v[154:155], v[154:155], 0, s[50:51]
	s_mov_b32 m0, s2
	ds_read_b128 v[214:217], v161
	ds_read_b128 v[218:221], v161 offset:1024
	ds_read_b128 v[222:225], v161 offset:2048
	ds_read_b128 v[226:229], v161 offset:3072
	global_load_lds_dwordx4 v[154:155], off
	v_lshl_add_u64 v[154:155], v[230:231], 0, s[50:51]
	s_add_i32 m0, s2, 0x2000
	s_nop 0
	global_load_lds_dwordx4 v[154:155], off
	s_barrier
	s_waitcnt lgkmcnt(0)
	v_mfma_f32_16x16x32_bf16 v[104:107], v[214:217], v[162:165], v[104:107]
	v_mfma_f32_16x16x32_bf16 v[96:99], v[222:225], v[162:165], v[96:99]
	v_mfma_f32_16x16x32_bf16 v[88:91], v[214:217], v[170:173], v[88:91]
	v_mfma_f32_16x16x32_bf16 v[80:83], v[222:225], v[170:173], v[80:83]
	v_mfma_f32_16x16x32_bf16 v[76:79], v[214:217], v[178:181], v[76:79]
	v_mfma_f32_16x16x32_bf16 v[72:75], v[222:225], v[178:181], v[72:75]
	v_mfma_f32_16x16x32_bf16 v[68:71], v[214:217], v[186:189], v[68:71]
	v_mfma_f32_16x16x32_bf16 v[64:67], v[222:225], v[186:189], v[64:67]
	v_mfma_f32_16x16x32_bf16 v[104:107], v[218:221], v[166:169], v[104:107]
	v_mfma_f32_16x16x32_bf16 v[96:99], v[226:229], v[166:169], v[96:99]
	v_mfma_f32_16x16x32_bf16 v[88:91], v[218:221], v[174:177], v[88:91]
	v_mfma_f32_16x16x32_bf16 v[80:83], v[226:229], v[174:177], v[80:83]
	v_mfma_f32_16x16x32_bf16 v[76:79], v[218:221], v[182:185], v[76:79]
	v_mfma_f32_16x16x32_bf16 v[72:75], v[226:229], v[182:185], v[72:75]
	v_mfma_f32_16x16x32_bf16 v[68:71], v[218:221], v[206:209], v[68:71]
	v_mfma_f32_16x16x32_bf16 v[64:67], v[226:229], v[206:209], v[64:67]
	s_mov_b32 m0, s45
	v_lshl_add_u64 v[154:155], v[232:233], 0, s[50:51]
	s_barrier
	ds_read_b128 v[162:165], v137 offset:49152
	ds_read_b128 v[166:169], v137 offset:50176
	ds_read_b128 v[170:173], v137 offset:51200
	ds_read_b128 v[174:177], v137 offset:52224
	ds_read_b128 v[178:181], v137 offset:53248
	ds_read_b128 v[182:185], v137 offset:54272
	ds_read_b128 v[186:189], v137 offset:55296
	ds_read_b128 v[206:209], v137 offset:56320
	global_load_lds_dwordx4 v[154:155], off
	v_lshl_add_u64 v[154:155], v[234:235], 0, s[50:51]
	s_mov_b32 m0, s53
	s_nop 0
	global_load_lds_dwordx4 v[154:155], off
	s_barrier
	s_waitcnt lgkmcnt(0)
	v_mfma_f32_16x16x32_bf16 v[60:63], v[138:141], v[162:165], v[60:63]
	v_mfma_f32_16x16x32_bf16 v[56:59], v[146:149], v[162:165], v[56:59]
	v_mfma_f32_16x16x32_bf16 v[52:55], v[138:141], v[170:173], v[52:55]
	v_mfma_f32_16x16x32_bf16 v[48:51], v[146:149], v[170:173], v[48:51]
	v_mfma_f32_16x16x32_bf16 v[40:43], v[138:141], v[178:181], v[40:43]
	v_mfma_f32_16x16x32_bf16 v[32:35], v[146:149], v[178:181], v[32:35]
	v_mfma_f32_16x16x32_bf16 v[24:27], v[138:141], v[186:189], v[24:27]
	v_mfma_f32_16x16x32_bf16 v[16:19], v[146:149], v[186:189], v[16:19]
	v_mfma_f32_16x16x32_bf16 v[60:63], v[142:145], v[166:169], v[60:63]
	v_mfma_f32_16x16x32_bf16 v[56:59], v[150:153], v[166:169], v[56:59]
	v_mfma_f32_16x16x32_bf16 v[52:55], v[142:145], v[174:177], v[52:55]
	v_mfma_f32_16x16x32_bf16 v[48:51], v[150:153], v[174:177], v[48:51]
	v_mfma_f32_16x16x32_bf16 v[40:43], v[142:145], v[182:185], v[40:43]
	v_mfma_f32_16x16x32_bf16 v[32:35], v[150:153], v[182:185], v[32:35]
	v_mfma_f32_16x16x32_bf16 v[24:27], v[142:145], v[206:209], v[24:27]
	v_mfma_f32_16x16x32_bf16 v[16:19], v[150:153], v[206:209], v[16:19]
	s_barrier
	s_add_u32 s2, s62, 0x80080
	s_addc_u32 s3, s63, 0
	s_add_i32 s6, s7, s10
	v_lshl_add_u64 v[138:139], s[2:3], 0, v[156:157]
	s_mov_b32 m0, s6
	s_nop 0
	global_load_lds_dwordx4 v[138:139], off
	v_lshl_add_u64 v[138:139], s[2:3], 0, v[128:129]
	s_add_i32 m0, s6, 0x2000
	s_nop 0
	global_load_lds_dwordx4 v[138:139], off
	s_waitcnt vmcnt(6)
	s_barrier
	v_mfma_f32_16x16x32_bf16 v[44:47], v[214:217], v[162:165], v[44:47]
	v_mfma_f32_16x16x32_bf16 v[36:39], v[222:225], v[162:165], v[36:39]
	v_mfma_f32_16x16x32_bf16 v[28:31], v[214:217], v[170:173], v[28:31]
	v_mfma_f32_16x16x32_bf16 v[20:23], v[222:225], v[170:173], v[20:23]
	v_mfma_f32_16x16x32_bf16 v[12:15], v[214:217], v[178:181], v[12:15]
	v_mfma_f32_16x16x32_bf16 v[8:11], v[222:225], v[178:181], v[8:11]
	v_mfma_f32_16x16x32_bf16 v[4:7], v[214:217], v[186:189], v[4:7]
	v_mfma_f32_16x16x32_bf16 v[0:3], v[222:225], v[186:189], v[0:3]
	v_mfma_f32_16x16x32_bf16 v[44:47], v[218:221], v[166:169], v[44:47]
	v_mfma_f32_16x16x32_bf16 v[36:39], v[226:229], v[166:169], v[36:39]
	v_mfma_f32_16x16x32_bf16 v[28:31], v[218:221], v[174:177], v[28:31]
	v_mfma_f32_16x16x32_bf16 v[20:23], v[226:229], v[174:177], v[20:23]
	v_mfma_f32_16x16x32_bf16 v[12:15], v[218:221], v[182:185], v[12:15]
	v_mfma_f32_16x16x32_bf16 v[8:11], v[226:229], v[182:185], v[8:11]
	v_mfma_f32_16x16x32_bf16 v[4:7], v[218:221], v[206:209], v[4:7]
	v_mfma_f32_16x16x32_bf16 v[0:3], v[226:229], v[206:209], v[0:3]
	s_add_i32 s54, s54, 2
	s_cmp_gt_u32 s54, 29
	s_mov_b64 s[6:7], s[60:61]
	s_barrier
	s_cbranch_scc1 .Lpost_286
.LBB0_286:
	s_add_u32 s60, s6, 0x100
	s_addc_u32 s61, s7, 0
	s_cmp_lg_u32 s54, 28
	s_cselect_b32 s55, s60, 0
	s_cselect_b32 s21, s61, 0
	s_add_u32 s2, s48, s55
	s_addc_u32 s3, s49, s21
	s_add_i32 s66, 0, 0x10000
	v_add_u32_e32 v150, s66, v136
	ds_read_b128 v[138:141], v150
	ds_read_b128 v[142:145], v150 offset:1024
	ds_read_b128 v[146:149], v150 offset:2048
	ds_read_b128 v[150:153], v150 offset:3072
	s_add_u32 s62, s42, s55
	s_addc_u32 s63, s43, s21
	v_lshl_add_u64 v[154:155], v[134:135], 0, s[6:7]
	s_add_i32 m0, s19, 0xc000
	ds_read_b128 v[162:165], v137
	ds_read_b128 v[166:169], v137 offset:1024
	ds_read_b128 v[170:173], v137 offset:2048
	ds_read_b128 v[174:177], v137 offset:3072
	ds_read_b128 v[178:181], v137 offset:4096
	ds_read_b128 v[182:185], v137 offset:5120
	ds_read_b128 v[186:189], v137 offset:6144
	ds_read_b128 v[206:209], v137 offset:7168
	global_load_lds_dwordx4 v[154:155], off
	v_lshl_add_u64 v[154:155], v[132:133], 0, s[6:7]
	s_add_i32 m0, s19, 0xe000
	s_nop 0
	global_load_lds_dwordx4 v[154:155], off
	s_waitcnt lgkmcnt(8)
	s_barrier
	s_waitcnt lgkmcnt(0)
	v_mfma_f32_16x16x32_bf16 v[124:127], v[138:141], v[162:165], v[124:127]
	v_mfma_f32_16x16x32_bf16 v[120:123], v[146:149], v[162:165], v[120:123]
	v_mfma_f32_16x16x32_bf16 v[116:119], v[138:141], v[170:173], v[116:119]
	v_mfma_f32_16x16x32_bf16 v[112:115], v[146:149], v[170:173], v[112:115]
	v_mfma_f32_16x16x32_bf16 v[108:111], v[138:141], v[178:181], v[108:111]
	v_mfma_f32_16x16x32_bf16 v[100:103], v[146:149], v[178:181], v[100:103]
	v_mfma_f32_16x16x32_bf16 v[92:95], v[138:141], v[186:189], v[92:95]
	v_mfma_f32_16x16x32_bf16 v[84:87], v[146:149], v[186:189], v[84:87]
	v_mfma_f32_16x16x32_bf16 v[124:127], v[142:145], v[166:169], v[124:127]
	v_mfma_f32_16x16x32_bf16 v[120:123], v[150:153], v[166:169], v[120:123]
	v_mfma_f32_16x16x32_bf16 v[116:119], v[142:145], v[174:177], v[116:119]
	v_mfma_f32_16x16x32_bf16 v[112:115], v[150:153], v[174:177], v[112:115]
	v_mfma_f32_16x16x32_bf16 v[108:111], v[142:145], v[182:185], v[108:111]
	v_mfma_f32_16x16x32_bf16 v[100:103], v[150:153], v[182:185], v[100:103]
	v_mfma_f32_16x16x32_bf16 v[92:95], v[142:145], v[206:209], v[92:95]
	v_mfma_f32_16x16x32_bf16 v[84:87], v[150:153], v[206:209], v[84:87]
	s_barrier
	s_add_i32 s21, 0, 0x14000
	v_add_u32_e32 v154, s21, v136
	s_add_i32 s6, s66, s10
	ds_read_b128 v[214:217], v154
	ds_read_b128 v[218:221], v154 offset:1024
	ds_read_b128 v[222:225], v154 offset:2048
	ds_read_b128 v[226:229], v154 offset:3072
	v_lshl_add_u64 v[154:155], s[62:63], 0, v[156:157]
	s_mov_b32 m0, s6
	v_lshl_add_u64 v[230:231], s[62:63], 0, v[128:129]
	global_load_lds_dwordx4 v[154:155], off
	s_add_i32 m0, s6, 0x2000
	s_nop 0
	global_load_lds_dwordx4 v[230:231], off
	s_barrier
	s_waitcnt lgkmcnt(0)
	v_mfma_f32_16x16x32_bf16 v[104:107], v[214:217], v[162:165], v[104:107]
	v_mfma_f32_16x16x32_bf16 v[96:99], v[222:225], v[162:165], v[96:99]
	v_mfma_f32_16x16x32_bf16 v[88:91], v[214:217], v[170:173], v[88:91]
	v_mfma_f32_16x16x32_bf16 v[80:83], v[222:225], v[170:173], v[80:83]
	v_mfma_f32_16x16x32_bf16 v[76:79], v[214:217], v[178:181], v[76:79]
	v_mfma_f32_16x16x32_bf16 v[72:75], v[222:225], v[178:181], v[72:75]
	v_mfma_f32_16x16x32_bf16 v[68:71], v[214:217], v[186:189], v[68:71]
	v_mfma_f32_16x16x32_bf16 v[64:67], v[222:225], v[186:189], v[64:67]
	v_mfma_f32_16x16x32_bf16 v[104:107], v[218:221], v[166:169], v[104:107]
	v_mfma_f32_16x16x32_bf16 v[96:99], v[226:229], v[166:169], v[96:99]
	v_mfma_f32_16x16x32_bf16 v[88:91], v[218:221], v[174:177], v[88:91]
	v_mfma_f32_16x16x32_bf16 v[80:83], v[226:229], v[174:177], v[80:83]
	v_mfma_f32_16x16x32_bf16 v[76:79], v[218:221], v[182:185], v[76:79]
	v_mfma_f32_16x16x32_bf16 v[72:75], v[226:229], v[182:185], v[72:75]
	v_mfma_f32_16x16x32_bf16 v[68:71], v[218:221], v[206:209], v[68:71]
	v_mfma_f32_16x16x32_bf16 v[64:67], v[226:229], v[206:209], v[64:67]
	s_mov_b32 m0, s19
	v_lshl_add_u64 v[232:233], s[2:3], 0, v[156:157]
	s_barrier
	ds_read_b128 v[162:165], v137 offset:16384
	ds_read_b128 v[166:169], v137 offset:17408
	ds_read_b128 v[170:173], v137 offset:18432
	ds_read_b128 v[174:177], v137 offset:19456
	ds_read_b128 v[178:181], v137 offset:20480
	ds_read_b128 v[182:185], v137 offset:21504
	ds_read_b128 v[186:189], v137 offset:22528
	ds_read_b128 v[206:209], v137 offset:23552
	global_load_lds_dwordx4 v[232:233], off
	v_lshl_add_u64 v[234:235], s[2:3], 0, v[128:129]
	s_mov_b32 m0, s24
	s_nop 0
	global_load_lds_dwordx4 v[234:235], off
	s_barrier
	s_waitcnt lgkmcnt(0)
	v_mfma_f32_16x16x32_bf16 v[60:63], v[138:141], v[162:165], v[60:63]
	v_mfma_f32_16x16x32_bf16 v[56:59], v[146:149], v[162:165], v[56:59]
	v_mfma_f32_16x16x32_bf16 v[52:55], v[138:141], v[170:173], v[52:55]
	v_mfma_f32_16x16x32_bf16 v[48:51], v[146:149], v[170:173], v[48:51]
	v_mfma_f32_16x16x32_bf16 v[40:43], v[138:141], v[178:181], v[40:43]
	v_mfma_f32_16x16x32_bf16 v[32:35], v[146:149], v[178:181], v[32:35]
	v_mfma_f32_16x16x32_bf16 v[24:27], v[138:141], v[186:189], v[24:27]
	v_mfma_f32_16x16x32_bf16 v[16:19], v[146:149], v[186:189], v[16:19]
	v_mfma_f32_16x16x32_bf16 v[60:63], v[142:145], v[166:169], v[60:63]
	v_mfma_f32_16x16x32_bf16 v[56:59], v[150:153], v[166:169], v[56:59]
	v_mfma_f32_16x16x32_bf16 v[52:55], v[142:145], v[174:177], v[52:55]
	v_mfma_f32_16x16x32_bf16 v[48:51], v[150:153], v[174:177], v[48:51]
	v_mfma_f32_16x16x32_bf16 v[40:43], v[142:145], v[182:185], v[40:43]
	v_mfma_f32_16x16x32_bf16 v[32:35], v[150:153], v[182:185], v[32:35]
	v_mfma_f32_16x16x32_bf16 v[24:27], v[142:145], v[206:209], v[24:27]
	v_mfma_f32_16x16x32_bf16 v[16:19], v[150:153], v[206:209], v[16:19]
	s_barrier
	s_add_u32 s6, s62, 0x80000
	s_addc_u32 s7, s63, 0
	s_add_i32 s21, s21, s10
	v_lshl_add_u64 v[138:139], s[6:7], 0, v[156:157]
	s_mov_b32 m0, s21
	s_nop 0
	global_load_lds_dwordx4 v[138:139], off
	v_lshl_add_u64 v[138:139], s[6:7], 0, v[128:129]
	s_add_i32 m0, s21, 0x2000
	s_nop 0
	global_load_lds_dwordx4 v[138:139], off
	s_waitcnt vmcnt(6)
	s_barrier
	v_mfma_f32_16x16x32_bf16 v[44:47], v[214:217], v[162:165], v[44:47]
	v_mfma_f32_16x16x32_bf16 v[36:39], v[222:225], v[162:165], v[36:39]
	v_mfma_f32_16x16x32_bf16 v[28:31], v[214:217], v[170:173], v[28:31]
	v_mfma_f32_16x16x32_bf16 v[20:23], v[222:225], v[170:173], v[20:23]
	v_mfma_f32_16x16x32_bf16 v[12:15], v[214:217], v[178:181], v[12:15]
	v_mfma_f32_16x16x32_bf16 v[8:11], v[222:225], v[178:181], v[8:11]
	v_mfma_f32_16x16x32_bf16 v[4:7], v[214:217], v[186:189], v[4:7]
	v_mfma_f32_16x16x32_bf16 v[0:3], v[222:225], v[186:189], v[0:3]
	v_mfma_f32_16x16x32_bf16 v[44:47], v[218:221], v[166:169], v[44:47]
	v_mfma_f32_16x16x32_bf16 v[36:39], v[226:229], v[166:169], v[36:39]
	v_mfma_f32_16x16x32_bf16 v[28:31], v[218:221], v[174:177], v[28:31]
	v_mfma_f32_16x16x32_bf16 v[20:23], v[226:229], v[174:177], v[20:23]
	v_mfma_f32_16x16x32_bf16 v[12:15], v[218:221], v[182:185], v[12:15]
	v_mfma_f32_16x16x32_bf16 v[8:11], v[226:229], v[182:185], v[8:11]
	v_mfma_f32_16x16x32_bf16 v[4:7], v[218:221], v[206:209], v[4:7]
	v_mfma_f32_16x16x32_bf16 v[0:3], v[226:229], v[206:209], v[0:3]
	s_add_i32 s6, 0, 0x18000
	v_add_u32_e32 v150, s6, v136
	s_barrier
	ds_read_b128 v[138:141], v150
	ds_read_b128 v[142:145], v150 offset:1024
	ds_read_b128 v[146:149], v150 offset:2048
	ds_read_b128 v[150:153], v150 offset:3072
	s_add_u32 s2, s2, 0x80000
	s_addc_u32 s3, s3, 0
	s_mov_b32 m0, s25
	v_lshl_add_u64 v[214:215], s[2:3], 0, v[156:157]
	ds_read_b128 v[162:165], v137 offset:32768
	ds_read_b128 v[166:169], v137 offset:33792
	ds_read_b128 v[170:173], v137 offset:34816
	ds_read_b128 v[174:177], v137 offset:35840
	ds_read_b128 v[178:181], v137 offset:36864
	ds_read_b128 v[182:185], v137 offset:37888
	ds_read_b128 v[186:189], v137 offset:38912
	ds_read_b128 v[206:209], v137 offset:39936
	global_load_lds_dwordx4 v[214:215], off
	v_lshl_add_u64 v[214:215], s[2:3], 0, v[128:129]
	s_mov_b32 m0, s34
	s_nop 0
	global_load_lds_dwordx4 v[214:215], off
	s_waitcnt lgkmcnt(8)
	s_barrier
	s_waitcnt lgkmcnt(0)
	v_mfma_f32_16x16x32_bf16 v[124:127], v[138:141], v[162:165], v[124:127]
	v_mfma_f32_16x16x32_bf16 v[120:123], v[146:149], v[162:165], v[120:123]
	v_mfma_f32_16x16x32_bf16 v[116:119], v[138:141], v[170:173], v[116:119]
	v_mfma_f32_16x16x32_bf16 v[112:115], v[146:149], v[170:173], v[112:115]
	v_mfma_f32_16x16x32_bf16 v[108:111], v[138:141], v[178:181], v[108:111]
	v_mfma_f32_16x16x32_bf16 v[100:103], v[146:149], v[178:181], v[100:103]
	v_mfma_f32_16x16x32_bf16 v[92:95], v[138:141], v[186:189], v[92:95]
	v_mfma_f32_16x16x32_bf16 v[84:87], v[146:149], v[186:189], v[84:87]
	v_mfma_f32_16x16x32_bf16 v[124:127], v[142:145], v[166:169], v[124:127]
	v_mfma_f32_16x16x32_bf16 v[120:123], v[150:153], v[166:169], v[120:123]
	v_mfma_f32_16x16x32_bf16 v[116:119], v[142:145], v[174:177], v[116:119]
	v_mfma_f32_16x16x32_bf16 v[112:115], v[150:153], v[174:177], v[112:115]
	v_mfma_f32_16x16x32_bf16 v[108:111], v[142:145], v[182:185], v[108:111]
	v_mfma_f32_16x16x32_bf16 v[100:103], v[150:153], v[182:185], v[100:103]
	v_mfma_f32_16x16x32_bf16 v[92:95], v[142:145], v[206:209], v[92:95]
	v_mfma_f32_16x16x32_bf16 v[84:87], v[150:153], v[206:209], v[84:87]
	s_barrier
	s_add_i32 s7, 0, 0x1c000
	s_add_i32 s2, s6, s10
	v_add_u32_e32 v161, s7, v136
	v_lshl_add_u64 v[154:155], v[154:155], 0, s[50:51]
	s_mov_b32 m0, s2
	ds_read_b128 v[214:217], v161
	ds_read_b128 v[218:221], v161 offset:1024
	ds_read_b128 v[222:225], v161 offset:2048
	ds_read_b128 v[226:229], v161 offset:3072
	global_load_lds_dwordx4 v[154:155], off
	v_lshl_add_u64 v[154:155], v[230:231], 0, s[50:51]
	s_add_i32 m0, s2, 0x2000
	s_nop 0
	global_load_lds_dwordx4 v[154:155], off
	s_barrier
	s_waitcnt lgkmcnt(0)
	v_mfma_f32_16x16x32_bf16 v[104:107], v[214:217], v[162:165], v[104:107]
	v_mfma_f32_16x16x32_bf16 v[96:99], v[222:225], v[162:165], v[96:99]
	v_mfma_f32_16x16x32_bf16 v[88:91], v[214:217], v[170:173], v[88:91]
	v_mfma_f32_16x16x32_bf16 v[80:83], v[222:225], v[170:173], v[80:83]
	v_mfma_f32_16x16x32_bf16 v[76:79], v[214:217], v[178:181], v[76:79]
	v_mfma_f32_16x16x32_bf16 v[72:75], v[222:225], v[178:181], v[72:75]
	v_mfma_f32_16x16x32_bf16 v[68:71], v[214:217], v[186:189], v[68:71]
	v_mfma_f32_16x16x32_bf16 v[64:67], v[222:225], v[186:189], v[64:67]
	v_mfma_f32_16x16x32_bf16 v[104:107], v[218:221], v[166:169], v[104:107]
	v_mfma_f32_16x16x32_bf16 v[96:99], v[226:229], v[166:169], v[96:99]
	v_mfma_f32_16x16x32_bf16 v[88:91], v[218:221], v[174:177], v[88:91]
	v_mfma_f32_16x16x32_bf16 v[80:83], v[226:229], v[174:177], v[80:83]
	v_mfma_f32_16x16x32_bf16 v[76:79], v[218:221], v[182:185], v[76:79]
	v_mfma_f32_16x16x32_bf16 v[72:75], v[226:229], v[182:185], v[72:75]
	v_mfma_f32_16x16x32_bf16 v[68:71], v[218:221], v[206:209], v[68:71]
	v_mfma_f32_16x16x32_bf16 v[64:67], v[226:229], v[206:209], v[64:67]
	s_mov_b32 m0, s45
	v_lshl_add_u64 v[154:155], v[232:233], 0, s[50:51]
	s_barrier
	ds_read_b128 v[162:165], v137 offset:49152
	ds_read_b128 v[166:169], v137 offset:50176
	ds_read_b128 v[170:173], v137 offset:51200
	ds_read_b128 v[174:177], v137 offset:52224
	ds_read_b128 v[178:181], v137 offset:53248
	ds_read_b128 v[182:185], v137 offset:54272
	ds_read_b128 v[186:189], v137 offset:55296
	ds_read_b128 v[206:209], v137 offset:56320
	global_load_lds_dwordx4 v[154:155], off
	v_lshl_add_u64 v[154:155], v[234:235], 0, s[50:51]
	s_mov_b32 m0, s53
	s_nop 0
	global_load_lds_dwordx4 v[154:155], off
	s_barrier
	s_waitcnt lgkmcnt(0)
	v_mfma_f32_16x16x32_bf16 v[60:63], v[138:141], v[162:165], v[60:63]
	v_mfma_f32_16x16x32_bf16 v[56:59], v[146:149], v[162:165], v[56:59]
	v_mfma_f32_16x16x32_bf16 v[52:55], v[138:141], v[170:173], v[52:55]
	v_mfma_f32_16x16x32_bf16 v[48:51], v[146:149], v[170:173], v[48:51]
	v_mfma_f32_16x16x32_bf16 v[40:43], v[138:141], v[178:181], v[40:43]
	v_mfma_f32_16x16x32_bf16 v[32:35], v[146:149], v[178:181], v[32:35]
	v_mfma_f32_16x16x32_bf16 v[24:27], v[138:141], v[186:189], v[24:27]
	v_mfma_f32_16x16x32_bf16 v[16:19], v[146:149], v[186:189], v[16:19]
	v_mfma_f32_16x16x32_bf16 v[60:63], v[142:145], v[166:169], v[60:63]
	v_mfma_f32_16x16x32_bf16 v[56:59], v[150:153], v[166:169], v[56:59]
	v_mfma_f32_16x16x32_bf16 v[52:55], v[142:145], v[174:177], v[52:55]
	v_mfma_f32_16x16x32_bf16 v[48:51], v[150:153], v[174:177], v[48:51]
	v_mfma_f32_16x16x32_bf16 v[40:43], v[142:145], v[182:185], v[40:43]
	v_mfma_f32_16x16x32_bf16 v[32:35], v[150:153], v[182:185], v[32:35]
	v_mfma_f32_16x16x32_bf16 v[24:27], v[142:145], v[206:209], v[24:27]
	v_mfma_f32_16x16x32_bf16 v[16:19], v[150:153], v[206:209], v[16:19]
	s_barrier
	s_add_u32 s2, s62, 0x80080
	s_addc_u32 s3, s63, 0
	s_add_i32 s6, s7, s10
	v_lshl_add_u64 v[138:139], s[2:3], 0, v[156:157]
	s_mov_b32 m0, s6
	s_nop 0
	global_load_lds_dwordx4 v[138:139], off
	v_lshl_add_u64 v[138:139], s[2:3], 0, v[128:129]
	s_add_i32 m0, s6, 0x2000
	s_nop 0
	global_load_lds_dwordx4 v[138:139], off
	s_waitcnt vmcnt(6)
	s_barrier
	v_mfma_f32_16x16x32_bf16 v[44:47], v[214:217], v[162:165], v[44:47]
	v_mfma_f32_16x16x32_bf16 v[36:39], v[222:225], v[162:165], v[36:39]
	v_mfma_f32_16x16x32_bf16 v[28:31], v[214:217], v[170:173], v[28:31]
	v_mfma_f32_16x16x32_bf16 v[20:23], v[222:225], v[170:173], v[20:23]
	v_mfma_f32_16x16x32_bf16 v[12:15], v[214:217], v[178:181], v[12:15]
	v_mfma_f32_16x16x32_bf16 v[8:11], v[222:225], v[178:181], v[8:11]
	v_mfma_f32_16x16x32_bf16 v[4:7], v[214:217], v[186:189], v[4:7]
	v_mfma_f32_16x16x32_bf16 v[0:3], v[222:225], v[186:189], v[0:3]
	v_mfma_f32_16x16x32_bf16 v[44:47], v[218:221], v[166:169], v[44:47]
	v_mfma_f32_16x16x32_bf16 v[36:39], v[226:229], v[166:169], v[36:39]
	v_mfma_f32_16x16x32_bf16 v[28:31], v[218:221], v[174:177], v[28:31]
	v_mfma_f32_16x16x32_bf16 v[20:23], v[226:229], v[174:177], v[20:23]
	v_mfma_f32_16x16x32_bf16 v[12:15], v[218:221], v[182:185], v[12:15]
	v_mfma_f32_16x16x32_bf16 v[8:11], v[226:229], v[182:185], v[8:11]
	v_mfma_f32_16x16x32_bf16 v[4:7], v[218:221], v[206:209], v[4:7]
	v_mfma_f32_16x16x32_bf16 v[0:3], v[226:229], v[206:209], v[0:3]
	s_add_i32 s54, s54, 2
	s_cmp_gt_u32 s54, 29
	s_mov_b64 s[6:7], s[60:61]
	s_barrier
	s_cbranch_scc0 .LBB0_286

.LBB0_325:
	s_add_i32 s83, s83, 1
	s_mul_i32 s6, s83, s18
	s_add_i32 s10, s6, s20
	s_cmpk_lt_i32 s10, 0x3b8
	s_cselect_b64 s[6:7], -1, 0
	s_cmpk_gt_i32 s10, 0x3b7
	s_cselect_b64 s[68:69], -1, 0
	s_and_b64 s[24:25], s[6:7], exec
	s_cselect_b32 s10, s10, 0
	s_ashr_i32 s21, s10, 31
	s_lshr_b32 s21, s21, 29
	s_add_i32 s21, s10, s21
	s_ashr_i32 s24, s21, 3
	s_and_b32 s21, s21, -8
	s_sub_i32 s10, s10, s21
	s_cmp_lt_i32 s10, 0
	s_movk_i32 s21, 0x78
	s_cselect_b32 s21, s21, 0x77
	s_mul_i32 s10, s21, s10
	s_add_i32 s21, s10, s24
	s_mul_hi_i32 s10, s21, 0x92492493
	s_add_i32 s10, s10, s21
	s_lshr_b32 s24, s10, 31
	s_ashr_i32 s10, s10, 4
	s_add_i32 s25, s10, s24
	s_lshl_b32 s37, s25, 2
	s_sub_i32 s10, 0x88, s37
	s_min_i32 s44, s10, 4
	s_abs_i32 s45, s44
	v_cvt_f32_u32_e32 v0, s45
	s_sub_i32 s46, 0, s45
	s_mul_i32 s25, s25, 28
	s_sub_i32 s21, s21, s25
	v_rcp_iflag_f32_e32 v0, v0
	s_mov_b32 s24, s36
	s_abs_i32 s36, s21
	s_xor_b32 s25, s21, s44
	v_mul_f32_e32 v0, 0x4f7ffffe, v0
	v_cvt_u32_f32_e32 v0, v0
	s_mov_b64 s[42:43], s[48:49]
	s_ashr_i32 s25, s25, 31
	s_mov_b32 s10, s66
	v_readfirstlane_b32 s47, v0
	s_mul_i32 s46, s46, s47
	s_mul_hi_u32 s46, s47, s46
	s_add_i32 s47, s47, s46
	s_mul_hi_u32 s46, s36, s47
	s_mul_i32 s47, s46, s45
	s_sub_i32 s36, s36, s47
	s_add_i32 s47, s46, 1
	s_sub_i32 s48, s36, s45
	s_cmp_ge_u32 s36, s45
	s_cselect_b32 s46, s47, s46
	s_cselect_b32 s36, s48, s36
	s_add_i32 s47, s46, 1
	s_cmp_ge_u32 s36, s45
	s_cselect_b32 s36, s47, s46
	s_xor_b32 s36, s36, s25
	s_sub_i32 s66, s36, s25
	s_mul_i32 s25, s66, s44
	s_sub_i32 s21, s21, s25
	s_add_i32 s36, s37, s21
	s_ashr_i32 s37, s36, 31
	s_lshl_b64 s[44:45], s[36:37], 19
	s_mov_b64 s[2:3], s[62:63]
	s_add_u32 s62, s58, s44
	s_addc_u32 s63, s59, s45
	s_and_b64 s[44:45], s[6:7], exec
	s_cselect_b32 s25, s63, s3
	s_cselect_b32 s37, s62, s2
	s_ashr_i32 s67, s66, 31
	s_lshl_b64 s[44:45], s[66:67], 19
	s_add_u32 s48, s19, s44
	s_addc_u32 s49, s34, s45
	s_and_b64 s[6:7], s[6:7], exec
	s_cselect_b32 s44, s49, s43
	s_cselect_b32 s45, s48, s42
	s_add_u32 s46, s42, 0x100
	s_addc_u32 s47, s43, 0
	s_add_u32 s6, s2, 0x40080
	s_addc_u32 s7, s3, 0
	s_mov_b32 s60, -2
	s_add_u32 s2, s6, 0xfffc0080
	s_addc_u32 s3, s7, -1
	s_add_i32 s21, 0, 0x10000
	v_add_u32_e32 v154, s21, v141
	ds_read_b128 v[136:139], v154
	ds_read_b128 v[150:153], v154 offset:1024
	ds_read_b128 v[162:165], v154 offset:2048
	ds_read_b128 v[166:169], v154 offset:3072
	s_cmp_eq_u32 s60, 12
	s_cselect_b32 s3, s25, s3
	s_cselect_b32 s2, s37, s2
	s_cselect_b32 s43, s44, s47
	s_cselect_b32 s42, s45, s46
	v_lshl_add_u64 v[154:155], s[6:7], 0, v[134:135]
	s_add_i32 m0, s53, 0xc000
	ds_read_b128 v[170:173], v149
	ds_read_b128 v[174:177], v149 offset:1024
	ds_read_b128 v[178:181], v149 offset:2048
	ds_read_b128 v[182:185], v149 offset:3072
	ds_read_b128 v[186:189], v149 offset:4096
	ds_read_b128 v[206:209], v149 offset:5120
	ds_read_b128 v[214:217], v149 offset:6144
	ds_read_b128 v[218:221], v149 offset:7168
	global_load_lds_dwordx4 v[154:155], off
	v_lshl_add_u64 v[154:155], s[6:7], 0, v[132:133]
	s_add_i32 m0, s53, 0xe000
	s_nop 0
	global_load_lds_dwordx4 v[154:155], off
	s_waitcnt lgkmcnt(8)
	s_barrier
	s_waitcnt lgkmcnt(0)
	v_mfma_f32_16x16x32_bf16 v[124:127], v[136:139], v[170:173], 0
	v_mfma_f32_16x16x32_bf16 v[120:123], v[162:165], v[170:173], 0
	v_mfma_f32_16x16x32_bf16 v[108:111], v[136:139], v[178:181], 0
	v_mfma_f32_16x16x32_bf16 v[104:107], v[162:165], v[178:181], 0
	v_mfma_f32_16x16x32_bf16 v[92:95], v[136:139], v[186:189], 0
	v_mfma_f32_16x16x32_bf16 v[88:91], v[162:165], v[186:189], 0
	v_mfma_f32_16x16x32_bf16 v[76:79], v[136:139], v[214:217], 0
	v_mfma_f32_16x16x32_bf16 v[72:75], v[162:165], v[214:217], 0
	v_mfma_f32_16x16x32_bf16 v[124:127], v[150:153], v[174:177], v[124:127]
	v_mfma_f32_16x16x32_bf16 v[120:123], v[166:169], v[174:177], v[120:123]
	v_mfma_f32_16x16x32_bf16 v[108:111], v[150:153], v[182:185], v[108:111]
	v_mfma_f32_16x16x32_bf16 v[104:107], v[166:169], v[182:185], v[104:107]
	v_mfma_f32_16x16x32_bf16 v[92:95], v[150:153], v[206:209], v[92:95]
	v_mfma_f32_16x16x32_bf16 v[88:91], v[166:169], v[206:209], v[88:91]
	v_mfma_f32_16x16x32_bf16 v[76:79], v[150:153], v[218:221], v[76:79]
	v_mfma_f32_16x16x32_bf16 v[72:75], v[166:169], v[218:221], v[72:75]
	s_barrier
	s_add_i32 s61, 0, 0x14000
	v_add_u32_e32 v154, s61, v141
	s_add_i32 s21, s21, s35
	ds_read_b128 v[222:225], v154
	ds_read_b128 v[226:229], v154 offset:1024
	ds_read_b128 v[230:233], v154 offset:2048
	ds_read_b128 v[234:237], v154 offset:3072
	v_lshl_add_u64 v[154:155], s[42:43], 0, v[130:131]
	s_mov_b32 m0, s21
	v_lshl_add_u64 v[238:239], s[42:43], 0, v[128:129]
	global_load_lds_dwordx4 v[154:155], off
	s_add_i32 m0, s21, 0x2000
	s_nop 0
	global_load_lds_dwordx4 v[238:239], off
	s_barrier
	s_waitcnt lgkmcnt(0)
	v_mfma_f32_16x16x32_bf16 v[116:119], v[222:225], v[170:173], 0
	v_mfma_f32_16x16x32_bf16 v[112:115], v[230:233], v[170:173], 0
	v_mfma_f32_16x16x32_bf16 v[100:103], v[222:225], v[178:181], 0
	v_mfma_f32_16x16x32_bf16 v[96:99], v[230:233], v[178:181], 0
	v_mfma_f32_16x16x32_bf16 v[84:87], v[222:225], v[186:189], 0
	v_mfma_f32_16x16x32_bf16 v[80:83], v[230:233], v[186:189], 0
	v_mfma_f32_16x16x32_bf16 v[68:71], v[222:225], v[214:217], 0
	v_mfma_f32_16x16x32_bf16 v[64:67], v[230:233], v[214:217], 0
	v_mfma_f32_16x16x32_bf16 v[116:119], v[226:229], v[174:177], v[116:119]
	v_mfma_f32_16x16x32_bf16 v[112:115], v[234:237], v[174:177], v[112:115]
	v_mfma_f32_16x16x32_bf16 v[100:103], v[226:229], v[182:185], v[100:103]
	v_mfma_f32_16x16x32_bf16 v[96:99], v[234:237], v[182:185], v[96:99]
	v_mfma_f32_16x16x32_bf16 v[84:87], v[226:229], v[206:209], v[84:87]
	v_mfma_f32_16x16x32_bf16 v[80:83], v[234:237], v[206:209], v[80:83]
	v_mfma_f32_16x16x32_bf16 v[68:71], v[226:229], v[218:221], v[68:71]
	v_mfma_f32_16x16x32_bf16 v[64:67], v[234:237], v[218:221], v[64:67]
	s_mov_b32 m0, s53
	v_lshl_add_u64 v[240:241], s[2:3], 0, v[130:131]
	s_barrier
	ds_read_b128 v[170:173], v149 offset:16384
	ds_read_b128 v[174:177], v149 offset:17408
	ds_read_b128 v[178:181], v149 offset:18432
	ds_read_b128 v[182:185], v149 offset:19456
	ds_read_b128 v[186:189], v149 offset:20480
	ds_read_b128 v[206:209], v149 offset:21504
	ds_read_b128 v[214:217], v149 offset:22528
	ds_read_b128 v[218:221], v149 offset:23552
	global_load_lds_dwordx4 v[240:241], off
	v_lshl_add_u64 v[242:243], s[2:3], 0, v[128:129]
	s_mov_b32 m0, s54
	s_nop 0
	global_load_lds_dwordx4 v[242:243], off
	s_barrier
	s_waitcnt lgkmcnt(0)
	v_mfma_f32_16x16x32_bf16 v[60:63], v[136:139], v[170:173], 0
	v_mfma_f32_16x16x32_bf16 v[56:59], v[162:165], v[170:173], 0
	v_mfma_f32_16x16x32_bf16 v[44:47], v[136:139], v[178:181], 0
	v_mfma_f32_16x16x32_bf16 v[40:43], v[162:165], v[178:181], 0
	v_mfma_f32_16x16x32_bf16 v[28:31], v[136:139], v[186:189], 0
	v_mfma_f32_16x16x32_bf16 v[24:27], v[162:165], v[186:189], 0
	v_mfma_f32_16x16x32_bf16 v[12:15], v[136:139], v[214:217], 0
	v_mfma_f32_16x16x32_bf16 v[8:11], v[162:165], v[214:217], 0
	v_mfma_f32_16x16x32_bf16 v[60:63], v[150:153], v[174:177], v[60:63]
	v_mfma_f32_16x16x32_bf16 v[56:59], v[166:169], v[174:177], v[56:59]
	v_mfma_f32_16x16x32_bf16 v[44:47], v[150:153], v[182:185], v[44:47]
	v_mfma_f32_16x16x32_bf16 v[40:43], v[166:169], v[182:185], v[40:43]
	v_mfma_f32_16x16x32_bf16 v[28:31], v[150:153], v[206:209], v[28:31]
	v_mfma_f32_16x16x32_bf16 v[24:27], v[166:169], v[206:209], v[24:27]
	v_mfma_f32_16x16x32_bf16 v[12:15], v[150:153], v[218:221], v[12:15]
	v_mfma_f32_16x16x32_bf16 v[8:11], v[166:169], v[218:221], v[8:11]
	s_barrier
	s_add_u32 s80, s42, 0x40000
	s_addc_u32 s81, s43, 0
	s_add_i32 s21, s61, s35
	v_lshl_add_u64 v[136:137], s[80:81], 0, v[130:131]
	s_mov_b32 m0, s21
	s_nop 0
	global_load_lds_dwordx4 v[136:137], off
	v_lshl_add_u64 v[136:137], s[80:81], 0, v[128:129]
	s_add_i32 m0, s21, 0x2000
	s_nop 0
	global_load_lds_dwordx4 v[136:137], off
	s_waitcnt vmcnt(6)
	s_barrier
	v_mfma_f32_16x16x32_bf16 v[52:55], v[222:225], v[170:173], 0
	v_mfma_f32_16x16x32_bf16 v[48:51], v[230:233], v[170:173], 0
	v_mfma_f32_16x16x32_bf16 v[36:39], v[222:225], v[178:181], 0
	v_mfma_f32_16x16x32_bf16 v[32:35], v[230:233], v[178:181], 0
	v_mfma_f32_16x16x32_bf16 v[20:23], v[222:225], v[186:189], 0
	v_mfma_f32_16x16x32_bf16 v[16:19], v[230:233], v[186:189], 0
	v_mfma_f32_16x16x32_bf16 v[4:7], v[222:225], v[214:217], 0
	v_mfma_f32_16x16x32_bf16 v[0:3], v[230:233], v[214:217], 0
	v_mfma_f32_16x16x32_bf16 v[52:55], v[226:229], v[174:177], v[52:55]
	v_mfma_f32_16x16x32_bf16 v[48:51], v[234:237], v[174:177], v[48:51]
	v_mfma_f32_16x16x32_bf16 v[36:39], v[226:229], v[182:185], v[36:39]
	v_mfma_f32_16x16x32_bf16 v[32:35], v[234:237], v[182:185], v[32:35]
	v_mfma_f32_16x16x32_bf16 v[20:23], v[226:229], v[206:209], v[20:23]
	v_mfma_f32_16x16x32_bf16 v[16:19], v[234:237], v[206:209], v[16:19]
	v_mfma_f32_16x16x32_bf16 v[4:7], v[226:229], v[218:221], v[4:7]
	v_mfma_f32_16x16x32_bf16 v[0:3], v[234:237], v[218:221], v[0:3]
	s_add_i32 s21, 0, 0x18000
	v_add_u32_e32 v156, s21, v141
	s_barrier
	ds_read_b128 v[136:139], v156
	ds_read_b128 v[150:153], v156 offset:1024
	ds_read_b128 v[162:165], v156 offset:2048
	ds_read_b128 v[166:169], v156 offset:3072
	s_add_u32 s2, s2, 0x40000
	s_addc_u32 s3, s3, 0
	s_mov_b32 m0, s55
	v_lshl_add_u64 v[222:223], s[2:3], 0, v[130:131]
	ds_read_b128 v[170:173], v149 offset:32768
	ds_read_b128 v[174:177], v149 offset:33792
	ds_read_b128 v[178:181], v149 offset:34816
	ds_read_b128 v[182:185], v149 offset:35840
	ds_read_b128 v[186:189], v149 offset:36864
	ds_read_b128 v[206:209], v149 offset:37888
	ds_read_b128 v[214:217], v149 offset:38912
	ds_read_b128 v[218:221], v149 offset:39936
	global_load_lds_dwordx4 v[222:223], off
	v_lshl_add_u64 v[222:223], s[2:3], 0, v[128:129]
	s_mov_b32 m0, s78
	s_nop 0
	global_load_lds_dwordx4 v[222:223], off
	s_waitcnt lgkmcnt(8)
	s_barrier
	s_waitcnt lgkmcnt(0)
	v_mfma_f32_16x16x32_bf16 v[124:127], v[136:139], v[170:173], v[124:127]
	v_mfma_f32_16x16x32_bf16 v[120:123], v[162:165], v[170:173], v[120:123]
	v_mfma_f32_16x16x32_bf16 v[108:111], v[136:139], v[178:181], v[108:111]
	v_mfma_f32_16x16x32_bf16 v[104:107], v[162:165], v[178:181], v[104:107]
	v_mfma_f32_16x16x32_bf16 v[92:95], v[136:139], v[186:189], v[92:95]
	v_mfma_f32_16x16x32_bf16 v[88:91], v[162:165], v[186:189], v[88:91]
	v_mfma_f32_16x16x32_bf16 v[76:79], v[136:139], v[214:217], v[76:79]
	v_mfma_f32_16x16x32_bf16 v[72:75], v[162:165], v[214:217], v[72:75]
	v_mfma_f32_16x16x32_bf16 v[124:127], v[150:153], v[174:177], v[124:127]
	v_mfma_f32_16x16x32_bf16 v[120:123], v[166:169], v[174:177], v[120:123]
	v_mfma_f32_16x16x32_bf16 v[108:111], v[150:153], v[182:185], v[108:111]
	v_mfma_f32_16x16x32_bf16 v[104:107], v[166:169], v[182:185], v[104:107]
	v_mfma_f32_16x16x32_bf16 v[92:95], v[150:153], v[206:209], v[92:95]
	v_mfma_f32_16x16x32_bf16 v[88:91], v[166:169], v[206:209], v[88:91]
	v_mfma_f32_16x16x32_bf16 v[76:79], v[150:153], v[218:221], v[76:79]
	v_mfma_f32_16x16x32_bf16 v[72:75], v[166:169], v[218:221], v[72:75]
	s_barrier
	s_add_i32 s61, 0, 0x1c000
	s_add_i32 s2, s21, s35
	v_add_u32_e32 v156, s61, v141
	v_lshl_add_u64 v[154:155], v[154:155], 0, s[50:51]
	s_mov_b32 m0, s2
	ds_read_b128 v[222:225], v156
	ds_read_b128 v[226:229], v156 offset:1024
	ds_read_b128 v[230:233], v156 offset:2048
	ds_read_b128 v[234:237], v156 offset:3072
	global_load_lds_dwordx4 v[154:155], off
	v_lshl_add_u64 v[154:155], v[238:239], 0, s[50:51]
	s_add_i32 m0, s2, 0x2000
	s_nop 0
	global_load_lds_dwordx4 v[154:155], off
	s_barrier
	s_waitcnt lgkmcnt(0)
	v_mfma_f32_16x16x32_bf16 v[116:119], v[222:225], v[170:173], v[116:119]
	v_mfma_f32_16x16x32_bf16 v[112:115], v[230:233], v[170:173], v[112:115]
	v_mfma_f32_16x16x32_bf16 v[100:103], v[222:225], v[178:181], v[100:103]
	v_mfma_f32_16x16x32_bf16 v[96:99], v[230:233], v[178:181], v[96:99]
	v_mfma_f32_16x16x32_bf16 v[84:87], v[222:225], v[186:189], v[84:87]
	v_mfma_f32_16x16x32_bf16 v[80:83], v[230:233], v[186:189], v[80:83]
	v_mfma_f32_16x16x32_bf16 v[68:71], v[222:225], v[214:217], v[68:71]
	v_mfma_f32_16x16x32_bf16 v[64:67], v[230:233], v[214:217], v[64:67]
	v_mfma_f32_16x16x32_bf16 v[116:119], v[226:229], v[174:177], v[116:119]
	v_mfma_f32_16x16x32_bf16 v[112:115], v[234:237], v[174:177], v[112:115]
	v_mfma_f32_16x16x32_bf16 v[100:103], v[226:229], v[182:185], v[100:103]
	v_mfma_f32_16x16x32_bf16 v[96:99], v[234:237], v[182:185], v[96:99]
	v_mfma_f32_16x16x32_bf16 v[84:87], v[226:229], v[206:209], v[84:87]
	v_mfma_f32_16x16x32_bf16 v[80:83], v[234:237], v[206:209], v[80:83]
	v_mfma_f32_16x16x32_bf16 v[68:71], v[226:229], v[218:221], v[68:71]
	v_mfma_f32_16x16x32_bf16 v[64:67], v[234:237], v[218:221], v[64:67]
	s_mov_b32 m0, s79
	v_lshl_add_u64 v[154:155], v[240:241], 0, s[50:51]
	s_barrier
	ds_read_b128 v[170:173], v149 offset:49152
	ds_read_b128 v[174:177], v149 offset:50176
	ds_read_b128 v[178:181], v149 offset:51200
	ds_read_b128 v[182:185], v149 offset:52224
	ds_read_b128 v[186:189], v149 offset:53248
	ds_read_b128 v[206:209], v149 offset:54272
	ds_read_b128 v[214:217], v149 offset:55296
	ds_read_b128 v[218:221], v149 offset:56320
	global_load_lds_dwordx4 v[154:155], off
	v_lshl_add_u64 v[154:155], v[242:243], 0, s[50:51]
	s_mov_b32 m0, s82
	s_nop 0
	global_load_lds_dwordx4 v[154:155], off
	s_barrier
	s_waitcnt lgkmcnt(0)
	v_mfma_f32_16x16x32_bf16 v[60:63], v[136:139], v[170:173], v[60:63]
	v_mfma_f32_16x16x32_bf16 v[56:59], v[162:165], v[170:173], v[56:59]
	v_mfma_f32_16x16x32_bf16 v[44:47], v[136:139], v[178:181], v[44:47]
	v_mfma_f32_16x16x32_bf16 v[40:43], v[162:165], v[178:181], v[40:43]
	v_mfma_f32_16x16x32_bf16 v[28:31], v[136:139], v[186:189], v[28:31]
	v_mfma_f32_16x16x32_bf16 v[24:27], v[162:165], v[186:189], v[24:27]
	v_mfma_f32_16x16x32_bf16 v[12:15], v[136:139], v[214:217], v[12:15]
	v_mfma_f32_16x16x32_bf16 v[8:11], v[162:165], v[214:217], v[8:11]
	v_mfma_f32_16x16x32_bf16 v[60:63], v[150:153], v[174:177], v[60:63]
	v_mfma_f32_16x16x32_bf16 v[56:59], v[166:169], v[174:177], v[56:59]
	v_mfma_f32_16x16x32_bf16 v[44:47], v[150:153], v[182:185], v[44:47]
	v_mfma_f32_16x16x32_bf16 v[40:43], v[166:169], v[182:185], v[40:43]
	v_mfma_f32_16x16x32_bf16 v[28:31], v[150:153], v[206:209], v[28:31]
	v_mfma_f32_16x16x32_bf16 v[24:27], v[166:169], v[206:209], v[24:27]
	v_mfma_f32_16x16x32_bf16 v[12:15], v[150:153], v[218:221], v[12:15]
	v_mfma_f32_16x16x32_bf16 v[8:11], v[166:169], v[218:221], v[8:11]
	s_barrier
	s_add_u32 s2, s42, 0x40080
	s_addc_u32 s3, s43, 0
	s_add_i32 s21, s61, s35
	v_lshl_add_u64 v[136:137], s[2:3], 0, v[130:131]
	s_mov_b32 m0, s21
	s_nop 0
	global_load_lds_dwordx4 v[136:137], off
	v_lshl_add_u64 v[136:137], s[2:3], 0, v[128:129]
	s_add_i32 m0, s21, 0x2000
	s_nop 0
	global_load_lds_dwordx4 v[136:137], off
	s_waitcnt vmcnt(6)
	s_barrier
	v_mfma_f32_16x16x32_bf16 v[52:55], v[222:225], v[170:173], v[52:55]
	v_mfma_f32_16x16x32_bf16 v[48:51], v[230:233], v[170:173], v[48:51]
	v_mfma_f32_16x16x32_bf16 v[36:39], v[222:225], v[178:181], v[36:39]
	v_mfma_f32_16x16x32_bf16 v[32:35], v[230:233], v[178:181], v[32:35]
	v_mfma_f32_16x16x32_bf16 v[20:23], v[222:225], v[186:189], v[20:23]
	v_mfma_f32_16x16x32_bf16 v[16:19], v[230:233], v[186:189], v[16:19]
	v_mfma_f32_16x16x32_bf16 v[4:7], v[222:225], v[214:217], v[4:7]
	v_mfma_f32_16x16x32_bf16 v[0:3], v[230:233], v[214:217], v[0:3]
	v_mfma_f32_16x16x32_bf16 v[52:55], v[226:229], v[174:177], v[52:55]
	v_mfma_f32_16x16x32_bf16 v[48:51], v[234:237], v[174:177], v[48:51]
	v_mfma_f32_16x16x32_bf16 v[36:39], v[226:229], v[182:185], v[36:39]
	v_mfma_f32_16x16x32_bf16 v[32:35], v[234:237], v[182:185], v[32:35]
	v_mfma_f32_16x16x32_bf16 v[20:23], v[226:229], v[206:209], v[20:23]
	v_mfma_f32_16x16x32_bf16 v[16:19], v[234:237], v[206:209], v[16:19]
	v_mfma_f32_16x16x32_bf16 v[4:7], v[226:229], v[218:221], v[4:7]
	v_mfma_f32_16x16x32_bf16 v[0:3], v[234:237], v[218:221], v[0:3]
	s_add_i32 s60, s60, 2
	s_add_u32 s46, s46, 0x100
	s_addc_u32 s47, s47, 0
	s_add_u32 s6, s6, 0x100
	s_addc_u32 s7, s7, 0
	s_cmp_gt_u32 s60, 13
	s_barrier
	s_cbranch_scc1 .Lpost_326
.LBB0_326:
	s_add_u32 s2, s6, 0xfffc0080
	s_addc_u32 s3, s7, -1
	s_add_i32 s21, 0, 0x10000
	v_add_u32_e32 v154, s21, v141
	ds_read_b128 v[136:139], v154
	ds_read_b128 v[150:153], v154 offset:1024
	ds_read_b128 v[162:165], v154 offset:2048
	ds_read_b128 v[166:169], v154 offset:3072
	s_cmp_eq_u32 s60, 12
	s_cselect_b32 s3, s25, s3
	s_cselect_b32 s2, s37, s2
	s_cselect_b32 s43, s44, s47
	s_cselect_b32 s42, s45, s46
	v_lshl_add_u64 v[154:155], s[6:7], 0, v[134:135]
	s_add_i32 m0, s53, 0xc000
	ds_read_b128 v[170:173], v149
	ds_read_b128 v[174:177], v149 offset:1024
	ds_read_b128 v[178:181], v149 offset:2048
	ds_read_b128 v[182:185], v149 offset:3072
	ds_read_b128 v[186:189], v149 offset:4096
	ds_read_b128 v[206:209], v149 offset:5120
	ds_read_b128 v[214:217], v149 offset:6144
	ds_read_b128 v[218:221], v149 offset:7168
	global_load_lds_dwordx4 v[154:155], off
	v_lshl_add_u64 v[154:155], s[6:7], 0, v[132:133]
	s_add_i32 m0, s53, 0xe000
	s_nop 0
	global_load_lds_dwordx4 v[154:155], off
	s_waitcnt lgkmcnt(8)
	s_barrier
	s_waitcnt lgkmcnt(0)
	v_mfma_f32_16x16x32_bf16 v[124:127], v[136:139], v[170:173], v[124:127]
	v_mfma_f32_16x16x32_bf16 v[120:123], v[162:165], v[170:173], v[120:123]
	v_mfma_f32_16x16x32_bf16 v[108:111], v[136:139], v[178:181], v[108:111]
	v_mfma_f32_16x16x32_bf16 v[104:107], v[162:165], v[178:181], v[104:107]
	v_mfma_f32_16x16x32_bf16 v[92:95], v[136:139], v[186:189], v[92:95]
	v_mfma_f32_16x16x32_bf16 v[88:91], v[162:165], v[186:189], v[88:91]
	v_mfma_f32_16x16x32_bf16 v[76:79], v[136:139], v[214:217], v[76:79]
	v_mfma_f32_16x16x32_bf16 v[72:75], v[162:165], v[214:217], v[72:75]
	v_mfma_f32_16x16x32_bf16 v[124:127], v[150:153], v[174:177], v[124:127]
	v_mfma_f32_16x16x32_bf16 v[120:123], v[166:169], v[174:177], v[120:123]
	v_mfma_f32_16x16x32_bf16 v[108:111], v[150:153], v[182:185], v[108:111]
	v_mfma_f32_16x16x32_bf16 v[104:107], v[166:169], v[182:185], v[104:107]
	v_mfma_f32_16x16x32_bf16 v[92:95], v[150:153], v[206:209], v[92:95]
	v_mfma_f32_16x16x32_bf16 v[88:91], v[166:169], v[206:209], v[88:91]
	v_mfma_f32_16x16x32_bf16 v[76:79], v[150:153], v[218:221], v[76:79]
	v_mfma_f32_16x16x32_bf16 v[72:75], v[166:169], v[218:221], v[72:75]
	s_barrier
	s_add_i32 s61, 0, 0x14000
	v_add_u32_e32 v154, s61, v141
	s_add_i32 s21, s21, s35
	ds_read_b128 v[222:225], v154
	ds_read_b128 v[226:229], v154 offset:1024
	ds_read_b128 v[230:233], v154 offset:2048
	ds_read_b128 v[234:237], v154 offset:3072
	v_lshl_add_u64 v[154:155], s[42:43], 0, v[130:131]
	s_mov_b32 m0, s21
	v_lshl_add_u64 v[238:239], s[42:43], 0, v[128:129]
	global_load_lds_dwordx4 v[154:155], off
	s_add_i32 m0, s21, 0x2000
	s_nop 0
	global_load_lds_dwordx4 v[238:239], off
	s_barrier
	s_waitcnt lgkmcnt(0)
	v_mfma_f32_16x16x32_bf16 v[116:119], v[222:225], v[170:173], v[116:119]
	v_mfma_f32_16x16x32_bf16 v[112:115], v[230:233], v[170:173], v[112:115]
	v_mfma_f32_16x16x32_bf16 v[100:103], v[222:225], v[178:181], v[100:103]
	v_mfma_f32_16x16x32_bf16 v[96:99], v[230:233], v[178:181], v[96:99]
	v_mfma_f32_16x16x32_bf16 v[84:87], v[222:225], v[186:189], v[84:87]
	v_mfma_f32_16x16x32_bf16 v[80:83], v[230:233], v[186:189], v[80:83]
	v_mfma_f32_16x16x32_bf16 v[68:71], v[222:225], v[214:217], v[68:71]
	v_mfma_f32_16x16x32_bf16 v[64:67], v[230:233], v[214:217], v[64:67]
	v_mfma_f32_16x16x32_bf16 v[116:119], v[226:229], v[174:177], v[116:119]
	v_mfma_f32_16x16x32_bf16 v[112:115], v[234:237], v[174:177], v[112:115]
	v_mfma_f32_16x16x32_bf16 v[100:103], v[226:229], v[182:185], v[100:103]
	v_mfma_f32_16x16x32_bf16 v[96:99], v[234:237], v[182:185], v[96:99]
	v_mfma_f32_16x16x32_bf16 v[84:87], v[226:229], v[206:209], v[84:87]
	v_mfma_f32_16x16x32_bf16 v[80:83], v[234:237], v[206:209], v[80:83]
	v_mfma_f32_16x16x32_bf16 v[68:71], v[226:229], v[218:221], v[68:71]
	v_mfma_f32_16x16x32_bf16 v[64:67], v[234:237], v[218:221], v[64:67]
	s_mov_b32 m0, s53
	v_lshl_add_u64 v[240:241], s[2:3], 0, v[130:131]
	s_barrier
	ds_read_b128 v[170:173], v149 offset:16384
	ds_read_b128 v[174:177], v149 offset:17408
	ds_read_b128 v[178:181], v149 offset:18432
	ds_read_b128 v[182:185], v149 offset:19456
	ds_read_b128 v[186:189], v149 offset:20480
	ds_read_b128 v[206:209], v149 offset:21504
	ds_read_b128 v[214:217], v149 offset:22528
	ds_read_b128 v[218:221], v149 offset:23552
	global_load_lds_dwordx4 v[240:241], off
	v_lshl_add_u64 v[242:243], s[2:3], 0, v[128:129]
	s_mov_b32 m0, s54
	s_nop 0
	global_load_lds_dwordx4 v[242:243], off
	s_barrier
	s_waitcnt lgkmcnt(0)
	v_mfma_f32_16x16x32_bf16 v[60:63], v[136:139], v[170:173], v[60:63]
	v_mfma_f32_16x16x32_bf16 v[56:59], v[162:165], v[170:173], v[56:59]
	v_mfma_f32_16x16x32_bf16 v[44:47], v[136:139], v[178:181], v[44:47]
	v_mfma_f32_16x16x32_bf16 v[40:43], v[162:165], v[178:181], v[40:43]
	v_mfma_f32_16x16x32_bf16 v[28:31], v[136:139], v[186:189], v[28:31]
	v_mfma_f32_16x16x32_bf16 v[24:27], v[162:165], v[186:189], v[24:27]
	v_mfma_f32_16x16x32_bf16 v[12:15], v[136:139], v[214:217], v[12:15]
	v_mfma_f32_16x16x32_bf16 v[8:11], v[162:165], v[214:217], v[8:11]
	v_mfma_f32_16x16x32_bf16 v[60:63], v[150:153], v[174:177], v[60:63]
	v_mfma_f32_16x16x32_bf16 v[56:59], v[166:169], v[174:177], v[56:59]
	v_mfma_f32_16x16x32_bf16 v[44:47], v[150:153], v[182:185], v[44:47]
	v_mfma_f32_16x16x32_bf16 v[40:43], v[166:169], v[182:185], v[40:43]
	v_mfma_f32_16x16x32_bf16 v[28:31], v[150:153], v[206:209], v[28:31]
	v_mfma_f32_16x16x32_bf16 v[24:27], v[166:169], v[206:209], v[24:27]
	v_mfma_f32_16x16x32_bf16 v[12:15], v[150:153], v[218:221], v[12:15]
	v_mfma_f32_16x16x32_bf16 v[8:11], v[166:169], v[218:221], v[8:11]
	s_barrier
	s_add_u32 s80, s42, 0x40000
	s_addc_u32 s81, s43, 0
	s_add_i32 s21, s61, s35
	v_lshl_add_u64 v[136:137], s[80:81], 0, v[130:131]
	s_mov_b32 m0, s21
	s_nop 0
	global_load_lds_dwordx4 v[136:137], off
	v_lshl_add_u64 v[136:137], s[80:81], 0, v[128:129]
	s_add_i32 m0, s21, 0x2000
	s_nop 0
	global_load_lds_dwordx4 v[136:137], off
	s_waitcnt vmcnt(6)
	s_barrier
	v_mfma_f32_16x16x32_bf16 v[52:55], v[222:225], v[170:173], v[52:55]
	v_mfma_f32_16x16x32_bf16 v[48:51], v[230:233], v[170:173], v[48:51]
	v_mfma_f32_16x16x32_bf16 v[36:39], v[222:225], v[178:181], v[36:39]
	v_mfma_f32_16x16x32_bf16 v[32:35], v[230:233], v[178:181], v[32:35]
	v_mfma_f32_16x16x32_bf16 v[20:23], v[222:225], v[186:189], v[20:23]
	v_mfma_f32_16x16x32_bf16 v[16:19], v[230:233], v[186:189], v[16:19]
	v_mfma_f32_16x16x32_bf16 v[4:7], v[222:225], v[214:217], v[4:7]
	v_mfma_f32_16x16x32_bf16 v[0:3], v[230:233], v[214:217], v[0:3]
	v_mfma_f32_16x16x32_bf16 v[52:55], v[226:229], v[174:177], v[52:55]
	v_mfma_f32_16x16x32_bf16 v[48:51], v[234:237], v[174:177], v[48:51]
	v_mfma_f32_16x16x32_bf16 v[36:39], v[226:229], v[182:185], v[36:39]
	v_mfma_f32_16x16x32_bf16 v[32:35], v[234:237], v[182:185], v[32:35]
	v_mfma_f32_16x16x32_bf16 v[20:23], v[226:229], v[206:209], v[20:23]
	v_mfma_f32_16x16x32_bf16 v[16:19], v[234:237], v[206:209], v[16:19]
	v_mfma_f32_16x16x32_bf16 v[4:7], v[226:229], v[218:221], v[4:7]
	v_mfma_f32_16x16x32_bf16 v[0:3], v[234:237], v[218:221], v[0:3]
	s_add_i32 s21, 0, 0x18000
	v_add_u32_e32 v156, s21, v141
	s_barrier
	ds_read_b128 v[136:139], v156
	ds_read_b128 v[150:153], v156 offset:1024
	ds_read_b128 v[162:165], v156 offset:2048
	ds_read_b128 v[166:169], v156 offset:3072
	s_add_u32 s2, s2, 0x40000
	s_addc_u32 s3, s3, 0
	s_mov_b32 m0, s55
	v_lshl_add_u64 v[222:223], s[2:3], 0, v[130:131]
	ds_read_b128 v[170:173], v149 offset:32768
	ds_read_b128 v[174:177], v149 offset:33792
	ds_read_b128 v[178:181], v149 offset:34816
	ds_read_b128 v[182:185], v149 offset:35840
	ds_read_b128 v[186:189], v149 offset:36864
	ds_read_b128 v[206:209], v149 offset:37888
	ds_read_b128 v[214:217], v149 offset:38912
	ds_read_b128 v[218:221], v149 offset:39936
	global_load_lds_dwordx4 v[222:223], off
	v_lshl_add_u64 v[222:223], s[2:3], 0, v[128:129]
	s_mov_b32 m0, s78
	s_nop 0
	global_load_lds_dwordx4 v[222:223], off
	s_waitcnt lgkmcnt(8)
	s_barrier
	s_waitcnt lgkmcnt(0)
	v_mfma_f32_16x16x32_bf16 v[124:127], v[136:139], v[170:173], v[124:127]
	v_mfma_f32_16x16x32_bf16 v[120:123], v[162:165], v[170:173], v[120:123]
	v_mfma_f32_16x16x32_bf16 v[108:111], v[136:139], v[178:181], v[108:111]
	v_mfma_f32_16x16x32_bf16 v[104:107], v[162:165], v[178:181], v[104:107]
	v_mfma_f32_16x16x32_bf16 v[92:95], v[136:139], v[186:189], v[92:95]
	v_mfma_f32_16x16x32_bf16 v[88:91], v[162:165], v[186:189], v[88:91]
	v_mfma_f32_16x16x32_bf16 v[76:79], v[136:139], v[214:217], v[76:79]
	v_mfma_f32_16x16x32_bf16 v[72:75], v[162:165], v[214:217], v[72:75]
	v_mfma_f32_16x16x32_bf16 v[124:127], v[150:153], v[174:177], v[124:127]
	v_mfma_f32_16x16x32_bf16 v[120:123], v[166:169], v[174:177], v[120:123]
	v_mfma_f32_16x16x32_bf16 v[108:111], v[150:153], v[182:185], v[108:111]
	v_mfma_f32_16x16x32_bf16 v[104:107], v[166:169], v[182:185], v[104:107]
	v_mfma_f32_16x16x32_bf16 v[92:95], v[150:153], v[206:209], v[92:95]
	v_mfma_f32_16x16x32_bf16 v[88:91], v[166:169], v[206:209], v[88:91]
	v_mfma_f32_16x16x32_bf16 v[76:79], v[150:153], v[218:221], v[76:79]
	v_mfma_f32_16x16x32_bf16 v[72:75], v[166:169], v[218:221], v[72:75]
	s_barrier
	s_add_i32 s61, 0, 0x1c000
	s_add_i32 s2, s21, s35
	v_add_u32_e32 v156, s61, v141
	v_lshl_add_u64 v[154:155], v[154:155], 0, s[50:51]
	s_mov_b32 m0, s2
	ds_read_b128 v[222:225], v156
	ds_read_b128 v[226:229], v156 offset:1024
	ds_read_b128 v[230:233], v156 offset:2048
	ds_read_b128 v[234:237], v156 offset:3072
	global_load_lds_dwordx4 v[154:155], off
	v_lshl_add_u64 v[154:155], v[238:239], 0, s[50:51]
	s_add_i32 m0, s2, 0x2000
	s_nop 0
	global_load_lds_dwordx4 v[154:155], off
	s_barrier
	s_waitcnt lgkmcnt(0)
	v_mfma_f32_16x16x32_bf16 v[116:119], v[222:225], v[170:173], v[116:119]
	v_mfma_f32_16x16x32_bf16 v[112:115], v[230:233], v[170:173], v[112:115]
	v_mfma_f32_16x16x32_bf16 v[100:103], v[222:225], v[178:181], v[100:103]
	v_mfma_f32_16x16x32_bf16 v[96:99], v[230:233], v[178:181], v[96:99]
	v_mfma_f32_16x16x32_bf16 v[84:87], v[222:225], v[186:189], v[84:87]
	v_mfma_f32_16x16x32_bf16 v[80:83], v[230:233], v[186:189], v[80:83]
	v_mfma_f32_16x16x32_bf16 v[68:71], v[222:225], v[214:217], v[68:71]
	v_mfma_f32_16x16x32_bf16 v[64:67], v[230:233], v[214:217], v[64:67]
	v_mfma_f32_16x16x32_bf16 v[116:119], v[226:229], v[174:177], v[116:119]
	v_mfma_f32_16x16x32_bf16 v[112:115], v[234:237], v[174:177], v[112:115]
	v_mfma_f32_16x16x32_bf16 v[100:103], v[226:229], v[182:185], v[100:103]
	v_mfma_f32_16x16x32_bf16 v[96:99], v[234:237], v[182:185], v[96:99]
	v_mfma_f32_16x16x32_bf16 v[84:87], v[226:229], v[206:209], v[84:87]
	v_mfma_f32_16x16x32_bf16 v[80:83], v[234:237], v[206:209], v[80:83]
	v_mfma_f32_16x16x32_bf16 v[68:71], v[226:229], v[218:221], v[68:71]
	v_mfma_f32_16x16x32_bf16 v[64:67], v[234:237], v[218:221], v[64:67]
	s_mov_b32 m0, s79
	v_lshl_add_u64 v[154:155], v[240:241], 0, s[50:51]
	s_barrier
	ds_read_b128 v[170:173], v149 offset:49152
	ds_read_b128 v[174:177], v149 offset:50176
	ds_read_b128 v[178:181], v149 offset:51200
	ds_read_b128 v[182:185], v149 offset:52224
	ds_read_b128 v[186:189], v149 offset:53248
	ds_read_b128 v[206:209], v149 offset:54272
	ds_read_b128 v[214:217], v149 offset:55296
	ds_read_b128 v[218:221], v149 offset:56320
	global_load_lds_dwordx4 v[154:155], off
	v_lshl_add_u64 v[154:155], v[242:243], 0, s[50:51]
	s_mov_b32 m0, s82
	s_nop 0
	global_load_lds_dwordx4 v[154:155], off
	s_barrier
	s_waitcnt lgkmcnt(0)
	v_mfma_f32_16x16x32_bf16 v[60:63], v[136:139], v[170:173], v[60:63]
	v_mfma_f32_16x16x32_bf16 v[56:59], v[162:165], v[170:173], v[56:59]
	v_mfma_f32_16x16x32_bf16 v[44:47], v[136:139], v[178:181], v[44:47]
	v_mfma_f32_16x16x32_bf16 v[40:43], v[162:165], v[178:181], v[40:43]
	v_mfma_f32_16x16x32_bf16 v[28:31], v[136:139], v[186:189], v[28:31]
	v_mfma_f32_16x16x32_bf16 v[24:27], v[162:165], v[186:189], v[24:27]
	v_mfma_f32_16x16x32_bf16 v[12:15], v[136:139], v[214:217], v[12:15]
	v_mfma_f32_16x16x32_bf16 v[8:11], v[162:165], v[214:217], v[8:11]
	v_mfma_f32_16x16x32_bf16 v[60:63], v[150:153], v[174:177], v[60:63]
	v_mfma_f32_16x16x32_bf16 v[56:59], v[166:169], v[174:177], v[56:59]
	v_mfma_f32_16x16x32_bf16 v[44:47], v[150:153], v[182:185], v[44:47]
	v_mfma_f32_16x16x32_bf16 v[40:43], v[166:169], v[182:185], v[40:43]
	v_mfma_f32_16x16x32_bf16 v[28:31], v[150:153], v[206:209], v[28:31]
	v_mfma_f32_16x16x32_bf16 v[24:27], v[166:169], v[206:209], v[24:27]
	v_mfma_f32_16x16x32_bf16 v[12:15], v[150:153], v[218:221], v[12:15]
	v_mfma_f32_16x16x32_bf16 v[8:11], v[166:169], v[218:221], v[8:11]
	s_barrier
	s_add_u32 s2, s42, 0x40080
	s_addc_u32 s3, s43, 0
	s_add_i32 s21, s61, s35
	v_lshl_add_u64 v[136:137], s[2:3], 0, v[130:131]
	s_mov_b32 m0, s21
	s_nop 0
	global_load_lds_dwordx4 v[136:137], off
	v_lshl_add_u64 v[136:137], s[2:3], 0, v[128:129]
	s_add_i32 m0, s21, 0x2000
	s_nop 0
	global_load_lds_dwordx4 v[136:137], off
	s_waitcnt vmcnt(6)
	s_barrier
	v_mfma_f32_16x16x32_bf16 v[52:55], v[222:225], v[170:173], v[52:55]
	v_mfma_f32_16x16x32_bf16 v[48:51], v[230:233], v[170:173], v[48:51]
	v_mfma_f32_16x16x32_bf16 v[36:39], v[222:225], v[178:181], v[36:39]
	v_mfma_f32_16x16x32_bf16 v[32:35], v[230:233], v[178:181], v[32:35]
	v_mfma_f32_16x16x32_bf16 v[20:23], v[222:225], v[186:189], v[20:23]
	v_mfma_f32_16x16x32_bf16 v[16:19], v[230:233], v[186:189], v[16:19]
	v_mfma_f32_16x16x32_bf16 v[4:7], v[222:225], v[214:217], v[4:7]
	v_mfma_f32_16x16x32_bf16 v[0:3], v[230:233], v[214:217], v[0:3]
	v_mfma_f32_16x16x32_bf16 v[52:55], v[226:229], v[174:177], v[52:55]
	v_mfma_f32_16x16x32_bf16 v[48:51], v[234:237], v[174:177], v[48:51]
	v_mfma_f32_16x16x32_bf16 v[36:39], v[226:229], v[182:185], v[36:39]
	v_mfma_f32_16x16x32_bf16 v[32:35], v[234:237], v[182:185], v[32:35]
	v_mfma_f32_16x16x32_bf16 v[20:23], v[226:229], v[206:209], v[20:23]
	v_mfma_f32_16x16x32_bf16 v[16:19], v[234:237], v[206:209], v[16:19]
	v_mfma_f32_16x16x32_bf16 v[4:7], v[226:229], v[218:221], v[4:7]
	v_mfma_f32_16x16x32_bf16 v[0:3], v[234:237], v[218:221], v[0:3]
	s_add_i32 s60, s60, 2
	s_add_u32 s46, s46, 0x100
	s_addc_u32 s47, s47, 0
	s_add_u32 s6, s6, 0x100
	s_addc_u32 s7, s7, 0
	s_cmp_gt_u32 s60, 13
	s_barrier
	s_cbranch_scc0 .LBB0_326

.LBB0_513:
	s_add_i32 s82, s84, -2
	s_add_u32 s83, s6, 0x100
	s_addc_u32 vcc_lo, s7, 0
	s_add_u32 s6, s60, 0x80
	s_addc_u32 s7, s61, 0
	s_mov_b32 s2, 0
	s_add_i32 vcc_hi, s2, 2
	s_add_u32 s21, s6, 0x80
	s_addc_u32 s3, s7, 0
	s_add_i32 s74, 0, 0x10000
	v_add_u32_e32 v140, s74, v161
	ds_read_b128 v[128:131], v140
	ds_read_b128 v[132:135], v140 offset:1024
	ds_read_b128 v[136:139], v140 offset:2048
	ds_read_b128 v[140:143], v140 offset:3072
	s_cmp_eq_u32 s82, s2
	s_cselect_b32 s2, s80, s21
	s_cselect_b32 s3, s81, s3
	s_cselect_b32 s61, s39, vcc_lo
	s_cselect_b32 s60, s38, s83
	v_lshl_add_u64 v[206:207], s[6:7], 0, v[168:169]
	s_add_i32 m0, s88, 0xc000
	ds_read_b128 v[144:147], v214
	ds_read_b128 v[148:151], v214 offset:1024
	ds_read_b128 v[152:155], v214 offset:2048
	ds_read_b128 v[170:173], v214 offset:3072
	ds_read_b128 v[174:177], v214 offset:4096
	ds_read_b128 v[178:181], v214 offset:5120
	ds_read_b128 v[182:185], v214 offset:6144
	ds_read_b128 v[186:189], v214 offset:7168
	global_load_lds_dwordx4 v[206:207], off
	v_lshl_add_u64 v[206:207], s[6:7], 0, v[166:167]
	s_add_i32 m0, s88, 0xe000
	s_nop 0
	global_load_lds_dwordx4 v[206:207], off
	s_waitcnt lgkmcnt(8)
	s_barrier
	s_waitcnt lgkmcnt(0)
	v_mfma_f32_16x16x32_bf16 v[124:127], v[128:131], v[144:147], 0
	v_mfma_f32_16x16x32_bf16 v[120:123], v[136:139], v[144:147], 0
	v_mfma_f32_16x16x32_bf16 v[116:119], v[128:131], v[152:155], 0
	v_mfma_f32_16x16x32_bf16 v[108:111], v[136:139], v[152:155], 0
	v_mfma_f32_16x16x32_bf16 v[100:103], v[128:131], v[174:177], 0
	v_mfma_f32_16x16x32_bf16 v[92:95], v[136:139], v[174:177], 0
	v_mfma_f32_16x16x32_bf16 v[84:87], v[128:131], v[182:185], 0
	v_mfma_f32_16x16x32_bf16 v[76:79], v[136:139], v[182:185], 0
	v_mfma_f32_16x16x32_bf16 v[124:127], v[132:135], v[148:151], v[124:127]
	v_mfma_f32_16x16x32_bf16 v[120:123], v[140:143], v[148:151], v[120:123]
	v_mfma_f32_16x16x32_bf16 v[116:119], v[132:135], v[170:173], v[116:119]
	v_mfma_f32_16x16x32_bf16 v[108:111], v[140:143], v[170:173], v[108:111]
	v_mfma_f32_16x16x32_bf16 v[100:103], v[132:135], v[178:181], v[100:103]
	v_mfma_f32_16x16x32_bf16 v[92:95], v[140:143], v[178:181], v[92:95]
	v_mfma_f32_16x16x32_bf16 v[84:87], v[132:135], v[186:189], v[84:87]
	v_mfma_f32_16x16x32_bf16 v[76:79], v[140:143], v[186:189], v[76:79]
	s_barrier
	s_add_i32 s21, 0, 0x14000
	s_add_i32 s74, s74, s53
	v_add_u32_e32 v215, s21, v161
	v_lshl_add_u64 v[228:229], s[60:61], 0, v[156:157]
	s_mov_b32 m0, s74
	ds_read_b128 v[206:209], v215
	ds_read_b128 v[216:219], v215 offset:1024
	ds_read_b128 v[220:223], v215 offset:2048
	ds_read_b128 v[224:227], v215 offset:3072
	global_load_lds_dwordx4 v[228:229], off
	v_lshl_add_u64 v[230:231], s[60:61], 0, v[162:163]
	s_add_i32 m0, s74, 0x2000
	s_nop 0
	global_load_lds_dwordx4 v[230:231], off
	s_barrier
	s_waitcnt lgkmcnt(0)
	v_mfma_f32_16x16x32_bf16 v[112:115], v[206:209], v[144:147], 0
	v_mfma_f32_16x16x32_bf16 v[104:107], v[220:223], v[144:147], 0
	v_mfma_f32_16x16x32_bf16 v[96:99], v[206:209], v[152:155], 0
	v_mfma_f32_16x16x32_bf16 v[88:91], v[220:223], v[152:155], 0
	v_mfma_f32_16x16x32_bf16 v[80:83], v[206:209], v[174:177], 0
	v_mfma_f32_16x16x32_bf16 v[72:75], v[220:223], v[174:177], 0
	v_mfma_f32_16x16x32_bf16 v[68:71], v[206:209], v[182:185], 0
	v_mfma_f32_16x16x32_bf16 v[64:67], v[220:223], v[182:185], 0
	v_mfma_f32_16x16x32_bf16 v[112:115], v[216:219], v[148:151], v[112:115]
	v_mfma_f32_16x16x32_bf16 v[104:107], v[224:227], v[148:151], v[104:107]
	v_mfma_f32_16x16x32_bf16 v[96:99], v[216:219], v[170:173], v[96:99]
	v_mfma_f32_16x16x32_bf16 v[88:91], v[224:227], v[170:173], v[88:91]
	v_mfma_f32_16x16x32_bf16 v[80:83], v[216:219], v[178:181], v[80:83]
	v_mfma_f32_16x16x32_bf16 v[72:75], v[224:227], v[178:181], v[72:75]
	v_mfma_f32_16x16x32_bf16 v[68:71], v[216:219], v[186:189], v[68:71]
	v_mfma_f32_16x16x32_bf16 v[64:67], v[224:227], v[186:189], v[64:67]
	s_mov_b32 m0, s88
	v_lshl_add_u64 v[232:233], s[2:3], 0, v[156:157]
	s_barrier
	ds_read_b128 v[144:147], v214 offset:16384
	ds_read_b128 v[148:151], v214 offset:17408
	ds_read_b128 v[152:155], v214 offset:18432
	ds_read_b128 v[170:173], v214 offset:19456
	ds_read_b128 v[174:177], v214 offset:20480
	ds_read_b128 v[178:181], v214 offset:21504
	ds_read_b128 v[182:185], v214 offset:22528
	ds_read_b128 v[186:189], v214 offset:23552
	global_load_lds_dwordx4 v[232:233], off
	v_lshl_add_u64 v[234:235], s[2:3], 0, v[162:163]
	s_mov_b32 m0, s89
	s_nop 0
	global_load_lds_dwordx4 v[234:235], off
	s_barrier
	s_waitcnt lgkmcnt(0)
	v_mfma_f32_16x16x32_bf16 v[60:63], v[128:131], v[144:147], 0
	v_mfma_f32_16x16x32_bf16 v[56:59], v[136:139], v[144:147], 0
	v_mfma_f32_16x16x32_bf16 v[52:55], v[128:131], v[152:155], 0
	v_mfma_f32_16x16x32_bf16 v[44:47], v[136:139], v[152:155], 0
	v_mfma_f32_16x16x32_bf16 v[36:39], v[128:131], v[174:177], 0
	v_mfma_f32_16x16x32_bf16 v[28:31], v[136:139], v[174:177], 0
	v_mfma_f32_16x16x32_bf16 v[20:23], v[128:131], v[182:185], 0
	v_mfma_f32_16x16x32_bf16 v[12:15], v[136:139], v[182:185], 0
	v_mfma_f32_16x16x32_bf16 v[60:63], v[132:135], v[148:151], v[60:63]
	v_mfma_f32_16x16x32_bf16 v[56:59], v[140:143], v[148:151], v[56:59]
	v_mfma_f32_16x16x32_bf16 v[52:55], v[132:135], v[170:173], v[52:55]
	v_mfma_f32_16x16x32_bf16 v[44:47], v[140:143], v[170:173], v[44:47]
	v_mfma_f32_16x16x32_bf16 v[36:39], v[132:135], v[178:181], v[36:39]
	v_mfma_f32_16x16x32_bf16 v[28:31], v[140:143], v[178:181], v[28:31]
	v_mfma_f32_16x16x32_bf16 v[20:23], v[132:135], v[186:189], v[20:23]
	v_mfma_f32_16x16x32_bf16 v[12:15], v[140:143], v[186:189], v[12:15]
	s_barrier
	s_add_u32 s60, s60, s54
	s_addc_u32 s61, s61, 0
	s_add_i32 s21, s21, s53
	v_lshl_add_u64 v[236:237], s[60:61], 0, v[156:157]
	s_mov_b32 m0, s21
	v_lshl_add_u64 v[238:239], s[60:61], 0, v[162:163]
	global_load_lds_dwordx4 v[236:237], off
	s_add_i32 m0, s21, 0x2000
	s_nop 0
	global_load_lds_dwordx4 v[238:239], off
	s_waitcnt vmcnt(6)
	s_barrier
	v_mfma_f32_16x16x32_bf16 v[48:51], v[206:209], v[144:147], 0
	v_mfma_f32_16x16x32_bf16 v[40:43], v[220:223], v[144:147], 0
	v_mfma_f32_16x16x32_bf16 v[32:35], v[206:209], v[152:155], 0
	v_mfma_f32_16x16x32_bf16 v[24:27], v[220:223], v[152:155], 0
	v_mfma_f32_16x16x32_bf16 v[16:19], v[206:209], v[174:177], 0
	v_mfma_f32_16x16x32_bf16 v[8:11], v[220:223], v[174:177], 0
	v_mfma_f32_16x16x32_bf16 v[4:7], v[206:209], v[182:185], 0
	v_mfma_f32_16x16x32_bf16 v[0:3], v[220:223], v[182:185], 0
	v_mfma_f32_16x16x32_bf16 v[48:51], v[216:219], v[148:151], v[48:51]
	v_mfma_f32_16x16x32_bf16 v[40:43], v[224:227], v[148:151], v[40:43]
	v_mfma_f32_16x16x32_bf16 v[32:35], v[216:219], v[170:173], v[32:35]
	v_mfma_f32_16x16x32_bf16 v[24:27], v[224:227], v[170:173], v[24:27]
	v_mfma_f32_16x16x32_bf16 v[16:19], v[216:219], v[178:181], v[16:19]
	v_mfma_f32_16x16x32_bf16 v[8:11], v[224:227], v[178:181], v[8:11]
	v_mfma_f32_16x16x32_bf16 v[4:7], v[216:219], v[186:189], v[4:7]
	v_mfma_f32_16x16x32_bf16 v[0:3], v[224:227], v[186:189], v[0:3]
	s_add_i32 s21, 0, 0x18000
	v_add_u32_e32 v140, s21, v161
	s_barrier
	ds_read_b128 v[128:131], v140
	ds_read_b128 v[132:135], v140 offset:1024
	ds_read_b128 v[136:139], v140 offset:2048
	ds_read_b128 v[140:143], v140 offset:3072
	s_add_u32 s2, s2, s54
	s_addc_u32 s3, s3, 0
	s_mov_b32 m0, s94
	v_lshl_add_u64 v[206:207], s[2:3], 0, v[156:157]
	ds_read_b128 v[144:147], v214 offset:32768
	ds_read_b128 v[148:151], v214 offset:33792
	ds_read_b128 v[152:155], v214 offset:34816
	ds_read_b128 v[170:173], v214 offset:35840
	ds_read_b128 v[174:177], v214 offset:36864
	ds_read_b128 v[178:181], v214 offset:37888
	ds_read_b128 v[182:185], v214 offset:38912
	ds_read_b128 v[186:189], v214 offset:39936
	global_load_lds_dwordx4 v[206:207], off
	v_lshl_add_u64 v[206:207], s[2:3], 0, v[162:163]
	s_mov_b32 m0, s95
	s_nop 0
	global_load_lds_dwordx4 v[206:207], off
	s_waitcnt lgkmcnt(8)
	s_barrier
	s_waitcnt lgkmcnt(0)
	v_mfma_f32_16x16x32_bf16 v[124:127], v[128:131], v[144:147], v[124:127]
	v_mfma_f32_16x16x32_bf16 v[120:123], v[136:139], v[144:147], v[120:123]
	v_mfma_f32_16x16x32_bf16 v[116:119], v[128:131], v[152:155], v[116:119]
	v_mfma_f32_16x16x32_bf16 v[108:111], v[136:139], v[152:155], v[108:111]
	v_mfma_f32_16x16x32_bf16 v[100:103], v[128:131], v[174:177], v[100:103]
	v_mfma_f32_16x16x32_bf16 v[92:95], v[136:139], v[174:177], v[92:95]
	v_mfma_f32_16x16x32_bf16 v[84:87], v[128:131], v[182:185], v[84:87]
	v_mfma_f32_16x16x32_bf16 v[76:79], v[136:139], v[182:185], v[76:79]
	v_mfma_f32_16x16x32_bf16 v[124:127], v[132:135], v[148:151], v[124:127]
	v_mfma_f32_16x16x32_bf16 v[120:123], v[140:143], v[148:151], v[120:123]
	v_mfma_f32_16x16x32_bf16 v[116:119], v[132:135], v[170:173], v[116:119]
	v_mfma_f32_16x16x32_bf16 v[108:111], v[140:143], v[170:173], v[108:111]
	v_mfma_f32_16x16x32_bf16 v[100:103], v[132:135], v[178:181], v[100:103]
	v_mfma_f32_16x16x32_bf16 v[92:95], v[140:143], v[178:181], v[92:95]
	v_mfma_f32_16x16x32_bf16 v[84:87], v[132:135], v[186:189], v[84:87]
	v_mfma_f32_16x16x32_bf16 v[76:79], v[140:143], v[186:189], v[76:79]
	s_barrier
	s_add_i32 s2, 0, 0x1c000
	s_add_i32 s3, s21, s53
	v_add_u32_e32 v215, s2, v161
	v_lshl_add_u64 v[228:229], v[228:229], 0, s[50:51]
	s_mov_b32 m0, s3
	ds_read_b128 v[206:209], v215
	ds_read_b128 v[216:219], v215 offset:1024
	ds_read_b128 v[220:223], v215 offset:2048
	ds_read_b128 v[224:227], v215 offset:3072
	global_load_lds_dwordx4 v[228:229], off
	v_lshl_add_u64 v[228:229], v[230:231], 0, s[50:51]
	s_add_i32 m0, s3, 0x2000
	s_nop 0
	global_load_lds_dwordx4 v[228:229], off
	s_barrier
	s_waitcnt lgkmcnt(0)
	v_mfma_f32_16x16x32_bf16 v[112:115], v[206:209], v[144:147], v[112:115]
	v_mfma_f32_16x16x32_bf16 v[104:107], v[220:223], v[144:147], v[104:107]
	v_mfma_f32_16x16x32_bf16 v[96:99], v[206:209], v[152:155], v[96:99]
	v_mfma_f32_16x16x32_bf16 v[88:91], v[220:223], v[152:155], v[88:91]
	v_mfma_f32_16x16x32_bf16 v[80:83], v[206:209], v[174:177], v[80:83]
	v_mfma_f32_16x16x32_bf16 v[72:75], v[220:223], v[174:177], v[72:75]
	v_mfma_f32_16x16x32_bf16 v[68:71], v[206:209], v[182:185], v[68:71]
	v_mfma_f32_16x16x32_bf16 v[64:67], v[220:223], v[182:185], v[64:67]
	v_mfma_f32_16x16x32_bf16 v[112:115], v[216:219], v[148:151], v[112:115]
	v_mfma_f32_16x16x32_bf16 v[104:107], v[224:227], v[148:151], v[104:107]
	v_mfma_f32_16x16x32_bf16 v[96:99], v[216:219], v[170:173], v[96:99]
	v_mfma_f32_16x16x32_bf16 v[88:91], v[224:227], v[170:173], v[88:91]
	v_mfma_f32_16x16x32_bf16 v[80:83], v[216:219], v[178:181], v[80:83]
	v_mfma_f32_16x16x32_bf16 v[72:75], v[224:227], v[178:181], v[72:75]
	v_mfma_f32_16x16x32_bf16 v[68:71], v[216:219], v[186:189], v[68:71]
	v_mfma_f32_16x16x32_bf16 v[64:67], v[224:227], v[186:189], v[64:67]
	s_mov_b32 m0, s96
	v_lshl_add_u64 v[228:229], v[232:233], 0, s[50:51]
	s_barrier
	ds_read_b128 v[144:147], v214 offset:49152
	ds_read_b128 v[148:151], v214 offset:50176
	ds_read_b128 v[152:155], v214 offset:51200
	ds_read_b128 v[170:173], v214 offset:52224
	ds_read_b128 v[174:177], v214 offset:53248
	ds_read_b128 v[178:181], v214 offset:54272
	ds_read_b128 v[182:185], v214 offset:55296
	ds_read_b128 v[186:189], v214 offset:56320
	global_load_lds_dwordx4 v[228:229], off
	v_lshl_add_u64 v[228:229], v[234:235], 0, s[50:51]
	s_mov_b32 m0, s97
	s_nop 0
	global_load_lds_dwordx4 v[228:229], off
	s_barrier
	s_waitcnt lgkmcnt(0)
	v_mfma_f32_16x16x32_bf16 v[60:63], v[128:131], v[144:147], v[60:63]
	v_mfma_f32_16x16x32_bf16 v[56:59], v[136:139], v[144:147], v[56:59]
	v_mfma_f32_16x16x32_bf16 v[52:55], v[128:131], v[152:155], v[52:55]
	v_mfma_f32_16x16x32_bf16 v[44:47], v[136:139], v[152:155], v[44:47]
	v_mfma_f32_16x16x32_bf16 v[36:39], v[128:131], v[174:177], v[36:39]
	v_mfma_f32_16x16x32_bf16 v[28:31], v[136:139], v[174:177], v[28:31]
	v_mfma_f32_16x16x32_bf16 v[20:23], v[128:131], v[182:185], v[20:23]
	v_mfma_f32_16x16x32_bf16 v[12:15], v[136:139], v[182:185], v[12:15]
	v_mfma_f32_16x16x32_bf16 v[60:63], v[132:135], v[148:151], v[60:63]
	v_mfma_f32_16x16x32_bf16 v[56:59], v[140:143], v[148:151], v[56:59]
	v_mfma_f32_16x16x32_bf16 v[52:55], v[132:135], v[170:173], v[52:55]
	v_mfma_f32_16x16x32_bf16 v[44:47], v[140:143], v[170:173], v[44:47]
	v_mfma_f32_16x16x32_bf16 v[36:39], v[132:135], v[178:181], v[36:39]
	v_mfma_f32_16x16x32_bf16 v[28:31], v[140:143], v[178:181], v[28:31]
	v_mfma_f32_16x16x32_bf16 v[20:23], v[132:135], v[186:189], v[20:23]
	v_mfma_f32_16x16x32_bf16 v[12:15], v[140:143], v[186:189], v[12:15]
	s_barrier
	s_add_i32 s2, s2, s53
	v_lshl_add_u64 v[128:129], v[236:237], 0, s[50:51]
	s_mov_b32 m0, s2
	s_nop 0
	global_load_lds_dwordx4 v[128:129], off
	v_lshl_add_u64 v[128:129], v[238:239], 0, s[50:51]
	s_add_i32 m0, s2, 0x2000
	s_nop 0
	global_load_lds_dwordx4 v[128:129], off
	s_waitcnt vmcnt(6)
	s_barrier
	v_mfma_f32_16x16x32_bf16 v[48:51], v[206:209], v[144:147], v[48:51]
	v_mfma_f32_16x16x32_bf16 v[40:43], v[220:223], v[144:147], v[40:43]
	v_mfma_f32_16x16x32_bf16 v[32:35], v[206:209], v[152:155], v[32:35]
	v_mfma_f32_16x16x32_bf16 v[24:27], v[220:223], v[152:155], v[24:27]
	v_mfma_f32_16x16x32_bf16 v[16:19], v[206:209], v[174:177], v[16:19]
	v_mfma_f32_16x16x32_bf16 v[8:11], v[220:223], v[174:177], v[8:11]
	v_mfma_f32_16x16x32_bf16 v[4:7], v[206:209], v[182:185], v[4:7]
	v_mfma_f32_16x16x32_bf16 v[0:3], v[220:223], v[182:185], v[0:3]
	v_mfma_f32_16x16x32_bf16 v[48:51], v[216:219], v[148:151], v[48:51]
	v_mfma_f32_16x16x32_bf16 v[40:43], v[224:227], v[148:151], v[40:43]
	v_mfma_f32_16x16x32_bf16 v[32:35], v[216:219], v[170:173], v[32:35]
	v_mfma_f32_16x16x32_bf16 v[24:27], v[224:227], v[170:173], v[24:27]
	v_mfma_f32_16x16x32_bf16 v[16:19], v[216:219], v[178:181], v[16:19]
	v_mfma_f32_16x16x32_bf16 v[8:11], v[224:227], v[178:181], v[8:11]
	v_mfma_f32_16x16x32_bf16 v[4:7], v[216:219], v[186:189], v[4:7]
	v_mfma_f32_16x16x32_bf16 v[0:3], v[224:227], v[186:189], v[0:3]
	s_add_u32 s83, s83, 0x100
	s_addc_u32 vcc_lo, vcc_lo, 0
	s_add_u32 s6, s6, 0x100
	s_addc_u32 s7, s7, 0
	s_cmp_ge_u32 vcc_hi, s84
	s_mov_b32 s2, vcc_hi
	s_barrier
	s_cbranch_scc1 .Lpost_514
.LBB0_514:
	s_add_i32 vcc_hi, s2, 2
	s_add_u32 s21, s6, 0x80
	s_addc_u32 s3, s7, 0
	s_add_i32 s74, 0, 0x10000
	v_add_u32_e32 v140, s74, v161
	ds_read_b128 v[128:131], v140
	ds_read_b128 v[132:135], v140 offset:1024
	ds_read_b128 v[136:139], v140 offset:2048
	ds_read_b128 v[140:143], v140 offset:3072
	s_cmp_eq_u32 s82, s2
	s_cselect_b32 s2, s80, s21
	s_cselect_b32 s3, s81, s3
	s_cselect_b32 s61, s39, vcc_lo
	s_cselect_b32 s60, s38, s83
	v_lshl_add_u64 v[206:207], s[6:7], 0, v[168:169]
	s_add_i32 m0, s88, 0xc000
	ds_read_b128 v[144:147], v214
	ds_read_b128 v[148:151], v214 offset:1024
	ds_read_b128 v[152:155], v214 offset:2048
	ds_read_b128 v[170:173], v214 offset:3072
	ds_read_b128 v[174:177], v214 offset:4096
	ds_read_b128 v[178:181], v214 offset:5120
	ds_read_b128 v[182:185], v214 offset:6144
	ds_read_b128 v[186:189], v214 offset:7168
	global_load_lds_dwordx4 v[206:207], off
	v_lshl_add_u64 v[206:207], s[6:7], 0, v[166:167]
	s_add_i32 m0, s88, 0xe000
	s_nop 0
	global_load_lds_dwordx4 v[206:207], off
	s_waitcnt lgkmcnt(8)
	s_barrier
	s_waitcnt lgkmcnt(0)
	v_mfma_f32_16x16x32_bf16 v[124:127], v[128:131], v[144:147], v[124:127]
	v_mfma_f32_16x16x32_bf16 v[120:123], v[136:139], v[144:147], v[120:123]
	v_mfma_f32_16x16x32_bf16 v[116:119], v[128:131], v[152:155], v[116:119]
	v_mfma_f32_16x16x32_bf16 v[108:111], v[136:139], v[152:155], v[108:111]
	v_mfma_f32_16x16x32_bf16 v[100:103], v[128:131], v[174:177], v[100:103]
	v_mfma_f32_16x16x32_bf16 v[92:95], v[136:139], v[174:177], v[92:95]
	v_mfma_f32_16x16x32_bf16 v[84:87], v[128:131], v[182:185], v[84:87]
	v_mfma_f32_16x16x32_bf16 v[76:79], v[136:139], v[182:185], v[76:79]
	v_mfma_f32_16x16x32_bf16 v[124:127], v[132:135], v[148:151], v[124:127]
	v_mfma_f32_16x16x32_bf16 v[120:123], v[140:143], v[148:151], v[120:123]
	v_mfma_f32_16x16x32_bf16 v[116:119], v[132:135], v[170:173], v[116:119]
	v_mfma_f32_16x16x32_bf16 v[108:111], v[140:143], v[170:173], v[108:111]
	v_mfma_f32_16x16x32_bf16 v[100:103], v[132:135], v[178:181], v[100:103]
	v_mfma_f32_16x16x32_bf16 v[92:95], v[140:143], v[178:181], v[92:95]
	v_mfma_f32_16x16x32_bf16 v[84:87], v[132:135], v[186:189], v[84:87]
	v_mfma_f32_16x16x32_bf16 v[76:79], v[140:143], v[186:189], v[76:79]
	s_barrier
	s_add_i32 s21, 0, 0x14000
	s_add_i32 s74, s74, s53
	v_add_u32_e32 v215, s21, v161
	v_lshl_add_u64 v[228:229], s[60:61], 0, v[156:157]
	s_mov_b32 m0, s74
	ds_read_b128 v[206:209], v215
	ds_read_b128 v[216:219], v215 offset:1024
	ds_read_b128 v[220:223], v215 offset:2048
	ds_read_b128 v[224:227], v215 offset:3072
	global_load_lds_dwordx4 v[228:229], off
	v_lshl_add_u64 v[230:231], s[60:61], 0, v[162:163]
	s_add_i32 m0, s74, 0x2000
	s_nop 0
	global_load_lds_dwordx4 v[230:231], off
	s_barrier
	s_waitcnt lgkmcnt(0)
	v_mfma_f32_16x16x32_bf16 v[112:115], v[206:209], v[144:147], v[112:115]
	v_mfma_f32_16x16x32_bf16 v[104:107], v[220:223], v[144:147], v[104:107]
	v_mfma_f32_16x16x32_bf16 v[96:99], v[206:209], v[152:155], v[96:99]
	v_mfma_f32_16x16x32_bf16 v[88:91], v[220:223], v[152:155], v[88:91]
	v_mfma_f32_16x16x32_bf16 v[80:83], v[206:209], v[174:177], v[80:83]
	v_mfma_f32_16x16x32_bf16 v[72:75], v[220:223], v[174:177], v[72:75]
	v_mfma_f32_16x16x32_bf16 v[68:71], v[206:209], v[182:185], v[68:71]
	v_mfma_f32_16x16x32_bf16 v[64:67], v[220:223], v[182:185], v[64:67]
	v_mfma_f32_16x16x32_bf16 v[112:115], v[216:219], v[148:151], v[112:115]
	v_mfma_f32_16x16x32_bf16 v[104:107], v[224:227], v[148:151], v[104:107]
	v_mfma_f32_16x16x32_bf16 v[96:99], v[216:219], v[170:173], v[96:99]
	v_mfma_f32_16x16x32_bf16 v[88:91], v[224:227], v[170:173], v[88:91]
	v_mfma_f32_16x16x32_bf16 v[80:83], v[216:219], v[178:181], v[80:83]
	v_mfma_f32_16x16x32_bf16 v[72:75], v[224:227], v[178:181], v[72:75]
	v_mfma_f32_16x16x32_bf16 v[68:71], v[216:219], v[186:189], v[68:71]
	v_mfma_f32_16x16x32_bf16 v[64:67], v[224:227], v[186:189], v[64:67]
	s_mov_b32 m0, s88
	v_lshl_add_u64 v[232:233], s[2:3], 0, v[156:157]
	s_barrier
	ds_read_b128 v[144:147], v214 offset:16384
	ds_read_b128 v[148:151], v214 offset:17408
	ds_read_b128 v[152:155], v214 offset:18432
	ds_read_b128 v[170:173], v214 offset:19456
	ds_read_b128 v[174:177], v214 offset:20480
	ds_read_b128 v[178:181], v214 offset:21504
	ds_read_b128 v[182:185], v214 offset:22528
	ds_read_b128 v[186:189], v214 offset:23552
	global_load_lds_dwordx4 v[232:233], off
	v_lshl_add_u64 v[234:235], s[2:3], 0, v[162:163]
	s_mov_b32 m0, s89
	s_nop 0
	global_load_lds_dwordx4 v[234:235], off
	s_barrier
	s_waitcnt lgkmcnt(0)
	v_mfma_f32_16x16x32_bf16 v[60:63], v[128:131], v[144:147], v[60:63]
	v_mfma_f32_16x16x32_bf16 v[56:59], v[136:139], v[144:147], v[56:59]
	v_mfma_f32_16x16x32_bf16 v[52:55], v[128:131], v[152:155], v[52:55]
	v_mfma_f32_16x16x32_bf16 v[44:47], v[136:139], v[152:155], v[44:47]
	v_mfma_f32_16x16x32_bf16 v[36:39], v[128:131], v[174:177], v[36:39]
	v_mfma_f32_16x16x32_bf16 v[28:31], v[136:139], v[174:177], v[28:31]
	v_mfma_f32_16x16x32_bf16 v[20:23], v[128:131], v[182:185], v[20:23]
	v_mfma_f32_16x16x32_bf16 v[12:15], v[136:139], v[182:185], v[12:15]
	v_mfma_f32_16x16x32_bf16 v[60:63], v[132:135], v[148:151], v[60:63]
	v_mfma_f32_16x16x32_bf16 v[56:59], v[140:143], v[148:151], v[56:59]
	v_mfma_f32_16x16x32_bf16 v[52:55], v[132:135], v[170:173], v[52:55]
	v_mfma_f32_16x16x32_bf16 v[44:47], v[140:143], v[170:173], v[44:47]
	v_mfma_f32_16x16x32_bf16 v[36:39], v[132:135], v[178:181], v[36:39]
	v_mfma_f32_16x16x32_bf16 v[28:31], v[140:143], v[178:181], v[28:31]
	v_mfma_f32_16x16x32_bf16 v[20:23], v[132:135], v[186:189], v[20:23]
	v_mfma_f32_16x16x32_bf16 v[12:15], v[140:143], v[186:189], v[12:15]
	s_barrier
	s_add_u32 s60, s60, s54
	s_addc_u32 s61, s61, 0
	s_add_i32 s21, s21, s53
	v_lshl_add_u64 v[236:237], s[60:61], 0, v[156:157]
	s_mov_b32 m0, s21
	v_lshl_add_u64 v[238:239], s[60:61], 0, v[162:163]
	global_load_lds_dwordx4 v[236:237], off
	s_add_i32 m0, s21, 0x2000
	s_nop 0
	global_load_lds_dwordx4 v[238:239], off
	s_waitcnt vmcnt(6)
	s_barrier
	v_mfma_f32_16x16x32_bf16 v[48:51], v[206:209], v[144:147], v[48:51]
	v_mfma_f32_16x16x32_bf16 v[40:43], v[220:223], v[144:147], v[40:43]
	v_mfma_f32_16x16x32_bf16 v[32:35], v[206:209], v[152:155], v[32:35]
	v_mfma_f32_16x16x32_bf16 v[24:27], v[220:223], v[152:155], v[24:27]
	v_mfma_f32_16x16x32_bf16 v[16:19], v[206:209], v[174:177], v[16:19]
	v_mfma_f32_16x16x32_bf16 v[8:11], v[220:223], v[174:177], v[8:11]
	v_mfma_f32_16x16x32_bf16 v[4:7], v[206:209], v[182:185], v[4:7]
	v_mfma_f32_16x16x32_bf16 v[0:3], v[220:223], v[182:185], v[0:3]
	v_mfma_f32_16x16x32_bf16 v[48:51], v[216:219], v[148:151], v[48:51]
	v_mfma_f32_16x16x32_bf16 v[40:43], v[224:227], v[148:151], v[40:43]
	v_mfma_f32_16x16x32_bf16 v[32:35], v[216:219], v[170:173], v[32:35]
	v_mfma_f32_16x16x32_bf16 v[24:27], v[224:227], v[170:173], v[24:27]
	v_mfma_f32_16x16x32_bf16 v[16:19], v[216:219], v[178:181], v[16:19]
	v_mfma_f32_16x16x32_bf16 v[8:11], v[224:227], v[178:181], v[8:11]
	v_mfma_f32_16x16x32_bf16 v[4:7], v[216:219], v[186:189], v[4:7]
	v_mfma_f32_16x16x32_bf16 v[0:3], v[224:227], v[186:189], v[0:3]
	s_add_i32 s21, 0, 0x18000
	v_add_u32_e32 v140, s21, v161
	s_barrier
	ds_read_b128 v[128:131], v140
	ds_read_b128 v[132:135], v140 offset:1024
	ds_read_b128 v[136:139], v140 offset:2048
	ds_read_b128 v[140:143], v140 offset:3072
	s_add_u32 s2, s2, s54
	s_addc_u32 s3, s3, 0
	s_mov_b32 m0, s94
	v_lshl_add_u64 v[206:207], s[2:3], 0, v[156:157]
	ds_read_b128 v[144:147], v214 offset:32768
	ds_read_b128 v[148:151], v214 offset:33792
	ds_read_b128 v[152:155], v214 offset:34816
	ds_read_b128 v[170:173], v214 offset:35840
	ds_read_b128 v[174:177], v214 offset:36864
	ds_read_b128 v[178:181], v214 offset:37888
	ds_read_b128 v[182:185], v214 offset:38912
	ds_read_b128 v[186:189], v214 offset:39936
	global_load_lds_dwordx4 v[206:207], off
	v_lshl_add_u64 v[206:207], s[2:3], 0, v[162:163]
	s_mov_b32 m0, s95
	s_nop 0
	global_load_lds_dwordx4 v[206:207], off
	s_waitcnt lgkmcnt(8)
	s_barrier
	s_waitcnt lgkmcnt(0)
	v_mfma_f32_16x16x32_bf16 v[124:127], v[128:131], v[144:147], v[124:127]
	v_mfma_f32_16x16x32_bf16 v[120:123], v[136:139], v[144:147], v[120:123]
	v_mfma_f32_16x16x32_bf16 v[116:119], v[128:131], v[152:155], v[116:119]
	v_mfma_f32_16x16x32_bf16 v[108:111], v[136:139], v[152:155], v[108:111]
	v_mfma_f32_16x16x32_bf16 v[100:103], v[128:131], v[174:177], v[100:103]
	v_mfma_f32_16x16x32_bf16 v[92:95], v[136:139], v[174:177], v[92:95]
	v_mfma_f32_16x16x32_bf16 v[84:87], v[128:131], v[182:185], v[84:87]
	v_mfma_f32_16x16x32_bf16 v[76:79], v[136:139], v[182:185], v[76:79]
	v_mfma_f32_16x16x32_bf16 v[124:127], v[132:135], v[148:151], v[124:127]
	v_mfma_f32_16x16x32_bf16 v[120:123], v[140:143], v[148:151], v[120:123]
	v_mfma_f32_16x16x32_bf16 v[116:119], v[132:135], v[170:173], v[116:119]
	v_mfma_f32_16x16x32_bf16 v[108:111], v[140:143], v[170:173], v[108:111]
	v_mfma_f32_16x16x32_bf16 v[100:103], v[132:135], v[178:181], v[100:103]
	v_mfma_f32_16x16x32_bf16 v[92:95], v[140:143], v[178:181], v[92:95]
	v_mfma_f32_16x16x32_bf16 v[84:87], v[132:135], v[186:189], v[84:87]
	v_mfma_f32_16x16x32_bf16 v[76:79], v[140:143], v[186:189], v[76:79]
	s_barrier
	s_add_i32 s2, 0, 0x1c000
	s_add_i32 s3, s21, s53
	v_add_u32_e32 v215, s2, v161
	v_lshl_add_u64 v[228:229], v[228:229], 0, s[50:51]
	s_mov_b32 m0, s3
	ds_read_b128 v[206:209], v215
	ds_read_b128 v[216:219], v215 offset:1024
	ds_read_b128 v[220:223], v215 offset:2048
	ds_read_b128 v[224:227], v215 offset:3072
	global_load_lds_dwordx4 v[228:229], off
	v_lshl_add_u64 v[228:229], v[230:231], 0, s[50:51]
	s_add_i32 m0, s3, 0x2000
	s_nop 0
	global_load_lds_dwordx4 v[228:229], off
	s_barrier
	s_waitcnt lgkmcnt(0)
	v_mfma_f32_16x16x32_bf16 v[112:115], v[206:209], v[144:147], v[112:115]
	v_mfma_f32_16x16x32_bf16 v[104:107], v[220:223], v[144:147], v[104:107]
	v_mfma_f32_16x16x32_bf16 v[96:99], v[206:209], v[152:155], v[96:99]
	v_mfma_f32_16x16x32_bf16 v[88:91], v[220:223], v[152:155], v[88:91]
	v_mfma_f32_16x16x32_bf16 v[80:83], v[206:209], v[174:177], v[80:83]
	v_mfma_f32_16x16x32_bf16 v[72:75], v[220:223], v[174:177], v[72:75]
	v_mfma_f32_16x16x32_bf16 v[68:71], v[206:209], v[182:185], v[68:71]
	v_mfma_f32_16x16x32_bf16 v[64:67], v[220:223], v[182:185], v[64:67]
	v_mfma_f32_16x16x32_bf16 v[112:115], v[216:219], v[148:151], v[112:115]
	v_mfma_f32_16x16x32_bf16 v[104:107], v[224:227], v[148:151], v[104:107]
	v_mfma_f32_16x16x32_bf16 v[96:99], v[216:219], v[170:173], v[96:99]
	v_mfma_f32_16x16x32_bf16 v[88:91], v[224:227], v[170:173], v[88:91]
	v_mfma_f32_16x16x32_bf16 v[80:83], v[216:219], v[178:181], v[80:83]
	v_mfma_f32_16x16x32_bf16 v[72:75], v[224:227], v[178:181], v[72:75]
	v_mfma_f32_16x16x32_bf16 v[68:71], v[216:219], v[186:189], v[68:71]
	v_mfma_f32_16x16x32_bf16 v[64:67], v[224:227], v[186:189], v[64:67]
	s_mov_b32 m0, s96
	v_lshl_add_u64 v[228:229], v[232:233], 0, s[50:51]
	s_barrier
	ds_read_b128 v[144:147], v214 offset:49152
	ds_read_b128 v[148:151], v214 offset:50176
	ds_read_b128 v[152:155], v214 offset:51200
	ds_read_b128 v[170:173], v214 offset:52224
	ds_read_b128 v[174:177], v214 offset:53248
	ds_read_b128 v[178:181], v214 offset:54272
	ds_read_b128 v[182:185], v214 offset:55296
	ds_read_b128 v[186:189], v214 offset:56320
	global_load_lds_dwordx4 v[228:229], off
	v_lshl_add_u64 v[228:229], v[234:235], 0, s[50:51]
	s_mov_b32 m0, s97
	s_nop 0
	global_load_lds_dwordx4 v[228:229], off
	s_barrier
	s_waitcnt lgkmcnt(0)
	v_mfma_f32_16x16x32_bf16 v[60:63], v[128:131], v[144:147], v[60:63]
	v_mfma_f32_16x16x32_bf16 v[56:59], v[136:139], v[144:147], v[56:59]
	v_mfma_f32_16x16x32_bf16 v[52:55], v[128:131], v[152:155], v[52:55]
	v_mfma_f32_16x16x32_bf16 v[44:47], v[136:139], v[152:155], v[44:47]
	v_mfma_f32_16x16x32_bf16 v[36:39], v[128:131], v[174:177], v[36:39]
	v_mfma_f32_16x16x32_bf16 v[28:31], v[136:139], v[174:177], v[28:31]
	v_mfma_f32_16x16x32_bf16 v[20:23], v[128:131], v[182:185], v[20:23]
	v_mfma_f32_16x16x32_bf16 v[12:15], v[136:139], v[182:185], v[12:15]
	v_mfma_f32_16x16x32_bf16 v[60:63], v[132:135], v[148:151], v[60:63]
	v_mfma_f32_16x16x32_bf16 v[56:59], v[140:143], v[148:151], v[56:59]
	v_mfma_f32_16x16x32_bf16 v[52:55], v[132:135], v[170:173], v[52:55]
	v_mfma_f32_16x16x32_bf16 v[44:47], v[140:143], v[170:173], v[44:47]
	v_mfma_f32_16x16x32_bf16 v[36:39], v[132:135], v[178:181], v[36:39]
	v_mfma_f32_16x16x32_bf16 v[28:31], v[140:143], v[178:181], v[28:31]
	v_mfma_f32_16x16x32_bf16 v[20:23], v[132:135], v[186:189], v[20:23]
	v_mfma_f32_16x16x32_bf16 v[12:15], v[140:143], v[186:189], v[12:15]
	s_barrier
	s_add_i32 s2, s2, s53
	v_lshl_add_u64 v[128:129], v[236:237], 0, s[50:51]
	s_mov_b32 m0, s2
	s_nop 0
	global_load_lds_dwordx4 v[128:129], off
	v_lshl_add_u64 v[128:129], v[238:239], 0, s[50:51]
	s_add_i32 m0, s2, 0x2000
	s_nop 0
	global_load_lds_dwordx4 v[128:129], off
	s_waitcnt vmcnt(6)
	s_barrier
	v_mfma_f32_16x16x32_bf16 v[48:51], v[206:209], v[144:147], v[48:51]
	v_mfma_f32_16x16x32_bf16 v[40:43], v[220:223], v[144:147], v[40:43]
	v_mfma_f32_16x16x32_bf16 v[32:35], v[206:209], v[152:155], v[32:35]
	v_mfma_f32_16x16x32_bf16 v[24:27], v[220:223], v[152:155], v[24:27]
	v_mfma_f32_16x16x32_bf16 v[16:19], v[206:209], v[174:177], v[16:19]
	v_mfma_f32_16x16x32_bf16 v[8:11], v[220:223], v[174:177], v[8:11]
	v_mfma_f32_16x16x32_bf16 v[4:7], v[206:209], v[182:185], v[4:7]
	v_mfma_f32_16x16x32_bf16 v[0:3], v[220:223], v[182:185], v[0:3]
	v_mfma_f32_16x16x32_bf16 v[48:51], v[216:219], v[148:151], v[48:51]
	v_mfma_f32_16x16x32_bf16 v[40:43], v[224:227], v[148:151], v[40:43]
	v_mfma_f32_16x16x32_bf16 v[32:35], v[216:219], v[170:173], v[32:35]
	v_mfma_f32_16x16x32_bf16 v[24:27], v[224:227], v[170:173], v[24:27]
	v_mfma_f32_16x16x32_bf16 v[16:19], v[216:219], v[178:181], v[16:19]
	v_mfma_f32_16x16x32_bf16 v[8:11], v[224:227], v[178:181], v[8:11]
	v_mfma_f32_16x16x32_bf16 v[4:7], v[216:219], v[186:189], v[4:7]
	v_mfma_f32_16x16x32_bf16 v[0:3], v[224:227], v[186:189], v[0:3]
	s_add_u32 s83, s83, 0x100
	s_addc_u32 vcc_lo, vcc_lo, 0
	s_add_u32 s6, s6, 0x100
	s_addc_u32 s7, s7, 0
	s_cmp_ge_u32 vcc_hi, s84
	s_mov_b32 s2, vcc_hi
	s_barrier
	s_cbranch_scc0 .LBB0_514

.LBB0_554:
	s_add_i32 s68, s68, 1
	s_mul_i32 s2, s68, s18
	s_add_i32 s10, s2, s20
	s_cmp_lt_i32 s10, s19
	s_cselect_b64 s[2:3], -1, 0
	s_cmp_ge_i32 s10, s19
	s_cselect_b64 s[38:39], -1, 0
	s_and_b64 s[6:7], s[2:3], exec
	s_cselect_b32 s6, s10, 0
	s_ashr_i32 s7, s6, 31
	s_lshr_b32 s7, s7, 29
	s_add_i32 s7, s6, s7
	s_ashr_i32 s10, s7, 3
	s_and_b32 s7, s7, -8
	s_sub_i32 s6, s6, s7
	s_cmp_lt_i32 s6, 0
	s_cselect_b32 s7, s61, s60
	s_mul_i32 s6, s7, s6
	s_add_i32 s10, s6, s10
	s_mul_hi_i32 s6, s10, 0x2e8ba2e9
	s_lshr_b32 s7, s6, 31
	s_ashr_i32 s6, s6, 4
	s_add_i32 s24, s6, s7
	s_lshl_b32 s25, s24, 2
	s_sub_i32 s6, s9, s25
	s_min_i32 s41, s6, 4
	s_abs_i32 s40, s41
	v_cvt_f32_u32_e32 v0, s40
	s_mov_b64 s[6:7], s[34:35]
	s_mov_b64 s[54:55], s[36:37]
	s_sub_i32 s35, 0, s40
	v_rcp_iflag_f32_e32 v0, v0
	s_mulk_i32 s24, 0x58
	s_sub_i32 s10, s10, s24
	s_abs_i32 s34, s10
	v_mul_f32_e32 v0, 0x4f7ffffe, v0
	v_cvt_u32_f32_e32 v0, v0
	s_xor_b32 s24, s10, s41
	s_ashr_i32 s24, s24, 31
	s_mov_b32 s73, -2
	v_readfirstlane_b32 s36, v0
	s_mul_i32 s35, s35, s36
	s_mul_hi_u32 s35, s36, s35
	s_add_i32 s36, s36, s35
	s_mul_hi_u32 s35, s34, s36
	s_mul_i32 s36, s35, s40
	s_sub_i32 s34, s34, s36
	s_add_i32 s36, s35, 1
	s_sub_i32 s37, s34, s40
	s_cmp_ge_u32 s34, s40
	s_cselect_b32 s35, s36, s35
	s_cselect_b32 s34, s37, s34
	s_add_i32 s36, s35, 1
	s_cmp_ge_u32 s34, s40
	s_cselect_b32 s34, s36, s35
	s_xor_b32 s34, s34, s24
	s_sub_i32 s40, s34, s24
	s_mul_i32 s24, s40, s41
	s_sub_i32 s10, s10, s24
	s_add_i32 s42, s25, s10
	s_ashr_i32 s43, s42, 31
	s_lshl_b64 s[24:25], s[42:43], 19
	s_add_u32 s34, s58, s24
	s_addc_u32 s35, s59, s25
	s_and_b64 s[24:25], s[2:3], exec
	s_cselect_b32 s10, s35, s7
	s_cselect_b32 s24, s34, s6
	s_ashr_i32 s41, s40, 31
	s_lshl_b64 s[36:37], s[40:41], 19
	s_add_u32 s36, s44, s36
	s_addc_u32 s37, s45, s37
	s_and_b64 s[2:3], s[2:3], exec
	s_cselect_b32 s25, s37, s55
	s_cselect_b32 s41, s36, s54
	s_add_u32 s43, s54, 0x100
	s_addc_u32 s69, s55, 0
	s_add_u32 s6, s6, 0x40080
	s_addc_u32 s7, s7, 0
	s_add_u32 s2, s6, 0xfffc0080
	s_addc_u32 s3, s7, -1
	s_add_i32 s77, 0, 0x10000
	v_add_u32_e32 v150, s77, v139
	ds_read_b128 v[134:137], v150
	ds_read_b128 v[142:145], v150 offset:1024
	ds_read_b128 v[146:149], v150 offset:2048
	ds_read_b128 v[150:153], v150 offset:3072
	s_cmp_eq_u32 s73, 12
	s_cselect_b32 s3, s10, s3
	s_cselect_b32 s2, s24, s2
	s_cselect_b32 s55, s25, s69
	s_cselect_b32 s54, s41, s43
	v_lshl_add_u64 v[154:155], s[6:7], 0, v[132:133]
	s_add_i32 m0, s47, 0xc000
	ds_read_b128 v[162:165], v141
	ds_read_b128 v[166:169], v141 offset:1024
	ds_read_b128 v[170:173], v141 offset:2048
	ds_read_b128 v[174:177], v141 offset:3072
	ds_read_b128 v[178:181], v141 offset:4096
	ds_read_b128 v[182:185], v141 offset:5120
	ds_read_b128 v[186:189], v141 offset:6144
	ds_read_b128 v[214:217], v141 offset:7168
	global_load_lds_dwordx4 v[154:155], off
	v_lshl_add_u64 v[154:155], s[6:7], 0, v[130:131]
	s_add_i32 m0, s47, 0xe000
	s_nop 0
	global_load_lds_dwordx4 v[154:155], off
	s_waitcnt lgkmcnt(8)
	s_barrier
	s_waitcnt lgkmcnt(0)
	v_mfma_f32_16x16x32_bf16 v[124:127], v[134:137], v[162:165], 0
	v_mfma_f32_16x16x32_bf16 v[116:119], v[146:149], v[162:165], 0
	v_mfma_f32_16x16x32_bf16 v[108:111], v[134:137], v[170:173], 0
	v_mfma_f32_16x16x32_bf16 v[100:103], v[146:149], v[170:173], 0
	v_mfma_f32_16x16x32_bf16 v[92:95], v[134:137], v[178:181], 0
	v_mfma_f32_16x16x32_bf16 v[84:87], v[146:149], v[178:181], 0
	v_mfma_f32_16x16x32_bf16 v[76:79], v[134:137], v[186:189], 0
	v_mfma_f32_16x16x32_bf16 v[68:71], v[146:149], v[186:189], 0
	v_mfma_f32_16x16x32_bf16 v[124:127], v[142:145], v[166:169], v[124:127]
	v_mfma_f32_16x16x32_bf16 v[116:119], v[150:153], v[166:169], v[116:119]
	v_mfma_f32_16x16x32_bf16 v[108:111], v[142:145], v[174:177], v[108:111]
	v_mfma_f32_16x16x32_bf16 v[100:103], v[150:153], v[174:177], v[100:103]
	v_mfma_f32_16x16x32_bf16 v[92:95], v[142:145], v[182:185], v[92:95]
	v_mfma_f32_16x16x32_bf16 v[84:87], v[150:153], v[182:185], v[84:87]
	v_mfma_f32_16x16x32_bf16 v[76:79], v[142:145], v[214:217], v[76:79]
	v_mfma_f32_16x16x32_bf16 v[68:71], v[150:153], v[214:217], v[68:71]
	s_barrier
	s_add_i32 s80, 0, 0x14000
	v_add_u32_e32 v154, s80, v139
	s_add_i32 s77, s77, s53
	ds_read_b128 v[218:221], v154
	ds_read_b128 v[222:225], v154 offset:1024
	ds_read_b128 v[226:229], v154 offset:2048
	ds_read_b128 v[230:233], v154 offset:3072
	v_lshl_add_u64 v[154:155], s[54:55], 0, v[156:157]
	s_mov_b32 m0, s77
	v_lshl_add_u64 v[206:207], s[54:55], 0, v[128:129]
	global_load_lds_dwordx4 v[154:155], off
	s_add_i32 m0, s77, 0x2000
	s_nop 0
	global_load_lds_dwordx4 v[206:207], off
	s_barrier
	s_waitcnt lgkmcnt(0)
	v_mfma_f32_16x16x32_bf16 v[120:123], v[218:221], v[162:165], 0
	v_mfma_f32_16x16x32_bf16 v[112:115], v[226:229], v[162:165], 0
	v_mfma_f32_16x16x32_bf16 v[104:107], v[218:221], v[170:173], 0
	v_mfma_f32_16x16x32_bf16 v[96:99], v[226:229], v[170:173], 0
	v_mfma_f32_16x16x32_bf16 v[88:91], v[218:221], v[178:181], 0
	v_mfma_f32_16x16x32_bf16 v[80:83], v[226:229], v[178:181], 0
	v_mfma_f32_16x16x32_bf16 v[72:75], v[218:221], v[186:189], 0
	v_mfma_f32_16x16x32_bf16 v[64:67], v[226:229], v[186:189], 0
	v_mfma_f32_16x16x32_bf16 v[120:123], v[222:225], v[166:169], v[120:123]
	v_mfma_f32_16x16x32_bf16 v[112:115], v[230:233], v[166:169], v[112:115]
	v_mfma_f32_16x16x32_bf16 v[104:107], v[222:225], v[174:177], v[104:107]
	v_mfma_f32_16x16x32_bf16 v[96:99], v[230:233], v[174:177], v[96:99]
	v_mfma_f32_16x16x32_bf16 v[88:91], v[222:225], v[182:185], v[88:91]
	v_mfma_f32_16x16x32_bf16 v[80:83], v[230:233], v[182:185], v[80:83]
	v_mfma_f32_16x16x32_bf16 v[72:75], v[222:225], v[214:217], v[72:75]
	v_mfma_f32_16x16x32_bf16 v[64:67], v[230:233], v[214:217], v[64:67]
	s_mov_b32 m0, s47
	v_lshl_add_u64 v[208:209], s[2:3], 0, v[156:157]
	s_barrier
	ds_read_b128 v[162:165], v141 offset:16384
	ds_read_b128 v[166:169], v141 offset:17408
	ds_read_b128 v[170:173], v141 offset:18432
	ds_read_b128 v[174:177], v141 offset:19456
	ds_read_b128 v[178:181], v141 offset:20480
	ds_read_b128 v[182:185], v141 offset:21504
	ds_read_b128 v[186:189], v141 offset:22528
	ds_read_b128 v[214:217], v141 offset:23552
	global_load_lds_dwordx4 v[208:209], off
	v_lshl_add_u64 v[234:235], s[2:3], 0, v[128:129]
	s_mov_b32 m0, s49
	s_nop 0
	global_load_lds_dwordx4 v[234:235], off
	s_barrier
	s_waitcnt lgkmcnt(0)
	v_mfma_f32_16x16x32_bf16 v[60:63], v[134:137], v[162:165], 0
	v_mfma_f32_16x16x32_bf16 v[52:55], v[146:149], v[162:165], 0
	v_mfma_f32_16x16x32_bf16 v[44:47], v[134:137], v[170:173], 0
	v_mfma_f32_16x16x32_bf16 v[36:39], v[146:149], v[170:173], 0
	v_mfma_f32_16x16x32_bf16 v[28:31], v[134:137], v[178:181], 0
	v_mfma_f32_16x16x32_bf16 v[20:23], v[146:149], v[178:181], 0
	v_mfma_f32_16x16x32_bf16 v[12:15], v[134:137], v[186:189], 0
	v_mfma_f32_16x16x32_bf16 v[4:7], v[146:149], v[186:189], 0
	v_mfma_f32_16x16x32_bf16 v[60:63], v[142:145], v[166:169], v[60:63]
	v_mfma_f32_16x16x32_bf16 v[52:55], v[150:153], v[166:169], v[52:55]
	v_mfma_f32_16x16x32_bf16 v[44:47], v[142:145], v[174:177], v[44:47]
	v_mfma_f32_16x16x32_bf16 v[36:39], v[150:153], v[174:177], v[36:39]
	v_mfma_f32_16x16x32_bf16 v[28:31], v[142:145], v[182:185], v[28:31]
	v_mfma_f32_16x16x32_bf16 v[20:23], v[150:153], v[182:185], v[20:23]
	v_mfma_f32_16x16x32_bf16 v[12:15], v[142:145], v[214:217], v[12:15]
	v_mfma_f32_16x16x32_bf16 v[4:7], v[150:153], v[214:217], v[4:7]
	s_barrier
	s_add_u32 s78, s54, 0x40000
	s_addc_u32 s79, s55, 0
	s_add_i32 s77, s80, s53
	v_lshl_add_u64 v[134:135], s[78:79], 0, v[156:157]
	s_mov_b32 m0, s77
	s_nop 0
	global_load_lds_dwordx4 v[134:135], off
	v_lshl_add_u64 v[134:135], s[78:79], 0, v[128:129]
	s_add_i32 m0, s77, 0x2000
	s_nop 0
	global_load_lds_dwordx4 v[134:135], off
	s_waitcnt vmcnt(6)
	s_barrier
	v_mfma_f32_16x16x32_bf16 v[56:59], v[218:221], v[162:165], 0
	v_mfma_f32_16x16x32_bf16 v[48:51], v[226:229], v[162:165], 0
	v_mfma_f32_16x16x32_bf16 v[40:43], v[218:221], v[170:173], 0
	v_mfma_f32_16x16x32_bf16 v[32:35], v[226:229], v[170:173], 0
	v_mfma_f32_16x16x32_bf16 v[24:27], v[218:221], v[178:181], 0
	v_mfma_f32_16x16x32_bf16 v[16:19], v[226:229], v[178:181], 0
	v_mfma_f32_16x16x32_bf16 v[8:11], v[218:221], v[186:189], 0
	v_mfma_f32_16x16x32_bf16 v[0:3], v[226:229], v[186:189], 0
	v_mfma_f32_16x16x32_bf16 v[56:59], v[222:225], v[166:169], v[56:59]
	v_mfma_f32_16x16x32_bf16 v[48:51], v[230:233], v[166:169], v[48:51]
	v_mfma_f32_16x16x32_bf16 v[40:43], v[222:225], v[174:177], v[40:43]
	v_mfma_f32_16x16x32_bf16 v[32:35], v[230:233], v[174:177], v[32:35]
	v_mfma_f32_16x16x32_bf16 v[24:27], v[222:225], v[182:185], v[24:27]
	v_mfma_f32_16x16x32_bf16 v[16:19], v[230:233], v[182:185], v[16:19]
	v_mfma_f32_16x16x32_bf16 v[8:11], v[222:225], v[214:217], v[8:11]
	v_mfma_f32_16x16x32_bf16 v[0:3], v[230:233], v[214:217], v[0:3]
	s_add_i32 s77, 0, 0x18000
	v_add_u32_e32 v150, s77, v139
	s_barrier
	ds_read_b128 v[134:137], v150
	ds_read_b128 v[142:145], v150 offset:1024
	ds_read_b128 v[146:149], v150 offset:2048
	ds_read_b128 v[150:153], v150 offset:3072
	s_add_u32 s2, s2, 0x40000
	s_addc_u32 s3, s3, 0
	s_mov_b32 m0, s62
	v_lshl_add_u64 v[218:219], s[2:3], 0, v[156:157]
	ds_read_b128 v[162:165], v141 offset:32768
	ds_read_b128 v[166:169], v141 offset:33792
	ds_read_b128 v[170:173], v141 offset:34816
	ds_read_b128 v[174:177], v141 offset:35840
	ds_read_b128 v[178:181], v141 offset:36864
	ds_read_b128 v[182:185], v141 offset:37888
	ds_read_b128 v[186:189], v141 offset:38912
	ds_read_b128 v[214:217], v141 offset:39936
	global_load_lds_dwordx4 v[218:219], off
	v_lshl_add_u64 v[218:219], s[2:3], 0, v[128:129]
	s_mov_b32 m0, s63
	s_nop 0
	global_load_lds_dwordx4 v[218:219], off
	s_waitcnt lgkmcnt(8)
	s_barrier
	s_waitcnt lgkmcnt(0)
	v_mfma_f32_16x16x32_bf16 v[124:127], v[134:137], v[162:165], v[124:127]
	v_mfma_f32_16x16x32_bf16 v[116:119], v[146:149], v[162:165], v[116:119]
	v_mfma_f32_16x16x32_bf16 v[108:111], v[134:137], v[170:173], v[108:111]
	v_mfma_f32_16x16x32_bf16 v[100:103], v[146:149], v[170:173], v[100:103]
	v_mfma_f32_16x16x32_bf16 v[92:95], v[134:137], v[178:181], v[92:95]
	v_mfma_f32_16x16x32_bf16 v[84:87], v[146:149], v[178:181], v[84:87]
	v_mfma_f32_16x16x32_bf16 v[76:79], v[134:137], v[186:189], v[76:79]
	v_mfma_f32_16x16x32_bf16 v[68:71], v[146:149], v[186:189], v[68:71]
	v_mfma_f32_16x16x32_bf16 v[124:127], v[142:145], v[166:169], v[124:127]
	v_mfma_f32_16x16x32_bf16 v[116:119], v[150:153], v[166:169], v[116:119]
	v_mfma_f32_16x16x32_bf16 v[108:111], v[142:145], v[174:177], v[108:111]
	v_mfma_f32_16x16x32_bf16 v[100:103], v[150:153], v[174:177], v[100:103]
	v_mfma_f32_16x16x32_bf16 v[92:95], v[142:145], v[182:185], v[92:95]
	v_mfma_f32_16x16x32_bf16 v[84:87], v[150:153], v[182:185], v[84:87]
	v_mfma_f32_16x16x32_bf16 v[76:79], v[142:145], v[214:217], v[76:79]
	v_mfma_f32_16x16x32_bf16 v[68:71], v[150:153], v[214:217], v[68:71]
	s_barrier
	s_add_i32 s78, 0, 0x1c000
	s_add_i32 s2, s77, s53
	v_add_u32_e32 v161, s78, v139
	v_lshl_add_u64 v[154:155], v[154:155], 0, s[50:51]
	s_mov_b32 m0, s2
	ds_read_b128 v[218:221], v161
	ds_read_b128 v[222:225], v161 offset:1024
	ds_read_b128 v[226:229], v161 offset:2048
	ds_read_b128 v[230:233], v161 offset:3072
	global_load_lds_dwordx4 v[154:155], off
	v_lshl_add_u64 v[154:155], v[206:207], 0, s[50:51]
	s_add_i32 m0, s2, 0x2000
	s_nop 0
	global_load_lds_dwordx4 v[154:155], off
	s_barrier
	s_waitcnt lgkmcnt(0)
	v_mfma_f32_16x16x32_bf16 v[120:123], v[218:221], v[162:165], v[120:123]
	v_mfma_f32_16x16x32_bf16 v[112:115], v[226:229], v[162:165], v[112:115]
	v_mfma_f32_16x16x32_bf16 v[104:107], v[218:221], v[170:173], v[104:107]
	v_mfma_f32_16x16x32_bf16 v[96:99], v[226:229], v[170:173], v[96:99]
	v_mfma_f32_16x16x32_bf16 v[88:91], v[218:221], v[178:181], v[88:91]
	v_mfma_f32_16x16x32_bf16 v[80:83], v[226:229], v[178:181], v[80:83]
	v_mfma_f32_16x16x32_bf16 v[72:75], v[218:221], v[186:189], v[72:75]
	v_mfma_f32_16x16x32_bf16 v[64:67], v[226:229], v[186:189], v[64:67]
	v_mfma_f32_16x16x32_bf16 v[120:123], v[222:225], v[166:169], v[120:123]
	v_mfma_f32_16x16x32_bf16 v[112:115], v[230:233], v[166:169], v[112:115]
	v_mfma_f32_16x16x32_bf16 v[104:107], v[222:225], v[174:177], v[104:107]
	v_mfma_f32_16x16x32_bf16 v[96:99], v[230:233], v[174:177], v[96:99]
	v_mfma_f32_16x16x32_bf16 v[88:91], v[222:225], v[182:185], v[88:91]
	v_mfma_f32_16x16x32_bf16 v[80:83], v[230:233], v[182:185], v[80:83]
	v_mfma_f32_16x16x32_bf16 v[72:75], v[222:225], v[214:217], v[72:75]
	v_mfma_f32_16x16x32_bf16 v[64:67], v[230:233], v[214:217], v[64:67]
	s_mov_b32 m0, s66
	v_lshl_add_u64 v[154:155], v[208:209], 0, s[50:51]
	s_barrier
	ds_read_b128 v[162:165], v141 offset:49152
	ds_read_b128 v[166:169], v141 offset:50176
	ds_read_b128 v[170:173], v141 offset:51200
	ds_read_b128 v[174:177], v141 offset:52224
	ds_read_b128 v[178:181], v141 offset:53248
	ds_read_b128 v[182:185], v141 offset:54272
	ds_read_b128 v[186:189], v141 offset:55296
	ds_read_b128 v[214:217], v141 offset:56320
	global_load_lds_dwordx4 v[154:155], off
	v_lshl_add_u64 v[154:155], v[234:235], 0, s[50:51]
	s_mov_b32 m0, s67
	s_nop 0
	global_load_lds_dwordx4 v[154:155], off
	s_barrier
	s_waitcnt lgkmcnt(0)
	v_mfma_f32_16x16x32_bf16 v[60:63], v[134:137], v[162:165], v[60:63]
	v_mfma_f32_16x16x32_bf16 v[52:55], v[146:149], v[162:165], v[52:55]
	v_mfma_f32_16x16x32_bf16 v[44:47], v[134:137], v[170:173], v[44:47]
	v_mfma_f32_16x16x32_bf16 v[36:39], v[146:149], v[170:173], v[36:39]
	v_mfma_f32_16x16x32_bf16 v[28:31], v[134:137], v[178:181], v[28:31]
	v_mfma_f32_16x16x32_bf16 v[20:23], v[146:149], v[178:181], v[20:23]
	v_mfma_f32_16x16x32_bf16 v[12:15], v[134:137], v[186:189], v[12:15]
	v_mfma_f32_16x16x32_bf16 v[4:7], v[146:149], v[186:189], v[4:7]
	v_mfma_f32_16x16x32_bf16 v[60:63], v[142:145], v[166:169], v[60:63]
	v_mfma_f32_16x16x32_bf16 v[52:55], v[150:153], v[166:169], v[52:55]
	v_mfma_f32_16x16x32_bf16 v[44:47], v[142:145], v[174:177], v[44:47]
	v_mfma_f32_16x16x32_bf16 v[36:39], v[150:153], v[174:177], v[36:39]
	v_mfma_f32_16x16x32_bf16 v[28:31], v[142:145], v[182:185], v[28:31]
	v_mfma_f32_16x16x32_bf16 v[20:23], v[150:153], v[182:185], v[20:23]
	v_mfma_f32_16x16x32_bf16 v[12:15], v[142:145], v[214:217], v[12:15]
	v_mfma_f32_16x16x32_bf16 v[4:7], v[150:153], v[214:217], v[4:7]
	s_barrier
	s_add_u32 s2, s54, 0x40080
	s_addc_u32 s3, s55, 0
	s_add_i32 s54, s78, s53
	v_lshl_add_u64 v[134:135], s[2:3], 0, v[156:157]
	s_mov_b32 m0, s54
	s_nop 0
	global_load_lds_dwordx4 v[134:135], off
	v_lshl_add_u64 v[134:135], s[2:3], 0, v[128:129]
	s_add_i32 m0, s54, 0x2000
	s_nop 0
	global_load_lds_dwordx4 v[134:135], off
	s_waitcnt vmcnt(6)
	s_barrier
	v_mfma_f32_16x16x32_bf16 v[56:59], v[218:221], v[162:165], v[56:59]
	v_mfma_f32_16x16x32_bf16 v[48:51], v[226:229], v[162:165], v[48:51]
	v_mfma_f32_16x16x32_bf16 v[40:43], v[218:221], v[170:173], v[40:43]
	v_mfma_f32_16x16x32_bf16 v[32:35], v[226:229], v[170:173], v[32:35]
	v_mfma_f32_16x16x32_bf16 v[24:27], v[218:221], v[178:181], v[24:27]
	v_mfma_f32_16x16x32_bf16 v[16:19], v[226:229], v[178:181], v[16:19]
	v_mfma_f32_16x16x32_bf16 v[8:11], v[218:221], v[186:189], v[8:11]
	v_mfma_f32_16x16x32_bf16 v[0:3], v[226:229], v[186:189], v[0:3]
	v_mfma_f32_16x16x32_bf16 v[56:59], v[222:225], v[166:169], v[56:59]
	v_mfma_f32_16x16x32_bf16 v[48:51], v[230:233], v[166:169], v[48:51]
	v_mfma_f32_16x16x32_bf16 v[40:43], v[222:225], v[174:177], v[40:43]
	v_mfma_f32_16x16x32_bf16 v[32:35], v[230:233], v[174:177], v[32:35]
	v_mfma_f32_16x16x32_bf16 v[24:27], v[222:225], v[182:185], v[24:27]
	v_mfma_f32_16x16x32_bf16 v[16:19], v[230:233], v[182:185], v[16:19]
	v_mfma_f32_16x16x32_bf16 v[8:11], v[222:225], v[214:217], v[8:11]
	v_mfma_f32_16x16x32_bf16 v[0:3], v[230:233], v[214:217], v[0:3]
	s_add_i32 s73, s73, 2
	s_add_u32 s43, s43, 0x100
	s_addc_u32 s69, s69, 0
	s_add_u32 s6, s6, 0x100
	s_addc_u32 s7, s7, 0
	s_cmp_gt_u32 s73, 13
	s_barrier
	s_cbranch_scc1 .Lpost_555
.LBB0_555:
	s_add_u32 s2, s6, 0xfffc0080
	s_addc_u32 s3, s7, -1
	s_add_i32 s77, 0, 0x10000
	v_add_u32_e32 v150, s77, v139
	ds_read_b128 v[134:137], v150
	ds_read_b128 v[142:145], v150 offset:1024
	ds_read_b128 v[146:149], v150 offset:2048
	ds_read_b128 v[150:153], v150 offset:3072
	s_cmp_eq_u32 s73, 12
	s_cselect_b32 s3, s10, s3
	s_cselect_b32 s2, s24, s2
	s_cselect_b32 s55, s25, s69
	s_cselect_b32 s54, s41, s43
	v_lshl_add_u64 v[154:155], s[6:7], 0, v[132:133]
	s_add_i32 m0, s47, 0xc000
	ds_read_b128 v[162:165], v141
	ds_read_b128 v[166:169], v141 offset:1024
	ds_read_b128 v[170:173], v141 offset:2048
	ds_read_b128 v[174:177], v141 offset:3072
	ds_read_b128 v[178:181], v141 offset:4096
	ds_read_b128 v[182:185], v141 offset:5120
	ds_read_b128 v[186:189], v141 offset:6144
	ds_read_b128 v[214:217], v141 offset:7168
	global_load_lds_dwordx4 v[154:155], off
	v_lshl_add_u64 v[154:155], s[6:7], 0, v[130:131]
	s_add_i32 m0, s47, 0xe000
	s_nop 0
	global_load_lds_dwordx4 v[154:155], off
	s_waitcnt lgkmcnt(8)
	s_barrier
	s_waitcnt lgkmcnt(0)
	v_mfma_f32_16x16x32_bf16 v[124:127], v[134:137], v[162:165], v[124:127]
	v_mfma_f32_16x16x32_bf16 v[116:119], v[146:149], v[162:165], v[116:119]
	v_mfma_f32_16x16x32_bf16 v[108:111], v[134:137], v[170:173], v[108:111]
	v_mfma_f32_16x16x32_bf16 v[100:103], v[146:149], v[170:173], v[100:103]
	v_mfma_f32_16x16x32_bf16 v[92:95], v[134:137], v[178:181], v[92:95]
	v_mfma_f32_16x16x32_bf16 v[84:87], v[146:149], v[178:181], v[84:87]
	v_mfma_f32_16x16x32_bf16 v[76:79], v[134:137], v[186:189], v[76:79]
	v_mfma_f32_16x16x32_bf16 v[68:71], v[146:149], v[186:189], v[68:71]
	v_mfma_f32_16x16x32_bf16 v[124:127], v[142:145], v[166:169], v[124:127]
	v_mfma_f32_16x16x32_bf16 v[116:119], v[150:153], v[166:169], v[116:119]
	v_mfma_f32_16x16x32_bf16 v[108:111], v[142:145], v[174:177], v[108:111]
	v_mfma_f32_16x16x32_bf16 v[100:103], v[150:153], v[174:177], v[100:103]
	v_mfma_f32_16x16x32_bf16 v[92:95], v[142:145], v[182:185], v[92:95]
	v_mfma_f32_16x16x32_bf16 v[84:87], v[150:153], v[182:185], v[84:87]
	v_mfma_f32_16x16x32_bf16 v[76:79], v[142:145], v[214:217], v[76:79]
	v_mfma_f32_16x16x32_bf16 v[68:71], v[150:153], v[214:217], v[68:71]
	s_barrier
	s_add_i32 s80, 0, 0x14000
	v_add_u32_e32 v154, s80, v139
	s_add_i32 s77, s77, s53
	ds_read_b128 v[218:221], v154
	ds_read_b128 v[222:225], v154 offset:1024
	ds_read_b128 v[226:229], v154 offset:2048
	ds_read_b128 v[230:233], v154 offset:3072
	v_lshl_add_u64 v[154:155], s[54:55], 0, v[156:157]
	s_mov_b32 m0, s77
	v_lshl_add_u64 v[206:207], s[54:55], 0, v[128:129]
	global_load_lds_dwordx4 v[154:155], off
	s_add_i32 m0, s77, 0x2000
	s_nop 0
	global_load_lds_dwordx4 v[206:207], off
	s_barrier
	s_waitcnt lgkmcnt(0)
	v_mfma_f32_16x16x32_bf16 v[120:123], v[218:221], v[162:165], v[120:123]
	v_mfma_f32_16x16x32_bf16 v[112:115], v[226:229], v[162:165], v[112:115]
	v_mfma_f32_16x16x32_bf16 v[104:107], v[218:221], v[170:173], v[104:107]
	v_mfma_f32_16x16x32_bf16 v[96:99], v[226:229], v[170:173], v[96:99]
	v_mfma_f32_16x16x32_bf16 v[88:91], v[218:221], v[178:181], v[88:91]
	v_mfma_f32_16x16x32_bf16 v[80:83], v[226:229], v[178:181], v[80:83]
	v_mfma_f32_16x16x32_bf16 v[72:75], v[218:221], v[186:189], v[72:75]
	v_mfma_f32_16x16x32_bf16 v[64:67], v[226:229], v[186:189], v[64:67]
	v_mfma_f32_16x16x32_bf16 v[120:123], v[222:225], v[166:169], v[120:123]
	v_mfma_f32_16x16x32_bf16 v[112:115], v[230:233], v[166:169], v[112:115]
	v_mfma_f32_16x16x32_bf16 v[104:107], v[222:225], v[174:177], v[104:107]
	v_mfma_f32_16x16x32_bf16 v[96:99], v[230:233], v[174:177], v[96:99]
	v_mfma_f32_16x16x32_bf16 v[88:91], v[222:225], v[182:185], v[88:91]
	v_mfma_f32_16x16x32_bf16 v[80:83], v[230:233], v[182:185], v[80:83]
	v_mfma_f32_16x16x32_bf16 v[72:75], v[222:225], v[214:217], v[72:75]
	v_mfma_f32_16x16x32_bf16 v[64:67], v[230:233], v[214:217], v[64:67]
	s_mov_b32 m0, s47
	v_lshl_add_u64 v[208:209], s[2:3], 0, v[156:157]
	s_barrier
	ds_read_b128 v[162:165], v141 offset:16384
	ds_read_b128 v[166:169], v141 offset:17408
	ds_read_b128 v[170:173], v141 offset:18432
	ds_read_b128 v[174:177], v141 offset:19456
	ds_read_b128 v[178:181], v141 offset:20480
	ds_read_b128 v[182:185], v141 offset:21504
	ds_read_b128 v[186:189], v141 offset:22528
	ds_read_b128 v[214:217], v141 offset:23552
	global_load_lds_dwordx4 v[208:209], off
	v_lshl_add_u64 v[234:235], s[2:3], 0, v[128:129]
	s_mov_b32 m0, s49
	s_nop 0
	global_load_lds_dwordx4 v[234:235], off
	s_barrier
	s_waitcnt lgkmcnt(0)
	v_mfma_f32_16x16x32_bf16 v[60:63], v[134:137], v[162:165], v[60:63]
	v_mfma_f32_16x16x32_bf16 v[52:55], v[146:149], v[162:165], v[52:55]
	v_mfma_f32_16x16x32_bf16 v[44:47], v[134:137], v[170:173], v[44:47]
	v_mfma_f32_16x16x32_bf16 v[36:39], v[146:149], v[170:173], v[36:39]
	v_mfma_f32_16x16x32_bf16 v[28:31], v[134:137], v[178:181], v[28:31]
	v_mfma_f32_16x16x32_bf16 v[20:23], v[146:149], v[178:181], v[20:23]
	v_mfma_f32_16x16x32_bf16 v[12:15], v[134:137], v[186:189], v[12:15]
	v_mfma_f32_16x16x32_bf16 v[4:7], v[146:149], v[186:189], v[4:7]
	v_mfma_f32_16x16x32_bf16 v[60:63], v[142:145], v[166:169], v[60:63]
	v_mfma_f32_16x16x32_bf16 v[52:55], v[150:153], v[166:169], v[52:55]
	v_mfma_f32_16x16x32_bf16 v[44:47], v[142:145], v[174:177], v[44:47]
	v_mfma_f32_16x16x32_bf16 v[36:39], v[150:153], v[174:177], v[36:39]
	v_mfma_f32_16x16x32_bf16 v[28:31], v[142:145], v[182:185], v[28:31]
	v_mfma_f32_16x16x32_bf16 v[20:23], v[150:153], v[182:185], v[20:23]
	v_mfma_f32_16x16x32_bf16 v[12:15], v[142:145], v[214:217], v[12:15]
	v_mfma_f32_16x16x32_bf16 v[4:7], v[150:153], v[214:217], v[4:7]
	s_barrier
	s_add_u32 s78, s54, 0x40000
	s_addc_u32 s79, s55, 0
	s_add_i32 s77, s80, s53
	v_lshl_add_u64 v[134:135], s[78:79], 0, v[156:157]
	s_mov_b32 m0, s77
	s_nop 0
	global_load_lds_dwordx4 v[134:135], off
	v_lshl_add_u64 v[134:135], s[78:79], 0, v[128:129]
	s_add_i32 m0, s77, 0x2000
	s_nop 0
	global_load_lds_dwordx4 v[134:135], off
	s_waitcnt vmcnt(6)
	s_barrier
	v_mfma_f32_16x16x32_bf16 v[56:59], v[218:221], v[162:165], v[56:59]
	v_mfma_f32_16x16x32_bf16 v[48:51], v[226:229], v[162:165], v[48:51]
	v_mfma_f32_16x16x32_bf16 v[40:43], v[218:221], v[170:173], v[40:43]
	v_mfma_f32_16x16x32_bf16 v[32:35], v[226:229], v[170:173], v[32:35]
	v_mfma_f32_16x16x32_bf16 v[24:27], v[218:221], v[178:181], v[24:27]
	v_mfma_f32_16x16x32_bf16 v[16:19], v[226:229], v[178:181], v[16:19]
	v_mfma_f32_16x16x32_bf16 v[8:11], v[218:221], v[186:189], v[8:11]
	v_mfma_f32_16x16x32_bf16 v[0:3], v[226:229], v[186:189], v[0:3]
	v_mfma_f32_16x16x32_bf16 v[56:59], v[222:225], v[166:169], v[56:59]
	v_mfma_f32_16x16x32_bf16 v[48:51], v[230:233], v[166:169], v[48:51]
	v_mfma_f32_16x16x32_bf16 v[40:43], v[222:225], v[174:177], v[40:43]
	v_mfma_f32_16x16x32_bf16 v[32:35], v[230:233], v[174:177], v[32:35]
	v_mfma_f32_16x16x32_bf16 v[24:27], v[222:225], v[182:185], v[24:27]
	v_mfma_f32_16x16x32_bf16 v[16:19], v[230:233], v[182:185], v[16:19]
	v_mfma_f32_16x16x32_bf16 v[8:11], v[222:225], v[214:217], v[8:11]
	v_mfma_f32_16x16x32_bf16 v[0:3], v[230:233], v[214:217], v[0:3]
	s_add_i32 s77, 0, 0x18000
	v_add_u32_e32 v150, s77, v139
	s_barrier
	ds_read_b128 v[134:137], v150
	ds_read_b128 v[142:145], v150 offset:1024
	ds_read_b128 v[146:149], v150 offset:2048
	ds_read_b128 v[150:153], v150 offset:3072
	s_add_u32 s2, s2, 0x40000
	s_addc_u32 s3, s3, 0
	s_mov_b32 m0, s62
	v_lshl_add_u64 v[218:219], s[2:3], 0, v[156:157]
	ds_read_b128 v[162:165], v141 offset:32768
	ds_read_b128 v[166:169], v141 offset:33792
	ds_read_b128 v[170:173], v141 offset:34816
	ds_read_b128 v[174:177], v141 offset:35840
	ds_read_b128 v[178:181], v141 offset:36864
	ds_read_b128 v[182:185], v141 offset:37888
	ds_read_b128 v[186:189], v141 offset:38912
	ds_read_b128 v[214:217], v141 offset:39936
	global_load_lds_dwordx4 v[218:219], off
	v_lshl_add_u64 v[218:219], s[2:3], 0, v[128:129]
	s_mov_b32 m0, s63
	s_nop 0
	global_load_lds_dwordx4 v[218:219], off
	s_waitcnt lgkmcnt(8)
	s_barrier
	s_waitcnt lgkmcnt(0)
	v_mfma_f32_16x16x32_bf16 v[124:127], v[134:137], v[162:165], v[124:127]
	v_mfma_f32_16x16x32_bf16 v[116:119], v[146:149], v[162:165], v[116:119]
	v_mfma_f32_16x16x32_bf16 v[108:111], v[134:137], v[170:173], v[108:111]
	v_mfma_f32_16x16x32_bf16 v[100:103], v[146:149], v[170:173], v[100:103]
	v_mfma_f32_16x16x32_bf16 v[92:95], v[134:137], v[178:181], v[92:95]
	v_mfma_f32_16x16x32_bf16 v[84:87], v[146:149], v[178:181], v[84:87]
	v_mfma_f32_16x16x32_bf16 v[76:79], v[134:137], v[186:189], v[76:79]
	v_mfma_f32_16x16x32_bf16 v[68:71], v[146:149], v[186:189], v[68:71]
	v_mfma_f32_16x16x32_bf16 v[124:127], v[142:145], v[166:169], v[124:127]
	v_mfma_f32_16x16x32_bf16 v[116:119], v[150:153], v[166:169], v[116:119]
	v_mfma_f32_16x16x32_bf16 v[108:111], v[142:145], v[174:177], v[108:111]
	v_mfma_f32_16x16x32_bf16 v[100:103], v[150:153], v[174:177], v[100:103]
	v_mfma_f32_16x16x32_bf16 v[92:95], v[142:145], v[182:185], v[92:95]
	v_mfma_f32_16x16x32_bf16 v[84:87], v[150:153], v[182:185], v[84:87]
	v_mfma_f32_16x16x32_bf16 v[76:79], v[142:145], v[214:217], v[76:79]
	v_mfma_f32_16x16x32_bf16 v[68:71], v[150:153], v[214:217], v[68:71]
	s_barrier
	s_add_i32 s78, 0, 0x1c000
	s_add_i32 s2, s77, s53
	v_add_u32_e32 v161, s78, v139
	v_lshl_add_u64 v[154:155], v[154:155], 0, s[50:51]
	s_mov_b32 m0, s2
	ds_read_b128 v[218:221], v161
	ds_read_b128 v[222:225], v161 offset:1024
	ds_read_b128 v[226:229], v161 offset:2048
	ds_read_b128 v[230:233], v161 offset:3072
	global_load_lds_dwordx4 v[154:155], off
	v_lshl_add_u64 v[154:155], v[206:207], 0, s[50:51]
	s_add_i32 m0, s2, 0x2000
	s_nop 0
	global_load_lds_dwordx4 v[154:155], off
	s_barrier
	s_waitcnt lgkmcnt(0)
	v_mfma_f32_16x16x32_bf16 v[120:123], v[218:221], v[162:165], v[120:123]
	v_mfma_f32_16x16x32_bf16 v[112:115], v[226:229], v[162:165], v[112:115]
	v_mfma_f32_16x16x32_bf16 v[104:107], v[218:221], v[170:173], v[104:107]
	v_mfma_f32_16x16x32_bf16 v[96:99], v[226:229], v[170:173], v[96:99]
	v_mfma_f32_16x16x32_bf16 v[88:91], v[218:221], v[178:181], v[88:91]
	v_mfma_f32_16x16x32_bf16 v[80:83], v[226:229], v[178:181], v[80:83]
	v_mfma_f32_16x16x32_bf16 v[72:75], v[218:221], v[186:189], v[72:75]
	v_mfma_f32_16x16x32_bf16 v[64:67], v[226:229], v[186:189], v[64:67]
	v_mfma_f32_16x16x32_bf16 v[120:123], v[222:225], v[166:169], v[120:123]
	v_mfma_f32_16x16x32_bf16 v[112:115], v[230:233], v[166:169], v[112:115]
	v_mfma_f32_16x16x32_bf16 v[104:107], v[222:225], v[174:177], v[104:107]
	v_mfma_f32_16x16x32_bf16 v[96:99], v[230:233], v[174:177], v[96:99]
	v_mfma_f32_16x16x32_bf16 v[88:91], v[222:225], v[182:185], v[88:91]
	v_mfma_f32_16x16x32_bf16 v[80:83], v[230:233], v[182:185], v[80:83]
	v_mfma_f32_16x16x32_bf16 v[72:75], v[222:225], v[214:217], v[72:75]
	v_mfma_f32_16x16x32_bf16 v[64:67], v[230:233], v[214:217], v[64:67]
	s_mov_b32 m0, s66
	v_lshl_add_u64 v[154:155], v[208:209], 0, s[50:51]
	s_barrier
	ds_read_b128 v[162:165], v141 offset:49152
	ds_read_b128 v[166:169], v141 offset:50176
	ds_read_b128 v[170:173], v141 offset:51200
	ds_read_b128 v[174:177], v141 offset:52224
	ds_read_b128 v[178:181], v141 offset:53248
	ds_read_b128 v[182:185], v141 offset:54272
	ds_read_b128 v[186:189], v141 offset:55296
	ds_read_b128 v[214:217], v141 offset:56320
	global_load_lds_dwordx4 v[154:155], off
	v_lshl_add_u64 v[154:155], v[234:235], 0, s[50:51]
	s_mov_b32 m0, s67
	s_nop 0
	global_load_lds_dwordx4 v[154:155], off
	s_barrier
	s_waitcnt lgkmcnt(0)
	v_mfma_f32_16x16x32_bf16 v[60:63], v[134:137], v[162:165], v[60:63]
	v_mfma_f32_16x16x32_bf16 v[52:55], v[146:149], v[162:165], v[52:55]
	v_mfma_f32_16x16x32_bf16 v[44:47], v[134:137], v[170:173], v[44:47]
	v_mfma_f32_16x16x32_bf16 v[36:39], v[146:149], v[170:173], v[36:39]
	v_mfma_f32_16x16x32_bf16 v[28:31], v[134:137], v[178:181], v[28:31]
	v_mfma_f32_16x16x32_bf16 v[20:23], v[146:149], v[178:181], v[20:23]
	v_mfma_f32_16x16x32_bf16 v[12:15], v[134:137], v[186:189], v[12:15]
	v_mfma_f32_16x16x32_bf16 v[4:7], v[146:149], v[186:189], v[4:7]
	v_mfma_f32_16x16x32_bf16 v[60:63], v[142:145], v[166:169], v[60:63]
	v_mfma_f32_16x16x32_bf16 v[52:55], v[150:153], v[166:169], v[52:55]
	v_mfma_f32_16x16x32_bf16 v[44:47], v[142:145], v[174:177], v[44:47]
	v_mfma_f32_16x16x32_bf16 v[36:39], v[150:153], v[174:177], v[36:39]
	v_mfma_f32_16x16x32_bf16 v[28:31], v[142:145], v[182:185], v[28:31]
	v_mfma_f32_16x16x32_bf16 v[20:23], v[150:153], v[182:185], v[20:23]
	v_mfma_f32_16x16x32_bf16 v[12:15], v[142:145], v[214:217], v[12:15]
	v_mfma_f32_16x16x32_bf16 v[4:7], v[150:153], v[214:217], v[4:7]
	s_barrier
	s_add_u32 s2, s54, 0x40080
	s_addc_u32 s3, s55, 0
	s_add_i32 s54, s78, s53
	v_lshl_add_u64 v[134:135], s[2:3], 0, v[156:157]
	s_mov_b32 m0, s54
	s_nop 0
	global_load_lds_dwordx4 v[134:135], off
	v_lshl_add_u64 v[134:135], s[2:3], 0, v[128:129]
	s_add_i32 m0, s54, 0x2000
	s_nop 0
	global_load_lds_dwordx4 v[134:135], off
	s_waitcnt vmcnt(6)
	s_barrier
	v_mfma_f32_16x16x32_bf16 v[56:59], v[218:221], v[162:165], v[56:59]
	v_mfma_f32_16x16x32_bf16 v[48:51], v[226:229], v[162:165], v[48:51]
	v_mfma_f32_16x16x32_bf16 v[40:43], v[218:221], v[170:173], v[40:43]
	v_mfma_f32_16x16x32_bf16 v[32:35], v[226:229], v[170:173], v[32:35]
	v_mfma_f32_16x16x32_bf16 v[24:27], v[218:221], v[178:181], v[24:27]
	v_mfma_f32_16x16x32_bf16 v[16:19], v[226:229], v[178:181], v[16:19]
	v_mfma_f32_16x16x32_bf16 v[8:11], v[218:221], v[186:189], v[8:11]
	v_mfma_f32_16x16x32_bf16 v[0:3], v[226:229], v[186:189], v[0:3]
	v_mfma_f32_16x16x32_bf16 v[56:59], v[222:225], v[166:169], v[56:59]
	v_mfma_f32_16x16x32_bf16 v[48:51], v[230:233], v[166:169], v[48:51]
	v_mfma_f32_16x16x32_bf16 v[40:43], v[222:225], v[174:177], v[40:43]
	v_mfma_f32_16x16x32_bf16 v[32:35], v[230:233], v[174:177], v[32:35]
	v_mfma_f32_16x16x32_bf16 v[24:27], v[222:225], v[182:185], v[24:27]
	v_mfma_f32_16x16x32_bf16 v[16:19], v[230:233], v[182:185], v[16:19]
	v_mfma_f32_16x16x32_bf16 v[8:11], v[222:225], v[214:217], v[8:11]
	v_mfma_f32_16x16x32_bf16 v[0:3], v[230:233], v[214:217], v[0:3]
	s_add_i32 s73, s73, 2
	s_add_u32 s43, s43, 0x100
	s_addc_u32 s69, s69, 0
	s_add_u32 s6, s6, 0x100
	s_addc_u32 s7, s7, 0
	s_cmp_gt_u32 s73, 13
	s_barrier
	s_cbranch_scc0 .LBB0_555
